# speedup vs baseline: 1.0068x; 1.0068x over previous
; #define WAIT_V0() asm volatile("s_waitcnt vmcnt(0)" ::: "memory")
; #define SBAR() __builtin_amdgcn_sched_barrier(0)
; template <int EPI>
; DEVI void gemm_tile(const u16* __restrict__ Ab, long lda, const u16* __restrict__ Bb, long ldb, int K, const EpiArgs& e,
;                     bool have0 = false, const u16* __restrict__ nA = nullptr, const u16* __restrict__ nB = nullptr) {
;     ...
;   f32x4 acc[8][4];
; #pragma unroll
;   for (int m = 0; m < 8; ++m)
; #pragma unroll
;     for (int n = 0; n < 4; ++n) acc[m][n] = f32x4{0.f, 0.f, 0.f, 0.f};
;   const int nt = K / BK;
;   if (!have0) GLDS_STAGE(0, 0);
;   WAIT_V0(); __syncthreads();
;   for (int t = 0; t < nt; ++t) {
;     const int cur = t & 1;
;     if (t + 1 < nt) GLDS_STAGE(cur ^ 1, t + 1);
;     else if (nA) {
; #pragma unroll
;       for (int i = 0; i < GL; ++i) {
;         __builtin_amdgcn_global_load_lds((const unsigned*)(nA + (long)i * 64 * lda + toffA), (unsigned*)(g_shm + wid * 1024 + i * 8192), 16, 0, 0);
;         __builtin_amdgcn_global_load_lds((const unsigned*)(nB + (long)i * 64 * ldb + toffB), (unsigned*)(g_shm + TILE_B + wid * 1024 + i * 8192), 16, 0, 0);
;       }
;     }
;     const char* sb = g_shm + cur * STAGE_B;
; #pragma unroll
;     for (int ks = 0; ks < 2; ++ks) {
;       bf16x8 Bf[4];
; #pragma unroll
;       for (int n = 0; n < 4; ++n) Bf[n] = *(const bf16x8*)(sb + b_base + n * 2048 + ks * 1024);
; #pragma unroll
;       for (int mh = 0; mh < 2; ++mh) {
;         bf16x8 At[4];
; #pragma unroll
;         for (int m = 0; m < 4; ++m) At[m] = *(const bf16x8*)(sb + a_base + (mh * 4 + m) * 2048 + ks * 1024);
;         __builtin_amdgcn_s_setprio(1);
; #pragma unroll
;         for (int m = 0; m < 4; ++m)
; #pragma unroll
;           for (int n = 0; n < 4; ++n) acc[mh * 4 + m][n] = __builtin_amdgcn_mfma_f32_16x16x32_bf16(Bf[n], At[m], acc[mh * 4 + m][n], 0, 0, 0);
;         __builtin_amdgcn_s_setprio(0);
;       }
;       SBAR();
;     }
;     if (t + 1 < nt) { WAIT_V0(); __syncthreads(); }
;   }
.Lkl_150_s3:
	s_cmp_eq_u32 s101, 1
	s_cbranch_scc1 .Lkl_150_y
.Lkl_150:
	s_waitcnt lgkmcnt(3)
	v_mfma_f32_16x16x32_bf16 v[126:129], v[150:153], v[170:173], v[126:129]
	v_mfma_f32_16x16x32_bf16 v[122:125], v[154:157], v[170:173], v[122:125]
	v_mfma_f32_16x16x32_bf16 v[118:121], v[158:161], v[170:173], v[118:121]
	v_mfma_f32_16x16x32_bf16 v[114:117], v[162:165], v[170:173], v[114:117]
	ds_read_b128 v[170:173], v149 offset:8192
	ds_read_b128 v[222:225], v169 offset:33792
	s_add_u32 s8, s4, 0x17800
	s_addc_u32 s9, s5, 0x0
	global_load_lds_dwordx4 v238, s[8:9] offset:2048
	s_add_u32 s8, s4, 0x17440
	s_addc_u32 s9, s5, 0x0
	global_load_lds_dwordx4 v238, s[8:9] offset:3072
.Lkl_150_s4:
	s_waitcnt lgkmcnt(4)
	v_mfma_f32_16x16x32_bf16 v[110:113], v[150:153], v[174:177], v[110:113]
	v_mfma_f32_16x16x32_bf16 v[106:109], v[154:157], v[174:177], v[106:109]
	v_mfma_f32_16x16x32_bf16 v[102:105], v[158:161], v[174:177], v[102:105]
	v_mfma_f32_16x16x32_bf16 v[98:101], v[162:165], v[174:177], v[98:101]
	ds_read_b128 v[174:177], v149 offset:10240
	ds_read_b128 v[226:229], v169 offset:35840
	s_add_i32 m0, s10, 0x9000
	s_add_u32 s8, s6, 0x1000
	s_addc_u32 s9, s7, 0x0
	global_load_lds_dwordx4 v239, s[8:9] offset:-4096
	s_add_u32 s8, s6, 0xc40
	s_addc_u32 s9, s7, 0x0
	global_load_lds_dwordx4 v239, s[8:9] offset:-3072
.Lkl_150_s5:
	s_waitcnt lgkmcnt(5)
	v_mfma_f32_16x16x32_bf16 v[94:97], v[150:153], v[214:217], v[94:97]
	v_mfma_f32_16x16x32_bf16 v[90:93], v[154:157], v[214:217], v[90:93]
	v_mfma_f32_16x16x32_bf16 v[86:89], v[158:161], v[214:217], v[86:89]
	v_mfma_f32_16x16x32_bf16 v[82:85], v[162:165], v[214:217], v[82:85]
	ds_read_b128 v[214:217], v149 offset:12288
	ds_read_b128 v[230:233], v169 offset:37888
	s_add_u32 s8, s6, 0x8800
	s_addc_u32 s9, s7, 0x0
	global_load_lds_dwordx4 v239, s[8:9] offset:-2048
	s_add_u32 s8, s6, 0x8440
	s_addc_u32 s9, s7, 0x0
	global_load_lds_dwordx4 v239, s[8:9] offset:-1024
.Lkl_150_s6:
	s_waitcnt lgkmcnt(6)
	v_mfma_f32_16x16x32_bf16 v[78:81], v[150:153], v[218:221], v[78:81]
	v_mfma_f32_16x16x32_bf16 v[74:77], v[154:157], v[218:221], v[74:77]
	v_mfma_f32_16x16x32_bf16 v[70:73], v[158:161], v[218:221], v[70:73]
	v_mfma_f32_16x16x32_bf16 v[66:69], v[162:165], v[218:221], v[66:69]
	ds_read_b128 v[218:221], v149 offset:14336
	ds_read_b128 v[234:237], v169 offset:39936
	s_add_u32 s8, s6, 0x10000
	s_addc_u32 s9, s7, 0x0
	global_load_lds_dwordx4 v239, s[8:9] offset:0
	s_add_u32 s8, s6, 0xfc40
	s_addc_u32 s9, s7, 0x0
	global_load_lds_dwordx4 v239, s[8:9] offset:1024
.Lkl_150_s7:
	s_waitcnt lgkmcnt(7)
	v_mfma_f32_16x16x32_bf16 v[62:65], v[150:153], v[170:173], v[62:65]
	v_mfma_f32_16x16x32_bf16 v[58:61], v[154:157], v[170:173], v[58:61]
	v_mfma_f32_16x16x32_bf16 v[54:57], v[158:161], v[170:173], v[54:57]
	v_mfma_f32_16x16x32_bf16 v[50:53], v[162:165], v[170:173], v[50:53]
	ds_read_b128 v[170:173], v149 offset:1024
	s_add_u32 s8, s6, 0x17800
	s_addc_u32 s9, s7, 0x0
	global_load_lds_dwordx4 v239, s[8:9] offset:2048
	s_add_u32 s8, s6, 0x17440
	s_addc_u32 s9, s7, 0x0
	global_load_lds_dwordx4 v239, s[8:9] offset:3072
.Lkl_150_s8:
	s_waitcnt lgkmcnt(6)
	v_mfma_f32_16x16x32_bf16 v[46:49], v[150:153], v[174:177], v[46:49]
	v_mfma_f32_16x16x32_bf16 v[42:45], v[154:157], v[174:177], v[42:45]
	v_mfma_f32_16x16x32_bf16 v[38:41], v[158:161], v[174:177], v[38:41]
	v_mfma_f32_16x16x32_bf16 v[34:37], v[162:165], v[174:177], v[34:37]
	ds_read_b128 v[174:177], v149 offset:3072
	s_waitcnt lgkmcnt(5)
	v_mfma_f32_16x16x32_bf16 v[30:33], v[150:153], v[214:217], v[30:33]
	v_mfma_f32_16x16x32_bf16 v[26:29], v[154:157], v[214:217], v[26:29]
	v_mfma_f32_16x16x32_bf16 v[22:25], v[158:161], v[214:217], v[22:25]
	v_mfma_f32_16x16x32_bf16 v[18:21], v[162:165], v[214:217], v[18:21]
	ds_read_b128 v[214:217], v149 offset:5120
	s_waitcnt lgkmcnt(4)
	v_mfma_f32_16x16x32_bf16 v[14:17], v[150:153], v[218:221], v[14:17]
	v_mfma_f32_16x16x32_bf16 v[10:13], v[154:157], v[218:221], v[10:13]
	v_mfma_f32_16x16x32_bf16 v[6:9], v[158:161], v[218:221], v[6:9]
	v_mfma_f32_16x16x32_bf16 v[2:5], v[162:165], v[218:221], v[2:5]
	ds_read_b128 v[218:221], v149 offset:7168
	s_waitcnt lgkmcnt(3)
	v_mfma_f32_16x16x32_bf16 v[126:129], v[222:225], v[170:173], v[126:129]
	v_mfma_f32_16x16x32_bf16 v[122:125], v[226:229], v[170:173], v[122:125]
	v_mfma_f32_16x16x32_bf16 v[118:121], v[230:233], v[170:173], v[118:121]
	v_mfma_f32_16x16x32_bf16 v[114:117], v[234:237], v[170:173], v[114:117]
	ds_read_b128 v[170:173], v149 offset:9216
	s_waitcnt lgkmcnt(3)
	v_mfma_f32_16x16x32_bf16 v[110:113], v[222:225], v[174:177], v[110:113]
	v_mfma_f32_16x16x32_bf16 v[106:109], v[226:229], v[174:177], v[106:109]
	v_mfma_f32_16x16x32_bf16 v[102:105], v[230:233], v[174:177], v[102:105]
	v_mfma_f32_16x16x32_bf16 v[98:101], v[234:237], v[174:177], v[98:101]
	ds_read_b128 v[174:177], v149 offset:11264
	s_waitcnt lgkmcnt(3)
	v_mfma_f32_16x16x32_bf16 v[94:97], v[222:225], v[214:217], v[94:97]
	v_mfma_f32_16x16x32_bf16 v[90:93], v[226:229], v[214:217], v[90:93]
	v_mfma_f32_16x16x32_bf16 v[86:89], v[230:233], v[214:217], v[86:89]
	v_mfma_f32_16x16x32_bf16 v[82:85], v[234:237], v[214:217], v[82:85]
	ds_read_b128 v[214:217], v149 offset:13312
	s_waitcnt lgkmcnt(3)
	v_mfma_f32_16x16x32_bf16 v[78:81], v[222:225], v[218:221], v[78:81]
	v_mfma_f32_16x16x32_bf16 v[74:77], v[226:229], v[218:221], v[74:77]
	v_mfma_f32_16x16x32_bf16 v[70:73], v[230:233], v[218:221], v[70:73]
	v_mfma_f32_16x16x32_bf16 v[66:69], v[234:237], v[218:221], v[66:69]
	ds_read_b128 v[218:221], v149 offset:15360
	s_waitcnt lgkmcnt(3)
	v_mfma_f32_16x16x32_bf16 v[62:65], v[222:225], v[170:173], v[62:65]
	v_mfma_f32_16x16x32_bf16 v[58:61], v[226:229], v[170:173], v[58:61]
	v_mfma_f32_16x16x32_bf16 v[54:57], v[230:233], v[170:173], v[54:57]
	v_mfma_f32_16x16x32_bf16 v[50:53], v[234:237], v[170:173], v[50:53]
	s_waitcnt lgkmcnt(2)
	v_mfma_f32_16x16x32_bf16 v[46:49], v[222:225], v[174:177], v[46:49]
	v_mfma_f32_16x16x32_bf16 v[42:45], v[226:229], v[174:177], v[42:45]
	v_mfma_f32_16x16x32_bf16 v[38:41], v[230:233], v[174:177], v[38:41]
	v_mfma_f32_16x16x32_bf16 v[34:37], v[234:237], v[174:177], v[34:37]
	s_waitcnt lgkmcnt(0)
	s_add_i32 s2, s2, 0x10000
	s_waitcnt vmcnt(0)
	s_add_u32 s14, s14, 0x80
	s_addc_u32 s15, s15, 0
	s_cmpk_eq_i32 s14, 0x780
	s_waitcnt vmcnt(0)
	s_barrier
; #define WAIT_V0() asm volatile("s_waitcnt vmcnt(0)" ::: "memory")
; #define SBAR() __builtin_amdgcn_sched_barrier(0)
; template <int EPI>
; DEVI void gemm_tile(const u16* __restrict__ Ab, long lda, const u16* __restrict__ Bb, long ldb, int K, const EpiArgs& e,
;                     bool have0 = false, const u16* __restrict__ nA = nullptr, const u16* __restrict__ nB = nullptr) {
;     ...
;   f32x4 acc[8][4];
; #pragma unroll
;   for (int m = 0; m < 8; ++m)
; #pragma unroll
;     for (int n = 0; n < 4; ++n) acc[m][n] = f32x4{0.f, 0.f, 0.f, 0.f};
;   const int nt = K / BK;
;   if (!have0) GLDS_STAGE(0, 0);
;   WAIT_V0(); __syncthreads();
;   for (int t = 0; t < nt; ++t) {
;     const int cur = t & 1;
;     if (t + 1 < nt) GLDS_STAGE(cur ^ 1, t + 1);
;     else if (nA) {
; #pragma unroll
;       for (int i = 0; i < GL; ++i) {
;         __builtin_amdgcn_global_load_lds((const unsigned*)(nA + (long)i * 64 * lda + toffA), (unsigned*)(g_shm + wid * 1024 + i * 8192), 16, 0, 0);
;         __builtin_amdgcn_global_load_lds((const unsigned*)(nB + (long)i * 64 * ldb + toffB), (unsigned*)(g_shm + TILE_B + wid * 1024 + i * 8192), 16, 0, 0);
;       }
;     }
;     const char* sb = g_shm + cur * STAGE_B;
; #pragma unroll
;     for (int ks = 0; ks < 2; ++ks) {
;       bf16x8 Bf[4];
; #pragma unroll
;       for (int n = 0; n < 4; ++n) Bf[n] = *(const bf16x8*)(sb + b_base + n * 2048 + ks * 1024);
; #pragma unroll
;       for (int mh = 0; mh < 2; ++mh) {
;         bf16x8 At[4];
; #pragma unroll
;         for (int m = 0; m < 4; ++m) At[m] = *(const bf16x8*)(sb + a_base + (mh * 4 + m) * 2048 + ks * 1024);
;         __builtin_amdgcn_s_setprio(1);
; #pragma unroll
;         for (int m = 0; m < 4; ++m)
; #pragma unroll
;           for (int n = 0; n < 4; ++n) acc[mh * 4 + m][n] = __builtin_amdgcn_mfma_f32_16x16x32_bf16(Bf[n], At[m], acc[mh * 4 + m][n], 0, 0, 0);
;         __builtin_amdgcn_s_setprio(0);
;       }
;       SBAR();
;     }
;     if (t + 1 < nt) { WAIT_V0(); __syncthreads(); }
;   }
	s_cselect_b32 s100, 1, 0
	s_and_b32 s3, s2, 0x10000
	v_or_b32_e32 v149, s3, v147
	v_add_u32_e32 v169, v149, v148
	v_add_u32_e32 v149, v149, v146
	ds_read_b128 v[150:153], v169 offset:32768
	ds_read_b128 v[154:157], v169 offset:34816
	ds_read_b128 v[158:161], v169 offset:36864
	ds_read_b128 v[162:165], v169 offset:38912
	ds_read_b128 v[170:173], v149
	ds_read_b128 v[174:177], v149 offset:2048
	s_add_u32 s4, s4, 0x80
	s_addc_u32 s5, s5, 0
	s_add_u32 s6, s6, 0x80
	s_addc_u32 s7, s7, 0
	s_cmp_eq_u32 s100, 1
	s_cbranch_scc1 .Lkl_150_s9
	v_readfirstlane_b32 s10, v140
	s_nop 3
	s_mul_i32 s8, s10, 8
	s_mul_i32 s9, s10, 0
	s_add_i32 s9, s9, 0x8000
	s_cmp_ge_u32 s10, 0x1000
	s_cselect_b32 s10, s9, s8
	s_xor_b32 s8, s3, 0x10000
	s_add_i32 s10, s10, s8
	s_add_i32 m0, s10, 0x1000
	s_add_u32 s8, s4, 0x1000
	s_addc_u32 s9, s5, 0x0
	global_load_lds_dwordx4 v238, s[8:9] offset:-4096
	s_add_u32 s8, s4, 0xc40
	s_addc_u32 s9, s5, 0x0
	global_load_lds_dwordx4 v238, s[8:9] offset:-3072
.Lkl_150_s9:
	v_mfma_f32_16x16x32_bf16 v[30:33], v[222:225], v[214:217], v[30:33]
	v_mfma_f32_16x16x32_bf16 v[26:29], v[226:229], v[214:217], v[26:29]
	v_mfma_f32_16x16x32_bf16 v[22:25], v[230:233], v[214:217], v[22:25]
	v_mfma_f32_16x16x32_bf16 v[18:21], v[234:237], v[214:217], v[18:21]
	ds_read_b128 v[214:217], v149 offset:4096
	s_cmp_eq_u32 s100, 1
	s_cbranch_scc1 .Lkl_150_s10
	s_add_u32 s8, s4, 0x8800
	s_addc_u32 s9, s5, 0x0
	global_load_lds_dwordx4 v238, s[8:9] offset:-2048
	s_add_u32 s8, s4, 0x8440
	s_addc_u32 s9, s5, 0x0
	global_load_lds_dwordx4 v238, s[8:9] offset:-1024
.Lkl_150_s10:
	v_mfma_f32_16x16x32_bf16 v[14:17], v[222:225], v[218:221], v[14:17]
	v_mfma_f32_16x16x32_bf16 v[10:13], v[226:229], v[218:221], v[10:13]
	v_mfma_f32_16x16x32_bf16 v[6:9], v[230:233], v[218:221], v[6:9]
	v_mfma_f32_16x16x32_bf16 v[2:5], v[234:237], v[218:221], v[2:5]
	ds_read_b128 v[218:221], v149 offset:6144
	s_cmp_eq_u32 s100, 1
	s_cbranch_scc1 .Lkl_150_s11
	s_add_u32 s8, s4, 0x10000
	s_addc_u32 s9, s5, 0x0
	global_load_lds_dwordx4 v238, s[8:9] offset:0
	s_add_u32 s8, s4, 0xfc40
	s_addc_u32 s9, s5, 0x0
	global_load_lds_dwordx4 v238, s[8:9] offset:1024
.Lkl_150_s11:
	s_cmp_eq_u32 s100, 1
	s_cbranch_scc0 .Lkl_150
	s_branch .Lkl_150_x
.Lkl_150_y:
	s_waitcnt lgkmcnt(3)
	v_mfma_f32_16x16x32_bf16 v[126:129], v[150:153], v[170:173], v[126:129]
	v_mfma_f32_16x16x32_bf16 v[122:125], v[154:157], v[170:173], v[122:125]
	v_mfma_f32_16x16x32_bf16 v[118:121], v[158:161], v[170:173], v[118:121]
	v_mfma_f32_16x16x32_bf16 v[114:117], v[162:165], v[170:173], v[114:117]
	ds_read_b128 v[170:173], v149 offset:8192
	ds_read_b128 v[222:225], v169 offset:33792
	s_waitcnt lgkmcnt(4)
	v_mfma_f32_16x16x32_bf16 v[110:113], v[150:153], v[174:177], v[110:113]
	v_mfma_f32_16x16x32_bf16 v[106:109], v[154:157], v[174:177], v[106:109]
	v_mfma_f32_16x16x32_bf16 v[102:105], v[158:161], v[174:177], v[102:105]
	v_mfma_f32_16x16x32_bf16 v[98:101], v[162:165], v[174:177], v[98:101]
	ds_read_b128 v[174:177], v149 offset:10240
	ds_read_b128 v[226:229], v169 offset:35840
	s_waitcnt lgkmcnt(5)
	v_mfma_f32_16x16x32_bf16 v[94:97], v[150:153], v[214:217], v[94:97]
	v_mfma_f32_16x16x32_bf16 v[90:93], v[154:157], v[214:217], v[90:93]
	v_mfma_f32_16x16x32_bf16 v[86:89], v[158:161], v[214:217], v[86:89]
	v_mfma_f32_16x16x32_bf16 v[82:85], v[162:165], v[214:217], v[82:85]
	ds_read_b128 v[214:217], v149 offset:12288
	ds_read_b128 v[230:233], v169 offset:37888
	s_waitcnt lgkmcnt(6)
	v_mfma_f32_16x16x32_bf16 v[78:81], v[150:153], v[218:221], v[78:81]
	v_mfma_f32_16x16x32_bf16 v[74:77], v[154:157], v[218:221], v[74:77]
	v_mfma_f32_16x16x32_bf16 v[70:73], v[158:161], v[218:221], v[70:73]
	v_mfma_f32_16x16x32_bf16 v[66:69], v[162:165], v[218:221], v[66:69]
	ds_read_b128 v[218:221], v149 offset:14336
	ds_read_b128 v[234:237], v169 offset:39936
	s_waitcnt lgkmcnt(7)
	v_mfma_f32_16x16x32_bf16 v[62:65], v[150:153], v[170:173], v[62:65]
	v_mfma_f32_16x16x32_bf16 v[58:61], v[154:157], v[170:173], v[58:61]
	v_mfma_f32_16x16x32_bf16 v[54:57], v[158:161], v[170:173], v[54:57]
	v_mfma_f32_16x16x32_bf16 v[50:53], v[162:165], v[170:173], v[50:53]
	ds_read_b128 v[170:173], v149 offset:1024
	s_waitcnt lgkmcnt(6)
	v_mfma_f32_16x16x32_bf16 v[46:49], v[150:153], v[174:177], v[46:49]
	v_mfma_f32_16x16x32_bf16 v[42:45], v[154:157], v[174:177], v[42:45]
	v_mfma_f32_16x16x32_bf16 v[38:41], v[158:161], v[174:177], v[38:41]
	v_mfma_f32_16x16x32_bf16 v[34:37], v[162:165], v[174:177], v[34:37]
	ds_read_b128 v[174:177], v149 offset:3072
	s_waitcnt lgkmcnt(5)
	v_mfma_f32_16x16x32_bf16 v[30:33], v[150:153], v[214:217], v[30:33]
	v_mfma_f32_16x16x32_bf16 v[26:29], v[154:157], v[214:217], v[26:29]
	v_mfma_f32_16x16x32_bf16 v[22:25], v[158:161], v[214:217], v[22:25]
	v_mfma_f32_16x16x32_bf16 v[18:21], v[162:165], v[214:217], v[18:21]
	ds_read_b128 v[214:217], v149 offset:5120
	s_waitcnt lgkmcnt(4)
	v_mfma_f32_16x16x32_bf16 v[14:17], v[150:153], v[218:221], v[14:17]
	v_mfma_f32_16x16x32_bf16 v[10:13], v[154:157], v[218:221], v[10:13]
	v_mfma_f32_16x16x32_bf16 v[6:9], v[158:161], v[218:221], v[6:9]
	v_mfma_f32_16x16x32_bf16 v[2:5], v[162:165], v[218:221], v[2:5]
	ds_read_b128 v[218:221], v149 offset:7168
	s_waitcnt lgkmcnt(3)
; #define WAIT_V0() asm volatile("s_waitcnt vmcnt(0)" ::: "memory")
; #define SBAR() __builtin_amdgcn_sched_barrier(0)
; template <int EPI>
; DEVI void gemm_tile(const u16* __restrict__ Ab, long lda, const u16* __restrict__ Bb, long ldb, int K, const EpiArgs& e,
;                     bool have0 = false, const u16* __restrict__ nA = nullptr, const u16* __restrict__ nB = nullptr) {
;     ...
;   for (int t = 0; t < nt; ++t) {
;     const int cur = t & 1;
;     if (t + 1 < nt) GLDS_STAGE(cur ^ 1, t + 1);
;     else if (nA) {
; #pragma unroll
;       for (int i = 0; i < GL; ++i) {
;         __builtin_amdgcn_global_load_lds((const unsigned*)(nA + (long)i * 64 * lda + toffA), (unsigned*)(g_shm + wid * 1024 + i * 8192), 16, 0, 0);
;         __builtin_amdgcn_global_load_lds((const unsigned*)(nB + (long)i * 64 * ldb + toffB), (unsigned*)(g_shm + TILE_B + wid * 1024 + i * 8192), 16, 0, 0);
;       }
;     }
;     const char* sb = g_shm + cur * STAGE_B;
; #pragma unroll
;     for (int ks = 0; ks < 2; ++ks) {
;       bf16x8 Bf[4];
; #pragma unroll
;       for (int n = 0; n < 4; ++n) Bf[n] = *(const bf16x8*)(sb + b_base + n * 2048 + ks * 1024);
; #pragma unroll
;       for (int mh = 0; mh < 2; ++mh) {
;         bf16x8 At[4];
; #pragma unroll
;         for (int m = 0; m < 4; ++m) At[m] = *(const bf16x8*)(sb + a_base + (mh * 4 + m) * 2048 + ks * 1024);
;         __builtin_amdgcn_s_setprio(1);
; #pragma unroll
;         for (int m = 0; m < 4; ++m)
; #pragma unroll
;           for (int n = 0; n < 4; ++n) acc[mh * 4 + m][n] = __builtin_amdgcn_mfma_f32_16x16x32_bf16(Bf[n], At[m], acc[mh * 4 + m][n], 0, 0, 0);
;         __builtin_amdgcn_s_setprio(0);
;       }
;       SBAR();
;     }
;     if (t + 1 < nt) { WAIT_V0(); __syncthreads(); }
;   }
	v_mfma_f32_16x16x32_bf16 v[126:129], v[222:225], v[170:173], v[126:129]
	v_mfma_f32_16x16x32_bf16 v[122:125], v[226:229], v[170:173], v[122:125]
	v_mfma_f32_16x16x32_bf16 v[118:121], v[230:233], v[170:173], v[118:121]
	v_mfma_f32_16x16x32_bf16 v[114:117], v[234:237], v[170:173], v[114:117]
	ds_read_b128 v[170:173], v149 offset:9216
	s_waitcnt lgkmcnt(3)
	v_mfma_f32_16x16x32_bf16 v[110:113], v[222:225], v[174:177], v[110:113]
	v_mfma_f32_16x16x32_bf16 v[106:109], v[226:229], v[174:177], v[106:109]
	v_mfma_f32_16x16x32_bf16 v[102:105], v[230:233], v[174:177], v[102:105]
	v_mfma_f32_16x16x32_bf16 v[98:101], v[234:237], v[174:177], v[98:101]
	ds_read_b128 v[174:177], v149 offset:11264
	s_waitcnt lgkmcnt(3)
	v_mfma_f32_16x16x32_bf16 v[94:97], v[222:225], v[214:217], v[94:97]
	v_mfma_f32_16x16x32_bf16 v[90:93], v[226:229], v[214:217], v[90:93]
	v_mfma_f32_16x16x32_bf16 v[86:89], v[230:233], v[214:217], v[86:89]
	v_mfma_f32_16x16x32_bf16 v[82:85], v[234:237], v[214:217], v[82:85]
	ds_read_b128 v[214:217], v149 offset:13312
	s_waitcnt lgkmcnt(3)
	v_mfma_f32_16x16x32_bf16 v[78:81], v[222:225], v[218:221], v[78:81]
	v_mfma_f32_16x16x32_bf16 v[74:77], v[226:229], v[218:221], v[74:77]
	v_mfma_f32_16x16x32_bf16 v[70:73], v[230:233], v[218:221], v[70:73]
	v_mfma_f32_16x16x32_bf16 v[66:69], v[234:237], v[218:221], v[66:69]
	ds_read_b128 v[218:221], v149 offset:15360
	s_waitcnt lgkmcnt(3)
	v_mfma_f32_16x16x32_bf16 v[62:65], v[222:225], v[170:173], v[62:65]
	v_mfma_f32_16x16x32_bf16 v[58:61], v[226:229], v[170:173], v[58:61]
	v_mfma_f32_16x16x32_bf16 v[54:57], v[230:233], v[170:173], v[54:57]
	v_mfma_f32_16x16x32_bf16 v[50:53], v[234:237], v[170:173], v[50:53]
	s_waitcnt lgkmcnt(2)
	v_mfma_f32_16x16x32_bf16 v[46:49], v[222:225], v[174:177], v[46:49]
	v_mfma_f32_16x16x32_bf16 v[42:45], v[226:229], v[174:177], v[42:45]
	v_mfma_f32_16x16x32_bf16 v[38:41], v[230:233], v[174:177], v[38:41]
	v_mfma_f32_16x16x32_bf16 v[34:37], v[234:237], v[174:177], v[34:37]
	s_waitcnt lgkmcnt(0)
	s_add_i32 s2, s2, 0x10000
	s_waitcnt vmcnt(0)
	s_add_u32 s14, s14, 0x80
	s_addc_u32 s15, s15, 0
	s_cmpk_eq_i32 s14, 0x780
	s_waitcnt vmcnt(0)
	s_barrier
	s_cselect_b32 s100, 1, 0
	s_and_b32 s3, s2, 0x10000
	v_or_b32_e32 v149, s3, v147
	v_add_u32_e32 v169, v149, v148
	v_add_u32_e32 v149, v149, v146
	ds_read_b128 v[150:153], v169 offset:32768
	ds_read_b128 v[154:157], v169 offset:34816
	ds_read_b128 v[158:161], v169 offset:36864
	ds_read_b128 v[162:165], v169 offset:38912
	ds_read_b128 v[170:173], v149
	ds_read_b128 v[174:177], v149 offset:2048
	s_add_u32 s4, s4, 0x80
	s_addc_u32 s5, s5, 0
	s_add_u32 s6, s6, 0x80
	s_addc_u32 s7, s7, 0
	v_mfma_f32_16x16x32_bf16 v[30:33], v[222:225], v[214:217], v[30:33]
	v_mfma_f32_16x16x32_bf16 v[26:29], v[226:229], v[214:217], v[26:29]
	v_mfma_f32_16x16x32_bf16 v[22:25], v[230:233], v[214:217], v[22:25]
	v_mfma_f32_16x16x32_bf16 v[18:21], v[234:237], v[214:217], v[18:21]
	ds_read_b128 v[214:217], v149 offset:4096
	v_mfma_f32_16x16x32_bf16 v[14:17], v[222:225], v[218:221], v[14:17]
	v_mfma_f32_16x16x32_bf16 v[10:13], v[226:229], v[218:221], v[10:13]
	v_mfma_f32_16x16x32_bf16 v[6:9], v[230:233], v[218:221], v[6:9]
	v_mfma_f32_16x16x32_bf16 v[2:5], v[234:237], v[218:221], v[2:5]
	ds_read_b128 v[218:221], v149 offset:6144
	s_cmp_eq_u32 s100, 1
	s_cbranch_scc0 .Lkl_150_y
.Lkl_150_x:
	s_setprio 0
	s_nop 3
	v_readlane_b32 s4, v240, 0
	v_readlane_b32 s5, v240, 1
	v_readlane_b32 s6, v240, 2
	v_readlane_b32 s7, v240, 3
	v_readlane_b32 s8, v240, 4
	v_readlane_b32 s9, v240, 5
	v_readlane_b32 s10, v240, 6
	s_waitcnt lgkmcnt(0)
	s_xor_b32 s3, s3, 0x10000
	v_or_b32_e32 v149, s3, v147
	v_add_u32_e32 v169, v149, v148
	v_add_u32_e32 v149, v149, v146
	s_cmp_eq_u32 s100, 1
	s_cmp_eq_u64 s[10:11], 0
	s_cbranch_scc1 .LBB0_138
	v_readfirstlane_b32 s2, v140
	v_lshl_add_u64 v[132:133], s[10:11], 0, v[130:131]
	s_mov_b32 m0, s2
	v_readfirstlane_b32 s2, v145
	v_lshl_add_u64 v[130:131], s[12:13], 0, v[130:131]
	global_load_lds_dwordx4 v[132:133], off
	s_mov_b32 m0, s2
	s_mov_b64 s[12:13], 0x20000
	v_readfirstlane_b32 s2, v144
	global_load_lds_dwordx4 v[130:131], off
	v_lshl_add_u64 v[134:135], v[132:133], 0, s[12:13]
	s_mov_b32 m0, s2
	v_readfirstlane_b32 s2, v143
	global_load_lds_dwordx4 v[134:135], off
	v_lshl_add_u64 v[134:135], v[130:131], 0, s[12:13]
	s_mov_b32 m0, s2
	v_readfirstlane_b32 s2, v142
	global_load_lds_dwordx4 v[134:135], off
	v_lshl_add_u64 v[134:135], v[132:133], 0, s[96:97]
	s_mov_b32 m0, s2
	v_readfirstlane_b32 s2, v141
	global_load_lds_dwordx4 v[134:135], off
	v_lshl_add_u64 v[134:135], v[130:131], 0, s[96:97]
	s_mov_b32 m0, s2
	s_mov_b64 s[12:13], 0x60000
	v_readfirstlane_b32 s2, v139
	global_load_lds_dwordx4 v[134:135], off
	v_lshl_add_u64 v[132:133], v[132:133], 0, s[12:13]
	s_mov_b32 m0, s2
	v_readfirstlane_b32 s2, v138
	global_load_lds_dwordx4 v[132:133], off
	v_lshl_add_u64 v[130:131], v[130:131], 0, s[12:13]
	s_mov_b32 m0, s2
	s_nop 0
	global_load_lds_dwordx4 v[130:131], off
	s_branch .LBB0_138

; #define WAIT_V0() asm volatile("s_waitcnt vmcnt(0)" ::: "memory")
; #define SBAR() __builtin_amdgcn_sched_barrier(0)
; template <int EPI>
; DEVI void gemm_tile(const u16* __restrict__ Ab, long lda, const u16* __restrict__ Bb, long ldb, int K, const EpiArgs& e,
;                     bool have0 = false, const u16* __restrict__ nA = nullptr, const u16* __restrict__ nB = nullptr) {
;     ...
;   f32x4 acc[8][4];
; #pragma unroll
;   for (int m = 0; m < 8; ++m)
; #pragma unroll
;     for (int n = 0; n < 4; ++n) acc[m][n] = f32x4{0.f, 0.f, 0.f, 0.f};
;   const int nt = K / BK;
;   if (!have0) GLDS_STAGE(0, 0);
;   WAIT_V0(); __syncthreads();
;   for (int t = 0; t < nt; ++t) {
;     const int cur = t & 1;
;     if (t + 1 < nt) GLDS_STAGE(cur ^ 1, t + 1);
;     else if (nA) {
; #pragma unroll
;       for (int i = 0; i < GL; ++i) {
;         __builtin_amdgcn_global_load_lds((const unsigned*)(nA + (long)i * 64 * lda + toffA), (unsigned*)(g_shm + wid * 1024 + i * 8192), 16, 0, 0);
;         __builtin_amdgcn_global_load_lds((const unsigned*)(nB + (long)i * 64 * ldb + toffB), (unsigned*)(g_shm + TILE_B + wid * 1024 + i * 8192), 16, 0, 0);
;       }
;     }
;     const char* sb = g_shm + cur * STAGE_B;
; #pragma unroll
;     for (int ks = 0; ks < 2; ++ks) {
;       bf16x8 Bf[4];
; #pragma unroll
;       for (int n = 0; n < 4; ++n) Bf[n] = *(const bf16x8*)(sb + b_base + n * 2048 + ks * 1024);
; #pragma unroll
;       for (int mh = 0; mh < 2; ++mh) {
;         bf16x8 At[4];
; #pragma unroll
;         for (int m = 0; m < 4; ++m) At[m] = *(const bf16x8*)(sb + a_base + (mh * 4 + m) * 2048 + ks * 1024);
;         __builtin_amdgcn_s_setprio(1);
; #pragma unroll
;         for (int m = 0; m < 4; ++m)
; #pragma unroll
;           for (int n = 0; n < 4; ++n) acc[mh * 4 + m][n] = __builtin_amdgcn_mfma_f32_16x16x32_bf16(Bf[n], At[m], acc[mh * 4 + m][n], 0, 0, 0);
;         __builtin_amdgcn_s_setprio(0);
;       }
;       SBAR();
;     }
;     if (t + 1 < nt) { WAIT_V0(); __syncthreads(); }
;   }
.Lkl_184:
	s_waitcnt lgkmcnt(3)
	v_mfma_f32_16x16x32_bf16 v[126:129], v[150:153], v[170:173], v[126:129]
	v_mfma_f32_16x16x32_bf16 v[122:125], v[154:157], v[170:173], v[122:125]
	v_mfma_f32_16x16x32_bf16 v[118:121], v[158:161], v[170:173], v[118:121]
	v_mfma_f32_16x16x32_bf16 v[114:117], v[162:165], v[170:173], v[114:117]
	ds_read_b128 v[170:173], v178 offset:8192
	ds_read_b128 v[222:225], v169 offset:33792
	s_add_u32 s8, s4, 0x41800
	s_addc_u32 s9, s5, 0x0
	global_load_lds_dwordx4 v238, s[8:9] offset:2048
	s_add_u32 s8, s4, 0x41440
	s_addc_u32 s9, s5, 0x0
	global_load_lds_dwordx4 v238, s[8:9] offset:3072
.Lkl_184_s4:
	s_waitcnt lgkmcnt(4)
	v_mfma_f32_16x16x32_bf16 v[110:113], v[150:153], v[174:177], v[110:113]
	v_mfma_f32_16x16x32_bf16 v[106:109], v[154:157], v[174:177], v[106:109]
	v_mfma_f32_16x16x32_bf16 v[102:105], v[158:161], v[174:177], v[102:105]
	v_mfma_f32_16x16x32_bf16 v[98:101], v[162:165], v[174:177], v[98:101]
	ds_read_b128 v[174:177], v178 offset:10240
	ds_read_b128 v[226:229], v169 offset:35840
	s_add_i32 m0, s10, 0x9000
	s_add_u32 s8, s6, 0x1000
	s_addc_u32 s9, s7, 0x0
	global_load_lds_dwordx4 v239, s[8:9] offset:-4096
	s_add_u32 s8, s6, 0xc40
	s_addc_u32 s9, s7, 0x0
	global_load_lds_dwordx4 v239, s[8:9] offset:-3072
.Lkl_184_s5:
	s_waitcnt lgkmcnt(5)
	v_mfma_f32_16x16x32_bf16 v[94:97], v[150:153], v[214:217], v[94:97]
	v_mfma_f32_16x16x32_bf16 v[90:93], v[154:157], v[214:217], v[90:93]
	v_mfma_f32_16x16x32_bf16 v[86:89], v[158:161], v[214:217], v[86:89]
	v_mfma_f32_16x16x32_bf16 v[82:85], v[162:165], v[214:217], v[82:85]
	ds_read_b128 v[214:217], v178 offset:12288
	ds_read_b128 v[230:233], v169 offset:37888
	s_add_u32 s8, s6, 0x16800
	s_addc_u32 s9, s7, 0x0
	global_load_lds_dwordx4 v239, s[8:9] offset:-2048
	s_add_u32 s8, s6, 0x16440
	s_addc_u32 s9, s7, 0x0
	global_load_lds_dwordx4 v239, s[8:9] offset:-1024
.Lkl_184_s6:
	s_waitcnt lgkmcnt(6)
	v_mfma_f32_16x16x32_bf16 v[78:81], v[150:153], v[218:221], v[78:81]
	v_mfma_f32_16x16x32_bf16 v[74:77], v[154:157], v[218:221], v[74:77]
	v_mfma_f32_16x16x32_bf16 v[70:73], v[158:161], v[218:221], v[70:73]
	v_mfma_f32_16x16x32_bf16 v[66:69], v[162:165], v[218:221], v[66:69]
	ds_read_b128 v[218:221], v178 offset:14336
	ds_read_b128 v[234:237], v169 offset:39936
	s_add_u32 s8, s6, 0x2c000
	s_addc_u32 s9, s7, 0x0
	global_load_lds_dwordx4 v239, s[8:9] offset:0
	s_add_u32 s8, s6, 0x2bc40
	s_addc_u32 s9, s7, 0x0
	global_load_lds_dwordx4 v239, s[8:9] offset:1024
.Lkl_184_s7:
	s_waitcnt lgkmcnt(7)
	v_mfma_f32_16x16x32_bf16 v[62:65], v[150:153], v[170:173], v[62:65]
	v_mfma_f32_16x16x32_bf16 v[58:61], v[154:157], v[170:173], v[58:61]
	v_mfma_f32_16x16x32_bf16 v[54:57], v[158:161], v[170:173], v[54:57]
	v_mfma_f32_16x16x32_bf16 v[50:53], v[162:165], v[170:173], v[50:53]
	ds_read_b128 v[170:173], v178 offset:1024
	s_add_u32 s8, s6, 0x41800
	s_addc_u32 s9, s7, 0x0
	global_load_lds_dwordx4 v239, s[8:9] offset:2048
	s_add_u32 s8, s6, 0x41440
	s_addc_u32 s9, s7, 0x0
	global_load_lds_dwordx4 v239, s[8:9] offset:3072
; #define WAIT_V0() asm volatile("s_waitcnt vmcnt(0)" ::: "memory")
; #define SBAR() __builtin_amdgcn_sched_barrier(0)
; template <int EPI>
; DEVI void gemm_tile(const u16* __restrict__ Ab, long lda, const u16* __restrict__ Bb, long ldb, int K, const EpiArgs& e,
;                     bool have0 = false, const u16* __restrict__ nA = nullptr, const u16* __restrict__ nB = nullptr) {
;     ...
;   f32x4 acc[8][4];
; #pragma unroll
;   for (int m = 0; m < 8; ++m)
; #pragma unroll
;     for (int n = 0; n < 4; ++n) acc[m][n] = f32x4{0.f, 0.f, 0.f, 0.f};
;   const int nt = K / BK;
;   if (!have0) GLDS_STAGE(0, 0);
;   WAIT_V0(); __syncthreads();
;   for (int t = 0; t < nt; ++t) {
;     const int cur = t & 1;
;     if (t + 1 < nt) GLDS_STAGE(cur ^ 1, t + 1);
;     else if (nA) {
; #pragma unroll
;       for (int i = 0; i < GL; ++i) {
;         __builtin_amdgcn_global_load_lds((const unsigned*)(nA + (long)i * 64 * lda + toffA), (unsigned*)(g_shm + wid * 1024 + i * 8192), 16, 0, 0);
;         __builtin_amdgcn_global_load_lds((const unsigned*)(nB + (long)i * 64 * ldb + toffB), (unsigned*)(g_shm + TILE_B + wid * 1024 + i * 8192), 16, 0, 0);
;       }
;     }
;     const char* sb = g_shm + cur * STAGE_B;
; #pragma unroll
;     for (int ks = 0; ks < 2; ++ks) {
;       bf16x8 Bf[4];
; #pragma unroll
;       for (int n = 0; n < 4; ++n) Bf[n] = *(const bf16x8*)(sb + b_base + n * 2048 + ks * 1024);
; #pragma unroll
;       for (int mh = 0; mh < 2; ++mh) {
;         bf16x8 At[4];
; #pragma unroll
;         for (int m = 0; m < 4; ++m) At[m] = *(const bf16x8*)(sb + a_base + (mh * 4 + m) * 2048 + ks * 1024);
;         __builtin_amdgcn_s_setprio(1);
; #pragma unroll
;         for (int m = 0; m < 4; ++m)
; #pragma unroll
;           for (int n = 0; n < 4; ++n) acc[mh * 4 + m][n] = __builtin_amdgcn_mfma_f32_16x16x32_bf16(Bf[n], At[m], acc[mh * 4 + m][n], 0, 0, 0);
;         __builtin_amdgcn_s_setprio(0);
;       }
;       SBAR();
;     }
;     if (t + 1 < nt) { WAIT_V0(); __syncthreads(); }
;   }
.Lkl_184_s8:
	s_waitcnt lgkmcnt(6)
	v_mfma_f32_16x16x32_bf16 v[46:49], v[150:153], v[174:177], v[46:49]
	v_mfma_f32_16x16x32_bf16 v[42:45], v[154:157], v[174:177], v[42:45]
	v_mfma_f32_16x16x32_bf16 v[38:41], v[158:161], v[174:177], v[38:41]
	v_mfma_f32_16x16x32_bf16 v[34:37], v[162:165], v[174:177], v[34:37]
	ds_read_b128 v[174:177], v178 offset:3072
	s_waitcnt lgkmcnt(5)
	v_mfma_f32_16x16x32_bf16 v[30:33], v[150:153], v[214:217], v[30:33]
	v_mfma_f32_16x16x32_bf16 v[26:29], v[154:157], v[214:217], v[26:29]
	v_mfma_f32_16x16x32_bf16 v[22:25], v[158:161], v[214:217], v[22:25]
	v_mfma_f32_16x16x32_bf16 v[18:21], v[162:165], v[214:217], v[18:21]
	ds_read_b128 v[214:217], v178 offset:5120
	s_waitcnt lgkmcnt(4)
	v_mfma_f32_16x16x32_bf16 v[14:17], v[150:153], v[218:221], v[14:17]
	v_mfma_f32_16x16x32_bf16 v[10:13], v[154:157], v[218:221], v[10:13]
	v_mfma_f32_16x16x32_bf16 v[6:9], v[158:161], v[218:221], v[6:9]
	v_mfma_f32_16x16x32_bf16 v[2:5], v[162:165], v[218:221], v[2:5]
	ds_read_b128 v[218:221], v178 offset:7168
	s_waitcnt lgkmcnt(3)
	v_mfma_f32_16x16x32_bf16 v[126:129], v[222:225], v[170:173], v[126:129]
	v_mfma_f32_16x16x32_bf16 v[122:125], v[226:229], v[170:173], v[122:125]
	v_mfma_f32_16x16x32_bf16 v[118:121], v[230:233], v[170:173], v[118:121]
	v_mfma_f32_16x16x32_bf16 v[114:117], v[234:237], v[170:173], v[114:117]
	ds_read_b128 v[170:173], v178 offset:9216
	s_waitcnt lgkmcnt(3)
	v_mfma_f32_16x16x32_bf16 v[110:113], v[222:225], v[174:177], v[110:113]
	v_mfma_f32_16x16x32_bf16 v[106:109], v[226:229], v[174:177], v[106:109]
	v_mfma_f32_16x16x32_bf16 v[102:105], v[230:233], v[174:177], v[102:105]
	v_mfma_f32_16x16x32_bf16 v[98:101], v[234:237], v[174:177], v[98:101]
	ds_read_b128 v[174:177], v178 offset:11264
	s_waitcnt lgkmcnt(3)
	v_mfma_f32_16x16x32_bf16 v[94:97], v[222:225], v[214:217], v[94:97]
	v_mfma_f32_16x16x32_bf16 v[90:93], v[226:229], v[214:217], v[90:93]
	v_mfma_f32_16x16x32_bf16 v[86:89], v[230:233], v[214:217], v[86:89]
	v_mfma_f32_16x16x32_bf16 v[82:85], v[234:237], v[214:217], v[82:85]
	ds_read_b128 v[214:217], v178 offset:13312
	s_waitcnt lgkmcnt(3)
	v_mfma_f32_16x16x32_bf16 v[78:81], v[222:225], v[218:221], v[78:81]
	v_mfma_f32_16x16x32_bf16 v[74:77], v[226:229], v[218:221], v[74:77]
	v_mfma_f32_16x16x32_bf16 v[70:73], v[230:233], v[218:221], v[70:73]
	v_mfma_f32_16x16x32_bf16 v[66:69], v[234:237], v[218:221], v[66:69]
	ds_read_b128 v[218:221], v178 offset:15360
	s_waitcnt lgkmcnt(3)
	v_mfma_f32_16x16x32_bf16 v[62:65], v[222:225], v[170:173], v[62:65]
	v_mfma_f32_16x16x32_bf16 v[58:61], v[226:229], v[170:173], v[58:61]
	v_mfma_f32_16x16x32_bf16 v[54:57], v[230:233], v[170:173], v[54:57]
	v_mfma_f32_16x16x32_bf16 v[50:53], v[234:237], v[170:173], v[50:53]
	s_waitcnt lgkmcnt(2)
	v_mfma_f32_16x16x32_bf16 v[46:49], v[222:225], v[174:177], v[46:49]
	v_mfma_f32_16x16x32_bf16 v[42:45], v[226:229], v[174:177], v[42:45]
	v_mfma_f32_16x16x32_bf16 v[38:41], v[230:233], v[174:177], v[38:41]
	v_mfma_f32_16x16x32_bf16 v[34:37], v[234:237], v[174:177], v[34:37]
	s_waitcnt lgkmcnt(0)
	s_waitcnt vmcnt(0)
	s_add_u32 s14, s14, 0x80
	s_addc_u32 s15, s15, 0
	s_add_i32 s3, s3, 0x10000
	s_cmpk_eq_i32 s14, 0x1580
	s_waitcnt vmcnt(0)
	s_barrier
	s_cselect_b32 s100, 1, 0
	s_and_b32 s22, s3, 0x10000
	v_or_b32_e32 v150, s22, v149
	v_add_u32_e32 v169, v150, v148
	v_or_b32_e32 v150, s22, v146
	v_add_u32_e32 v178, v150, v147
	ds_read_b128 v[150:153], v169 offset:32768
	ds_read_b128 v[154:157], v169 offset:34816
	ds_read_b128 v[158:161], v169 offset:36864
	ds_read_b128 v[162:165], v169 offset:38912
	ds_read_b128 v[170:173], v178
	ds_read_b128 v[174:177], v178 offset:2048
	s_add_u32 s4, s4, 0x80
	s_addc_u32 s5, s5, 0
	s_add_u32 s6, s6, 0x80
	s_addc_u32 s7, s7, 0
	s_cmp_eq_u32 s100, 1
	s_cbranch_scc1 .Lkl_184_s9
	v_readfirstlane_b32 s10, v143
	s_nop 3
	s_mul_i32 s8, s10, 8
	s_mul_i32 s9, s10, 0
	s_add_i32 s9, s9, 0x8000
	s_cmp_ge_u32 s10, 0x1000
	s_cselect_b32 s10, s9, s8
	s_xor_b32 s8, s22, 0x10000
	s_add_i32 s10, s10, s8
	s_add_i32 m0, s10, 0x1000
	s_add_u32 s8, s4, 0x1000
	s_addc_u32 s9, s5, 0x0
	global_load_lds_dwordx4 v238, s[8:9] offset:-4096
	s_add_u32 s8, s4, 0xc40
	s_addc_u32 s9, s5, 0x0
	global_load_lds_dwordx4 v238, s[8:9] offset:-3072
.Lkl_184_s9:
	v_mfma_f32_16x16x32_bf16 v[30:33], v[222:225], v[214:217], v[30:33]
	v_mfma_f32_16x16x32_bf16 v[26:29], v[226:229], v[214:217], v[26:29]
	v_mfma_f32_16x16x32_bf16 v[22:25], v[230:233], v[214:217], v[22:25]
	v_mfma_f32_16x16x32_bf16 v[18:21], v[234:237], v[214:217], v[18:21]
	ds_read_b128 v[214:217], v178 offset:4096
	s_cmp_eq_u32 s100, 1
	s_cbranch_scc1 .Lkl_184_s10
	s_add_u32 s8, s4, 0x16800
	s_addc_u32 s9, s5, 0x0
	global_load_lds_dwordx4 v238, s[8:9] offset:-2048
	s_add_u32 s8, s4, 0x16440
	s_addc_u32 s9, s5, 0x0
	global_load_lds_dwordx4 v238, s[8:9] offset:-1024
.Lkl_184_s10:
	v_mfma_f32_16x16x32_bf16 v[14:17], v[222:225], v[218:221], v[14:17]
	v_mfma_f32_16x16x32_bf16 v[10:13], v[226:229], v[218:221], v[10:13]
	v_mfma_f32_16x16x32_bf16 v[6:9], v[230:233], v[218:221], v[6:9]
	v_mfma_f32_16x16x32_bf16 v[2:5], v[234:237], v[218:221], v[2:5]
	ds_read_b128 v[218:221], v178 offset:6144
	s_cmp_eq_u32 s100, 1
	s_cbranch_scc1 .Lkl_184_s11
	s_add_u32 s8, s4, 0x2c000
	s_addc_u32 s9, s5, 0x0
	global_load_lds_dwordx4 v238, s[8:9] offset:0
	s_add_u32 s8, s4, 0x2bc40
	s_addc_u32 s9, s5, 0x0
	global_load_lds_dwordx4 v238, s[8:9] offset:1024

; #define WAIT_V0() asm volatile("s_waitcnt vmcnt(0)" ::: "memory")
; #define SBAR() __builtin_amdgcn_sched_barrier(0)
; template <int EPI>
; DEVI void gemm_tile(const u16* __restrict__ Ab, long lda, const u16* __restrict__ Bb, long ldb, int K, const EpiArgs& e,
;                     bool have0 = false, const u16* __restrict__ nA = nullptr, const u16* __restrict__ nB = nullptr) {
;     ...
;   for (int t = 0; t < nt; ++t) {
;     const int cur = t & 1;
;     if (t + 1 < nt) GLDS_STAGE(cur ^ 1, t + 1);
;     else if (nA) {
; #pragma unroll
;       for (int i = 0; i < GL; ++i) {
;         __builtin_amdgcn_global_load_lds((const unsigned*)(nA + (long)i * 64 * lda + toffA), (unsigned*)(g_shm + wid * 1024 + i * 8192), 16, 0, 0);
;         __builtin_amdgcn_global_load_lds((const unsigned*)(nB + (long)i * 64 * ldb + toffB), (unsigned*)(g_shm + TILE_B + wid * 1024 + i * 8192), 16, 0, 0);
;       }
;     }
;     const char* sb = g_shm + cur * STAGE_B;
; #pragma unroll
;     for (int ks = 0; ks < 2; ++ks) {
;       bf16x8 Bf[4];
; #pragma unroll
;       for (int n = 0; n < 4; ++n) Bf[n] = *(const bf16x8*)(sb + b_base + n * 2048 + ks * 1024);
; #pragma unroll
;       for (int mh = 0; mh < 2; ++mh) {
;         bf16x8 At[4];
; #pragma unroll
;         for (int m = 0; m < 4; ++m) At[m] = *(const bf16x8*)(sb + a_base + (mh * 4 + m) * 2048 + ks * 1024);
;         __builtin_amdgcn_s_setprio(1);
; #pragma unroll
;         for (int m = 0; m < 4; ++m)
; #pragma unroll
;           for (int n = 0; n < 4; ++n) acc[mh * 4 + m][n] = __builtin_amdgcn_mfma_f32_16x16x32_bf16(Bf[n], At[m], acc[mh * 4 + m][n], 0, 0, 0);
;         __builtin_amdgcn_s_setprio(0);
;       }
;       SBAR();
;     }
;     if (t + 1 < nt) { WAIT_V0(); __syncthreads(); }
;   }
.Lkl_184_y:
	s_waitcnt lgkmcnt(3)
	v_mfma_f32_16x16x32_bf16 v[126:129], v[150:153], v[170:173], v[126:129]
	v_mfma_f32_16x16x32_bf16 v[122:125], v[154:157], v[170:173], v[122:125]
	v_mfma_f32_16x16x32_bf16 v[118:121], v[158:161], v[170:173], v[118:121]
	v_mfma_f32_16x16x32_bf16 v[114:117], v[162:165], v[170:173], v[114:117]
	ds_read_b128 v[170:173], v178 offset:8192
	ds_read_b128 v[222:225], v169 offset:33792
	s_waitcnt lgkmcnt(4)
	v_mfma_f32_16x16x32_bf16 v[110:113], v[150:153], v[174:177], v[110:113]
	v_mfma_f32_16x16x32_bf16 v[106:109], v[154:157], v[174:177], v[106:109]
	v_mfma_f32_16x16x32_bf16 v[102:105], v[158:161], v[174:177], v[102:105]
	v_mfma_f32_16x16x32_bf16 v[98:101], v[162:165], v[174:177], v[98:101]
	ds_read_b128 v[174:177], v178 offset:10240
	ds_read_b128 v[226:229], v169 offset:35840
	s_waitcnt lgkmcnt(5)
	v_mfma_f32_16x16x32_bf16 v[94:97], v[150:153], v[214:217], v[94:97]
	v_mfma_f32_16x16x32_bf16 v[90:93], v[154:157], v[214:217], v[90:93]
	v_mfma_f32_16x16x32_bf16 v[86:89], v[158:161], v[214:217], v[86:89]
	v_mfma_f32_16x16x32_bf16 v[82:85], v[162:165], v[214:217], v[82:85]
	ds_read_b128 v[214:217], v178 offset:12288
	ds_read_b128 v[230:233], v169 offset:37888
	s_waitcnt lgkmcnt(6)
	v_mfma_f32_16x16x32_bf16 v[78:81], v[150:153], v[218:221], v[78:81]
	v_mfma_f32_16x16x32_bf16 v[74:77], v[154:157], v[218:221], v[74:77]
	v_mfma_f32_16x16x32_bf16 v[70:73], v[158:161], v[218:221], v[70:73]
	v_mfma_f32_16x16x32_bf16 v[66:69], v[162:165], v[218:221], v[66:69]
	ds_read_b128 v[218:221], v178 offset:14336
	ds_read_b128 v[234:237], v169 offset:39936
	s_waitcnt lgkmcnt(7)
	v_mfma_f32_16x16x32_bf16 v[62:65], v[150:153], v[170:173], v[62:65]
	v_mfma_f32_16x16x32_bf16 v[58:61], v[154:157], v[170:173], v[58:61]
	v_mfma_f32_16x16x32_bf16 v[54:57], v[158:161], v[170:173], v[54:57]
	v_mfma_f32_16x16x32_bf16 v[50:53], v[162:165], v[170:173], v[50:53]
	ds_read_b128 v[170:173], v178 offset:1024
	s_waitcnt lgkmcnt(6)
	v_mfma_f32_16x16x32_bf16 v[46:49], v[150:153], v[174:177], v[46:49]
	v_mfma_f32_16x16x32_bf16 v[42:45], v[154:157], v[174:177], v[42:45]
	v_mfma_f32_16x16x32_bf16 v[38:41], v[158:161], v[174:177], v[38:41]
	v_mfma_f32_16x16x32_bf16 v[34:37], v[162:165], v[174:177], v[34:37]
	ds_read_b128 v[174:177], v178 offset:3072
	s_waitcnt lgkmcnt(5)
	v_mfma_f32_16x16x32_bf16 v[30:33], v[150:153], v[214:217], v[30:33]
	v_mfma_f32_16x16x32_bf16 v[26:29], v[154:157], v[214:217], v[26:29]
	v_mfma_f32_16x16x32_bf16 v[22:25], v[158:161], v[214:217], v[22:25]
	v_mfma_f32_16x16x32_bf16 v[18:21], v[162:165], v[214:217], v[18:21]
	ds_read_b128 v[214:217], v178 offset:5120
	s_waitcnt lgkmcnt(4)
	v_mfma_f32_16x16x32_bf16 v[14:17], v[150:153], v[218:221], v[14:17]
	v_mfma_f32_16x16x32_bf16 v[10:13], v[154:157], v[218:221], v[10:13]
	v_mfma_f32_16x16x32_bf16 v[6:9], v[158:161], v[218:221], v[6:9]
	v_mfma_f32_16x16x32_bf16 v[2:5], v[162:165], v[218:221], v[2:5]
	ds_read_b128 v[218:221], v178 offset:7168
	s_waitcnt lgkmcnt(3)
	v_mfma_f32_16x16x32_bf16 v[126:129], v[222:225], v[170:173], v[126:129]
	v_mfma_f32_16x16x32_bf16 v[122:125], v[226:229], v[170:173], v[122:125]
	v_mfma_f32_16x16x32_bf16 v[118:121], v[230:233], v[170:173], v[118:121]
	v_mfma_f32_16x16x32_bf16 v[114:117], v[234:237], v[170:173], v[114:117]
	ds_read_b128 v[170:173], v178 offset:9216
	s_waitcnt lgkmcnt(3)
	v_mfma_f32_16x16x32_bf16 v[110:113], v[222:225], v[174:177], v[110:113]
	v_mfma_f32_16x16x32_bf16 v[106:109], v[226:229], v[174:177], v[106:109]
	v_mfma_f32_16x16x32_bf16 v[102:105], v[230:233], v[174:177], v[102:105]
	v_mfma_f32_16x16x32_bf16 v[98:101], v[234:237], v[174:177], v[98:101]
	ds_read_b128 v[174:177], v178 offset:11264
	s_waitcnt lgkmcnt(3)
	v_mfma_f32_16x16x32_bf16 v[94:97], v[222:225], v[214:217], v[94:97]
	v_mfma_f32_16x16x32_bf16 v[90:93], v[226:229], v[214:217], v[90:93]
	v_mfma_f32_16x16x32_bf16 v[86:89], v[230:233], v[214:217], v[86:89]
	v_mfma_f32_16x16x32_bf16 v[82:85], v[234:237], v[214:217], v[82:85]
	ds_read_b128 v[214:217], v178 offset:13312
	s_waitcnt lgkmcnt(3)
	v_mfma_f32_16x16x32_bf16 v[78:81], v[222:225], v[218:221], v[78:81]
	v_mfma_f32_16x16x32_bf16 v[74:77], v[226:229], v[218:221], v[74:77]
	v_mfma_f32_16x16x32_bf16 v[70:73], v[230:233], v[218:221], v[70:73]
	v_mfma_f32_16x16x32_bf16 v[66:69], v[234:237], v[218:221], v[66:69]
	ds_read_b128 v[218:221], v178 offset:15360
	s_waitcnt lgkmcnt(3)
	v_mfma_f32_16x16x32_bf16 v[62:65], v[222:225], v[170:173], v[62:65]
	v_mfma_f32_16x16x32_bf16 v[58:61], v[226:229], v[170:173], v[58:61]
	v_mfma_f32_16x16x32_bf16 v[54:57], v[230:233], v[170:173], v[54:57]
	v_mfma_f32_16x16x32_bf16 v[50:53], v[234:237], v[170:173], v[50:53]
	s_waitcnt lgkmcnt(2)
	v_mfma_f32_16x16x32_bf16 v[46:49], v[222:225], v[174:177], v[46:49]
	v_mfma_f32_16x16x32_bf16 v[42:45], v[226:229], v[174:177], v[42:45]
	v_mfma_f32_16x16x32_bf16 v[38:41], v[230:233], v[174:177], v[38:41]
	v_mfma_f32_16x16x32_bf16 v[34:37], v[234:237], v[174:177], v[34:37]
	s_waitcnt lgkmcnt(0)
	s_waitcnt vmcnt(0)
	s_add_u32 s14, s14, 0x80
	s_addc_u32 s15, s15, 0
	s_add_i32 s3, s3, 0x10000
	s_cmpk_eq_i32 s14, 0x1580
	s_waitcnt vmcnt(0)
	s_barrier
	s_cselect_b32 s100, 1, 0
	s_and_b32 s22, s3, 0x10000
	v_or_b32_e32 v150, s22, v149
	v_add_u32_e32 v169, v150, v148
	v_or_b32_e32 v150, s22, v146
	v_add_u32_e32 v178, v150, v147
	ds_read_b128 v[150:153], v169 offset:32768
	ds_read_b128 v[154:157], v169 offset:34816
	ds_read_b128 v[158:161], v169 offset:36864
	ds_read_b128 v[162:165], v169 offset:38912
	ds_read_b128 v[170:173], v178
	ds_read_b128 v[174:177], v178 offset:2048
	s_add_u32 s4, s4, 0x80
	s_addc_u32 s5, s5, 0
	s_add_u32 s6, s6, 0x80
	s_addc_u32 s7, s7, 0
	v_mfma_f32_16x16x32_bf16 v[30:33], v[222:225], v[214:217], v[30:33]
	v_mfma_f32_16x16x32_bf16 v[26:29], v[226:229], v[214:217], v[26:29]
	v_mfma_f32_16x16x32_bf16 v[22:25], v[230:233], v[214:217], v[22:25]
	v_mfma_f32_16x16x32_bf16 v[18:21], v[234:237], v[214:217], v[18:21]
	ds_read_b128 v[214:217], v178 offset:4096
	v_mfma_f32_16x16x32_bf16 v[14:17], v[222:225], v[218:221], v[14:17]
	v_mfma_f32_16x16x32_bf16 v[10:13], v[226:229], v[218:221], v[10:13]
	v_mfma_f32_16x16x32_bf16 v[6:9], v[230:233], v[218:221], v[6:9]
	v_mfma_f32_16x16x32_bf16 v[2:5], v[234:237], v[218:221], v[2:5]
	ds_read_b128 v[218:221], v178 offset:6144
	s_cmp_eq_u32 s100, 1
	s_cbranch_scc0 .Lkl_184_y
; template <int EPI>
; DEVI void gemm_tile(const u16* __restrict__ Ab, long lda, const u16* __restrict__ Bb, long ldb, int K, const EpiArgs& e,
;                     bool have0 = false, const u16* __restrict__ nA = nullptr, const u16* __restrict__ nB = nullptr) {
;     ...
;     if (t + 1 < nt) GLDS_STAGE(cur ^ 1, t + 1);
;     else if (nA) {
; #pragma unroll
;       for (int i = 0; i < GL; ++i) {
;         __builtin_amdgcn_global_load_lds((const unsigned*)(nA + (long)i * 64 * lda + toffA), (unsigned*)(g_shm + wid * 1024 + i * 8192), 16, 0, 0);
;         __builtin_amdgcn_global_load_lds((const unsigned*)(nB + (long)i * 64 * ldb + toffB), (unsigned*)(g_shm + TILE_B + wid * 1024 + i * 8192), 16, 0, 0);
;       }
;     }
.Lkl_184_x:
	s_setprio 0
	s_nop 3
	v_readlane_b32 s4, v240, 0
	v_readlane_b32 s5, v240, 1
	v_readlane_b32 s6, v240, 2
	v_readlane_b32 s7, v240, 3
	v_readlane_b32 s8, v240, 4
	v_readlane_b32 s9, v240, 5
	v_readlane_b32 s10, v240, 6
	s_waitcnt lgkmcnt(0)
	s_xor_b32 s22, s22, 0x10000
	v_or_b32_e32 v150, s22, v149
	v_add_u32_e32 v169, v150, v148
	v_or_b32_e32 v150, s22, v146
	v_add_u32_e32 v178, v150, v147
	s_cmp_eq_u32 s100, 1
	s_cmp_eq_u64 s[8:9], 0
	s_cbranch_scc1 .LBB0_172
	v_readfirstlane_b32 s3, v143
	v_lshl_add_u64 v[134:135], s[8:9], 0, v[132:133]
	s_mov_b32 m0, s3
	v_readfirstlane_b32 s3, v145
	v_lshl_add_u64 v[132:133], s[12:13], 0, v[132:133]
	global_load_lds_dwordx4 v[134:135], off
	s_mov_b32 m0, s3
	s_mov_b64 s[12:13], 0x58000
	v_readfirstlane_b32 s3, v144
	global_load_lds_dwordx4 v[132:133], off
	v_lshl_add_u64 v[136:137], v[134:135], 0, s[12:13]
	s_mov_b32 m0, s3
	v_readfirstlane_b32 s3, v142
	global_load_lds_dwordx4 v[136:137], off
	v_lshl_add_u64 v[136:137], v[132:133], 0, s[12:13]
	s_mov_b32 m0, s3
	s_mov_b64 s[12:13], 0xb0000
	v_readfirstlane_b32 s3, v141
	global_load_lds_dwordx4 v[136:137], off
	v_lshl_add_u64 v[136:137], v[134:135], 0, s[12:13]
	s_mov_b32 m0, s3
	v_readfirstlane_b32 s3, v140
	global_load_lds_dwordx4 v[136:137], off
	v_lshl_add_u64 v[136:137], v[132:133], 0, s[12:13]
	s_mov_b32 m0, s3
	s_mov_b64 s[12:13], 0x108000
	v_readfirstlane_b32 s3, v139
	global_load_lds_dwordx4 v[136:137], off
	v_lshl_add_u64 v[134:135], v[134:135], 0, s[12:13]
	s_mov_b32 m0, s3
	v_readfirstlane_b32 s3, v138
	global_load_lds_dwordx4 v[134:135], off
	v_lshl_add_u64 v[132:133], v[132:133], 0, s[12:13]
	s_mov_b32 m0, s3
	s_nop 0
	global_load_lds_dwordx4 v[132:133], off
	s_branch .LBB0_172

; #define WAIT_V0() asm volatile("s_waitcnt vmcnt(0)" ::: "memory")
; #define SBAR() __builtin_amdgcn_sched_barrier(0)
; template <int EPI>
; DEVI void gemm_tile(const u16* __restrict__ Ab, long lda, const u16* __restrict__ Bb, long ldb, int K, const EpiArgs& e,
;                     bool have0 = false, const u16* __restrict__ nA = nullptr, const u16* __restrict__ nB = nullptr) {
;     ...
;   f32x4 acc[8][4];
; #pragma unroll
;   for (int m = 0; m < 8; ++m)
; #pragma unroll
;     for (int n = 0; n < 4; ++n) acc[m][n] = f32x4{0.f, 0.f, 0.f, 0.f};
;   const int nt = K / BK;
;   if (!have0) GLDS_STAGE(0, 0);
;   WAIT_V0(); __syncthreads();
;   for (int t = 0; t < nt; ++t) {
;     const int cur = t & 1;
;     if (t + 1 < nt) GLDS_STAGE(cur ^ 1, t + 1);
;     else if (nA) {
; #pragma unroll
;       for (int i = 0; i < GL; ++i) {
;         __builtin_amdgcn_global_load_lds((const unsigned*)(nA + (long)i * 64 * lda + toffA), (unsigned*)(g_shm + wid * 1024 + i * 8192), 16, 0, 0);
;         __builtin_amdgcn_global_load_lds((const unsigned*)(nB + (long)i * 64 * ldb + toffB), (unsigned*)(g_shm + TILE_B + wid * 1024 + i * 8192), 16, 0, 0);
;       }
;     }
;     const char* sb = g_shm + cur * STAGE_B;
; #pragma unroll
;     for (int ks = 0; ks < 2; ++ks) {
;       bf16x8 Bf[4];
; #pragma unroll
;       for (int n = 0; n < 4; ++n) Bf[n] = *(const bf16x8*)(sb + b_base + n * 2048 + ks * 1024);
; #pragma unroll
;       for (int mh = 0; mh < 2; ++mh) {
;         bf16x8 At[4];
; #pragma unroll
;         for (int m = 0; m < 4; ++m) At[m] = *(const bf16x8*)(sb + a_base + (mh * 4 + m) * 2048 + ks * 1024);
;         __builtin_amdgcn_s_setprio(1);
; #pragma unroll
;         for (int m = 0; m < 4; ++m)
; #pragma unroll
;           for (int n = 0; n < 4; ++n) acc[mh * 4 + m][n] = __builtin_amdgcn_mfma_f32_16x16x32_bf16(Bf[n], At[m], acc[mh * 4 + m][n], 0, 0, 0);
;         __builtin_amdgcn_s_setprio(0);
;       }
;       SBAR();
;     }
;     if (t + 1 < nt) { WAIT_V0(); __syncthreads(); }
;   }
.Lkl_359:
	s_waitcnt lgkmcnt(3)
	v_mfma_f32_16x16x32_bf16 v[126:129], v[150:153], v[170:173], v[126:129]
	v_mfma_f32_16x16x32_bf16 v[122:125], v[154:157], v[170:173], v[122:125]
	v_mfma_f32_16x16x32_bf16 v[118:121], v[158:161], v[170:173], v[118:121]
	v_mfma_f32_16x16x32_bf16 v[114:117], v[162:165], v[170:173], v[114:117]
	ds_read_b128 v[170:173], v178 offset:8192
	ds_read_b128 v[222:225], v169 offset:33792
	s_add_u32 s8, s4, 0x2f800
	s_addc_u32 s9, s5, 0x0
	global_load_lds_dwordx4 v238, s[8:9] offset:2048
	s_add_u32 s8, s4, 0x2f440
	s_addc_u32 s9, s5, 0x0
	global_load_lds_dwordx4 v238, s[8:9] offset:3072

; #define WAIT_V0() asm volatile("s_waitcnt vmcnt(0)" ::: "memory")
; #define SBAR() __builtin_amdgcn_sched_barrier(0)
; template <int EPI>
; DEVI void gemm_tile(const u16* __restrict__ Ab, long lda, const u16* __restrict__ Bb, long ldb, int K, const EpiArgs& e,
;                     bool have0 = false, const u16* __restrict__ nA = nullptr, const u16* __restrict__ nB = nullptr) {
;     ...
;   f32x4 acc[8][4];
; #pragma unroll
;   for (int m = 0; m < 8; ++m)
; #pragma unroll
;     for (int n = 0; n < 4; ++n) acc[m][n] = f32x4{0.f, 0.f, 0.f, 0.f};
;   const int nt = K / BK;
;   if (!have0) GLDS_STAGE(0, 0);
;   WAIT_V0(); __syncthreads();
;   for (int t = 0; t < nt; ++t) {
;     const int cur = t & 1;
;     if (t + 1 < nt) GLDS_STAGE(cur ^ 1, t + 1);
;     else if (nA) {
; #pragma unroll
;       for (int i = 0; i < GL; ++i) {
;         __builtin_amdgcn_global_load_lds((const unsigned*)(nA + (long)i * 64 * lda + toffA), (unsigned*)(g_shm + wid * 1024 + i * 8192), 16, 0, 0);
;         __builtin_amdgcn_global_load_lds((const unsigned*)(nB + (long)i * 64 * ldb + toffB), (unsigned*)(g_shm + TILE_B + wid * 1024 + i * 8192), 16, 0, 0);
;       }
;     }
;     const char* sb = g_shm + cur * STAGE_B;
; #pragma unroll
;     for (int ks = 0; ks < 2; ++ks) {
;       bf16x8 Bf[4];
; #pragma unroll
;       for (int n = 0; n < 4; ++n) Bf[n] = *(const bf16x8*)(sb + b_base + n * 2048 + ks * 1024);
; #pragma unroll
;       for (int mh = 0; mh < 2; ++mh) {
;         bf16x8 At[4];
; #pragma unroll
;         for (int m = 0; m < 4; ++m) At[m] = *(const bf16x8*)(sb + a_base + (mh * 4 + m) * 2048 + ks * 1024);
;         __builtin_amdgcn_s_setprio(1);
; #pragma unroll
;         for (int m = 0; m < 4; ++m)
; #pragma unroll
;           for (int n = 0; n < 4; ++n) acc[mh * 4 + m][n] = __builtin_amdgcn_mfma_f32_16x16x32_bf16(Bf[n], At[m], acc[mh * 4 + m][n], 0, 0, 0);
;         __builtin_amdgcn_s_setprio(0);
;       }
;       SBAR();
;     }
;     if (t + 1 < nt) { WAIT_V0(); __syncthreads(); }
;   }
.Lkl_359_s5:
	s_waitcnt lgkmcnt(5)
	v_mfma_f32_16x16x32_bf16 v[94:97], v[150:153], v[192:195], v[94:97]
	v_mfma_f32_16x16x32_bf16 v[90:93], v[154:157], v[192:195], v[90:93]
	v_mfma_f32_16x16x32_bf16 v[86:89], v[158:161], v[192:195], v[86:89]
	v_mfma_f32_16x16x32_bf16 v[82:85], v[162:165], v[192:195], v[82:85]
	ds_read_b128 v[192:195], v178 offset:12288
	ds_read_b128 v[230:233], v169 offset:37888
	s_add_u32 s8, s6, 0x10800
	s_addc_u32 s9, s7, 0x0
	global_load_lds_dwordx4 v239, s[8:9] offset:-2048
	s_add_u32 s8, s6, 0x10440
	s_addc_u32 s9, s7, 0x0
	global_load_lds_dwordx4 v239, s[8:9] offset:-1024
.Lkl_359_s6:
	s_waitcnt lgkmcnt(6)
	v_mfma_f32_16x16x32_bf16 v[78:81], v[150:153], v[198:201], v[78:81]
	v_mfma_f32_16x16x32_bf16 v[74:77], v[154:157], v[198:201], v[74:77]
	v_mfma_f32_16x16x32_bf16 v[70:73], v[158:161], v[198:201], v[70:73]
	v_mfma_f32_16x16x32_bf16 v[66:69], v[162:165], v[198:201], v[66:69]
	ds_read_b128 v[198:201], v178 offset:14336
	ds_read_b128 v[234:237], v169 offset:39936
	s_add_u32 s8, s6, 0x20000
	s_addc_u32 s9, s7, 0x0
	global_load_lds_dwordx4 v239, s[8:9] offset:0
	s_add_u32 s8, s6, 0x1fc40
	s_addc_u32 s9, s7, 0x0
	global_load_lds_dwordx4 v239, s[8:9] offset:1024
.Lkl_359_s7:
	s_waitcnt lgkmcnt(7)
	v_mfma_f32_16x16x32_bf16 v[62:65], v[150:153], v[170:173], v[62:65]
	v_mfma_f32_16x16x32_bf16 v[58:61], v[154:157], v[170:173], v[58:61]
	v_mfma_f32_16x16x32_bf16 v[54:57], v[158:161], v[170:173], v[54:57]
	v_mfma_f32_16x16x32_bf16 v[50:53], v[162:165], v[170:173], v[50:53]
	ds_read_b128 v[170:173], v178 offset:1024
	s_add_u32 s8, s6, 0x2f800
	s_addc_u32 s9, s7, 0x0
	global_load_lds_dwordx4 v239, s[8:9] offset:2048
	s_add_u32 s8, s6, 0x2f440
	s_addc_u32 s9, s7, 0x0
	global_load_lds_dwordx4 v239, s[8:9] offset:3072
; #define WAIT_V0() asm volatile("s_waitcnt vmcnt(0)" ::: "memory")
; #define SBAR() __builtin_amdgcn_sched_barrier(0)
; template <int EPI>
; DEVI void gemm_tile(const u16* __restrict__ Ab, long lda, const u16* __restrict__ Bb, long ldb, int K, const EpiArgs& e,
;                     bool have0 = false, const u16* __restrict__ nA = nullptr, const u16* __restrict__ nB = nullptr) {
;     ...
;   f32x4 acc[8][4];
; #pragma unroll
;   for (int m = 0; m < 8; ++m)
; #pragma unroll
;     for (int n = 0; n < 4; ++n) acc[m][n] = f32x4{0.f, 0.f, 0.f, 0.f};
;   const int nt = K / BK;
;   if (!have0) GLDS_STAGE(0, 0);
;   WAIT_V0(); __syncthreads();
;   for (int t = 0; t < nt; ++t) {
;     const int cur = t & 1;
;     if (t + 1 < nt) GLDS_STAGE(cur ^ 1, t + 1);
;     else if (nA) {
; #pragma unroll
;       for (int i = 0; i < GL; ++i) {
;         __builtin_amdgcn_global_load_lds((const unsigned*)(nA + (long)i * 64 * lda + toffA), (unsigned*)(g_shm + wid * 1024 + i * 8192), 16, 0, 0);
;         __builtin_amdgcn_global_load_lds((const unsigned*)(nB + (long)i * 64 * ldb + toffB), (unsigned*)(g_shm + TILE_B + wid * 1024 + i * 8192), 16, 0, 0);
;       }
;     }
;     const char* sb = g_shm + cur * STAGE_B;
; #pragma unroll
;     for (int ks = 0; ks < 2; ++ks) {
;       bf16x8 Bf[4];
; #pragma unroll
;       for (int n = 0; n < 4; ++n) Bf[n] = *(const bf16x8*)(sb + b_base + n * 2048 + ks * 1024);
; #pragma unroll
;       for (int mh = 0; mh < 2; ++mh) {
;         bf16x8 At[4];
; #pragma unroll
;         for (int m = 0; m < 4; ++m) At[m] = *(const bf16x8*)(sb + a_base + (mh * 4 + m) * 2048 + ks * 1024);
;         __builtin_amdgcn_s_setprio(1);
; #pragma unroll
;         for (int m = 0; m < 4; ++m)
; #pragma unroll
;           for (int n = 0; n < 4; ++n) acc[mh * 4 + m][n] = __builtin_amdgcn_mfma_f32_16x16x32_bf16(Bf[n], At[m], acc[mh * 4 + m][n], 0, 0, 0);
;         __builtin_amdgcn_s_setprio(0);
;       }
;       SBAR();
;     }
;     if (t + 1 < nt) { WAIT_V0(); __syncthreads(); }
;   }
.Lkl_359_s8:
	s_waitcnt lgkmcnt(6)
	v_mfma_f32_16x16x32_bf16 v[46:49], v[150:153], v[174:177], v[46:49]
	v_mfma_f32_16x16x32_bf16 v[42:45], v[154:157], v[174:177], v[42:45]
	v_mfma_f32_16x16x32_bf16 v[38:41], v[158:161], v[174:177], v[38:41]
	v_mfma_f32_16x16x32_bf16 v[34:37], v[162:165], v[174:177], v[34:37]
	ds_read_b128 v[174:177], v178 offset:3072
	s_waitcnt lgkmcnt(5)
	v_mfma_f32_16x16x32_bf16 v[30:33], v[150:153], v[192:195], v[30:33]
	v_mfma_f32_16x16x32_bf16 v[26:29], v[154:157], v[192:195], v[26:29]
	v_mfma_f32_16x16x32_bf16 v[22:25], v[158:161], v[192:195], v[22:25]
	v_mfma_f32_16x16x32_bf16 v[18:21], v[162:165], v[192:195], v[18:21]
	ds_read_b128 v[192:195], v178 offset:5120
	s_waitcnt lgkmcnt(4)
	v_mfma_f32_16x16x32_bf16 v[14:17], v[150:153], v[198:201], v[14:17]
	v_mfma_f32_16x16x32_bf16 v[10:13], v[154:157], v[198:201], v[10:13]
	v_mfma_f32_16x16x32_bf16 v[6:9], v[158:161], v[198:201], v[6:9]
	v_mfma_f32_16x16x32_bf16 v[2:5], v[162:165], v[198:201], v[2:5]
	ds_read_b128 v[198:201], v178 offset:7168
	s_waitcnt lgkmcnt(3)
	v_mfma_f32_16x16x32_bf16 v[126:129], v[222:225], v[170:173], v[126:129]
	v_mfma_f32_16x16x32_bf16 v[122:125], v[226:229], v[170:173], v[122:125]
	v_mfma_f32_16x16x32_bf16 v[118:121], v[230:233], v[170:173], v[118:121]
	v_mfma_f32_16x16x32_bf16 v[114:117], v[234:237], v[170:173], v[114:117]
	ds_read_b128 v[170:173], v178 offset:9216
	s_waitcnt lgkmcnt(3)
	v_mfma_f32_16x16x32_bf16 v[110:113], v[222:225], v[174:177], v[110:113]
	v_mfma_f32_16x16x32_bf16 v[106:109], v[226:229], v[174:177], v[106:109]
	v_mfma_f32_16x16x32_bf16 v[102:105], v[230:233], v[174:177], v[102:105]
	v_mfma_f32_16x16x32_bf16 v[98:101], v[234:237], v[174:177], v[98:101]
	ds_read_b128 v[174:177], v178 offset:11264
	s_waitcnt lgkmcnt(3)
	v_mfma_f32_16x16x32_bf16 v[94:97], v[222:225], v[192:195], v[94:97]
	v_mfma_f32_16x16x32_bf16 v[90:93], v[226:229], v[192:195], v[90:93]
	v_mfma_f32_16x16x32_bf16 v[86:89], v[230:233], v[192:195], v[86:89]
	v_mfma_f32_16x16x32_bf16 v[82:85], v[234:237], v[192:195], v[82:85]
	ds_read_b128 v[192:195], v178 offset:13312
	s_waitcnt lgkmcnt(3)
	v_mfma_f32_16x16x32_bf16 v[78:81], v[222:225], v[198:201], v[78:81]
	v_mfma_f32_16x16x32_bf16 v[74:77], v[226:229], v[198:201], v[74:77]
	v_mfma_f32_16x16x32_bf16 v[70:73], v[230:233], v[198:201], v[70:73]
	v_mfma_f32_16x16x32_bf16 v[66:69], v[234:237], v[198:201], v[66:69]
	ds_read_b128 v[198:201], v178 offset:15360
	s_waitcnt lgkmcnt(3)
	v_mfma_f32_16x16x32_bf16 v[62:65], v[222:225], v[170:173], v[62:65]
	v_mfma_f32_16x16x32_bf16 v[58:61], v[226:229], v[170:173], v[58:61]
	v_mfma_f32_16x16x32_bf16 v[54:57], v[230:233], v[170:173], v[54:57]
	v_mfma_f32_16x16x32_bf16 v[50:53], v[234:237], v[170:173], v[50:53]
	s_waitcnt lgkmcnt(2)
	v_mfma_f32_16x16x32_bf16 v[46:49], v[222:225], v[174:177], v[46:49]
	v_mfma_f32_16x16x32_bf16 v[42:45], v[226:229], v[174:177], v[42:45]
	v_mfma_f32_16x16x32_bf16 v[38:41], v[230:233], v[174:177], v[38:41]
	v_mfma_f32_16x16x32_bf16 v[34:37], v[234:237], v[174:177], v[34:37]
	s_waitcnt lgkmcnt(0)
	s_waitcnt vmcnt(0)
	s_add_u32 s16, s16, 0x80
	s_addc_u32 s17, s17, 0
	s_add_i32 s2, s2, 0x10000
	s_cmpk_eq_i32 s16, 0xf80
	s_waitcnt vmcnt(0)
	s_barrier
	s_cselect_b32 s100, 1, 0
	s_and_b32 s3, s2, 0x10000
	v_or_b32_e32 v150, s3, v149
	v_add_u32_e32 v169, v150, v148
	v_or_b32_e32 v150, s3, v146
	v_add_u32_e32 v178, v150, v147
	ds_read_b128 v[150:153], v169 offset:32768
	ds_read_b128 v[154:157], v169 offset:34816
	ds_read_b128 v[158:161], v169 offset:36864
	ds_read_b128 v[162:165], v169 offset:38912
	ds_read_b128 v[170:173], v178
	ds_read_b128 v[174:177], v178 offset:2048
	s_add_u32 s4, s4, 0x80
	s_addc_u32 s5, s5, 0
	s_add_u32 s6, s6, 0x80
	s_addc_u32 s7, s7, 0
	s_cmp_eq_u32 s100, 1
	s_cbranch_scc1 .Lkl_359_s9
	v_readfirstlane_b32 s10, v142
	s_nop 3
	s_mul_i32 s8, s10, 8
	s_mul_i32 s9, s10, 0
	s_add_i32 s9, s9, 0x8000
	s_cmp_ge_u32 s10, 0x1000
	s_cselect_b32 s10, s9, s8
	s_xor_b32 s8, s3, 0x10000
	s_add_i32 s10, s10, s8
	s_add_i32 m0, s10, 0x1000
	s_add_u32 s8, s4, 0x1000
	s_addc_u32 s9, s5, 0x0
	global_load_lds_dwordx4 v238, s[8:9] offset:-4096
	s_add_u32 s8, s4, 0xc40
	s_addc_u32 s9, s5, 0x0
	global_load_lds_dwordx4 v238, s[8:9] offset:-3072
.Lkl_359_s9:
	v_mfma_f32_16x16x32_bf16 v[30:33], v[222:225], v[192:195], v[30:33]
	v_mfma_f32_16x16x32_bf16 v[26:29], v[226:229], v[192:195], v[26:29]
	v_mfma_f32_16x16x32_bf16 v[22:25], v[230:233], v[192:195], v[22:25]
	v_mfma_f32_16x16x32_bf16 v[18:21], v[234:237], v[192:195], v[18:21]
	ds_read_b128 v[192:195], v178 offset:4096
	s_cmp_eq_u32 s100, 1
	s_cbranch_scc1 .Lkl_359_s10
	s_add_u32 s8, s4, 0x10800
	s_addc_u32 s9, s5, 0x0
	global_load_lds_dwordx4 v238, s[8:9] offset:-2048
	s_add_u32 s8, s4, 0x10440
	s_addc_u32 s9, s5, 0x0
	global_load_lds_dwordx4 v238, s[8:9] offset:-1024
.Lkl_359_s10:
	v_mfma_f32_16x16x32_bf16 v[14:17], v[222:225], v[198:201], v[14:17]
	v_mfma_f32_16x16x32_bf16 v[10:13], v[226:229], v[198:201], v[10:13]
	v_mfma_f32_16x16x32_bf16 v[6:9], v[230:233], v[198:201], v[6:9]
	v_mfma_f32_16x16x32_bf16 v[2:5], v[234:237], v[198:201], v[2:5]
	ds_read_b128 v[198:201], v178 offset:6144
	s_cmp_eq_u32 s100, 1
	s_cbranch_scc1 .Lkl_359_s11
	s_add_u32 s8, s4, 0x20000
	s_addc_u32 s9, s5, 0x0
	global_load_lds_dwordx4 v238, s[8:9] offset:0
	s_add_u32 s8, s4, 0x1fc40
	s_addc_u32 s9, s5, 0x0
	global_load_lds_dwordx4 v238, s[8:9] offset:1024

; #define WAIT_V0() asm volatile("s_waitcnt vmcnt(0)" ::: "memory")
; #define SBAR() __builtin_amdgcn_sched_barrier(0)
; template <int EPI>
; DEVI void gemm_tile(const u16* __restrict__ Ab, long lda, const u16* __restrict__ Bb, long ldb, int K, const EpiArgs& e,
;                     bool have0 = false, const u16* __restrict__ nA = nullptr, const u16* __restrict__ nB = nullptr) {
;     ...
;   for (int t = 0; t < nt; ++t) {
;     const int cur = t & 1;
;     if (t + 1 < nt) GLDS_STAGE(cur ^ 1, t + 1);
;     else if (nA) {
; #pragma unroll
;       for (int i = 0; i < GL; ++i) {
;         __builtin_amdgcn_global_load_lds((const unsigned*)(nA + (long)i * 64 * lda + toffA), (unsigned*)(g_shm + wid * 1024 + i * 8192), 16, 0, 0);
;         __builtin_amdgcn_global_load_lds((const unsigned*)(nB + (long)i * 64 * ldb + toffB), (unsigned*)(g_shm + TILE_B + wid * 1024 + i * 8192), 16, 0, 0);
;       }
;     }
;     const char* sb = g_shm + cur * STAGE_B;
; #pragma unroll
;     for (int ks = 0; ks < 2; ++ks) {
;       bf16x8 Bf[4];
; #pragma unroll
;       for (int n = 0; n < 4; ++n) Bf[n] = *(const bf16x8*)(sb + b_base + n * 2048 + ks * 1024);
; #pragma unroll
;       for (int mh = 0; mh < 2; ++mh) {
;         bf16x8 At[4];
; #pragma unroll
;         for (int m = 0; m < 4; ++m) At[m] = *(const bf16x8*)(sb + a_base + (mh * 4 + m) * 2048 + ks * 1024);
;         __builtin_amdgcn_s_setprio(1);
; #pragma unroll
;         for (int m = 0; m < 4; ++m)
; #pragma unroll
;           for (int n = 0; n < 4; ++n) acc[mh * 4 + m][n] = __builtin_amdgcn_mfma_f32_16x16x32_bf16(Bf[n], At[m], acc[mh * 4 + m][n], 0, 0, 0);
;         __builtin_amdgcn_s_setprio(0);
;       }
;       SBAR();
;     }
;     if (t + 1 < nt) { WAIT_V0(); __syncthreads(); }
;   }
.Lkl_359_y:
	s_waitcnt lgkmcnt(3)
	v_mfma_f32_16x16x32_bf16 v[126:129], v[150:153], v[170:173], v[126:129]
	v_mfma_f32_16x16x32_bf16 v[122:125], v[154:157], v[170:173], v[122:125]
	v_mfma_f32_16x16x32_bf16 v[118:121], v[158:161], v[170:173], v[118:121]
	v_mfma_f32_16x16x32_bf16 v[114:117], v[162:165], v[170:173], v[114:117]
	ds_read_b128 v[170:173], v178 offset:8192
	ds_read_b128 v[222:225], v169 offset:33792
	s_waitcnt lgkmcnt(4)
	v_mfma_f32_16x16x32_bf16 v[110:113], v[150:153], v[174:177], v[110:113]
	v_mfma_f32_16x16x32_bf16 v[106:109], v[154:157], v[174:177], v[106:109]
	v_mfma_f32_16x16x32_bf16 v[102:105], v[158:161], v[174:177], v[102:105]
	v_mfma_f32_16x16x32_bf16 v[98:101], v[162:165], v[174:177], v[98:101]
	ds_read_b128 v[174:177], v178 offset:10240
	ds_read_b128 v[226:229], v169 offset:35840
	s_waitcnt lgkmcnt(5)
	v_mfma_f32_16x16x32_bf16 v[94:97], v[150:153], v[192:195], v[94:97]
	v_mfma_f32_16x16x32_bf16 v[90:93], v[154:157], v[192:195], v[90:93]
	v_mfma_f32_16x16x32_bf16 v[86:89], v[158:161], v[192:195], v[86:89]
	v_mfma_f32_16x16x32_bf16 v[82:85], v[162:165], v[192:195], v[82:85]
	ds_read_b128 v[192:195], v178 offset:12288
	ds_read_b128 v[230:233], v169 offset:37888
	s_waitcnt lgkmcnt(6)
	v_mfma_f32_16x16x32_bf16 v[78:81], v[150:153], v[198:201], v[78:81]
	v_mfma_f32_16x16x32_bf16 v[74:77], v[154:157], v[198:201], v[74:77]
	v_mfma_f32_16x16x32_bf16 v[70:73], v[158:161], v[198:201], v[70:73]
	v_mfma_f32_16x16x32_bf16 v[66:69], v[162:165], v[198:201], v[66:69]
	ds_read_b128 v[198:201], v178 offset:14336
	ds_read_b128 v[234:237], v169 offset:39936
	s_waitcnt lgkmcnt(7)
	v_mfma_f32_16x16x32_bf16 v[62:65], v[150:153], v[170:173], v[62:65]
	v_mfma_f32_16x16x32_bf16 v[58:61], v[154:157], v[170:173], v[58:61]
	v_mfma_f32_16x16x32_bf16 v[54:57], v[158:161], v[170:173], v[54:57]
	v_mfma_f32_16x16x32_bf16 v[50:53], v[162:165], v[170:173], v[50:53]
	ds_read_b128 v[170:173], v178 offset:1024
	s_waitcnt lgkmcnt(6)
	v_mfma_f32_16x16x32_bf16 v[46:49], v[150:153], v[174:177], v[46:49]
	v_mfma_f32_16x16x32_bf16 v[42:45], v[154:157], v[174:177], v[42:45]
	v_mfma_f32_16x16x32_bf16 v[38:41], v[158:161], v[174:177], v[38:41]
	v_mfma_f32_16x16x32_bf16 v[34:37], v[162:165], v[174:177], v[34:37]
	ds_read_b128 v[174:177], v178 offset:3072
	s_waitcnt lgkmcnt(5)
	v_mfma_f32_16x16x32_bf16 v[30:33], v[150:153], v[192:195], v[30:33]
	v_mfma_f32_16x16x32_bf16 v[26:29], v[154:157], v[192:195], v[26:29]
	v_mfma_f32_16x16x32_bf16 v[22:25], v[158:161], v[192:195], v[22:25]
	v_mfma_f32_16x16x32_bf16 v[18:21], v[162:165], v[192:195], v[18:21]
	ds_read_b128 v[192:195], v178 offset:5120
	s_waitcnt lgkmcnt(4)
	v_mfma_f32_16x16x32_bf16 v[14:17], v[150:153], v[198:201], v[14:17]
	v_mfma_f32_16x16x32_bf16 v[10:13], v[154:157], v[198:201], v[10:13]
	v_mfma_f32_16x16x32_bf16 v[6:9], v[158:161], v[198:201], v[6:9]
	v_mfma_f32_16x16x32_bf16 v[2:5], v[162:165], v[198:201], v[2:5]
	ds_read_b128 v[198:201], v178 offset:7168
	s_waitcnt lgkmcnt(3)
	v_mfma_f32_16x16x32_bf16 v[126:129], v[222:225], v[170:173], v[126:129]
	v_mfma_f32_16x16x32_bf16 v[122:125], v[226:229], v[170:173], v[122:125]
	v_mfma_f32_16x16x32_bf16 v[118:121], v[230:233], v[170:173], v[118:121]
	v_mfma_f32_16x16x32_bf16 v[114:117], v[234:237], v[170:173], v[114:117]
	ds_read_b128 v[170:173], v178 offset:9216
	s_waitcnt lgkmcnt(3)
	v_mfma_f32_16x16x32_bf16 v[110:113], v[222:225], v[174:177], v[110:113]
	v_mfma_f32_16x16x32_bf16 v[106:109], v[226:229], v[174:177], v[106:109]
	v_mfma_f32_16x16x32_bf16 v[102:105], v[230:233], v[174:177], v[102:105]
	v_mfma_f32_16x16x32_bf16 v[98:101], v[234:237], v[174:177], v[98:101]
	ds_read_b128 v[174:177], v178 offset:11264
	s_waitcnt lgkmcnt(3)
	v_mfma_f32_16x16x32_bf16 v[94:97], v[222:225], v[192:195], v[94:97]
	v_mfma_f32_16x16x32_bf16 v[90:93], v[226:229], v[192:195], v[90:93]
	v_mfma_f32_16x16x32_bf16 v[86:89], v[230:233], v[192:195], v[86:89]
	v_mfma_f32_16x16x32_bf16 v[82:85], v[234:237], v[192:195], v[82:85]
	ds_read_b128 v[192:195], v178 offset:13312
	s_waitcnt lgkmcnt(3)
	v_mfma_f32_16x16x32_bf16 v[78:81], v[222:225], v[198:201], v[78:81]
	v_mfma_f32_16x16x32_bf16 v[74:77], v[226:229], v[198:201], v[74:77]
	v_mfma_f32_16x16x32_bf16 v[70:73], v[230:233], v[198:201], v[70:73]
	v_mfma_f32_16x16x32_bf16 v[66:69], v[234:237], v[198:201], v[66:69]
	ds_read_b128 v[198:201], v178 offset:15360
	s_waitcnt lgkmcnt(3)
	v_mfma_f32_16x16x32_bf16 v[62:65], v[222:225], v[170:173], v[62:65]
	v_mfma_f32_16x16x32_bf16 v[58:61], v[226:229], v[170:173], v[58:61]
	v_mfma_f32_16x16x32_bf16 v[54:57], v[230:233], v[170:173], v[54:57]
	v_mfma_f32_16x16x32_bf16 v[50:53], v[234:237], v[170:173], v[50:53]
	s_waitcnt lgkmcnt(2)
	v_mfma_f32_16x16x32_bf16 v[46:49], v[222:225], v[174:177], v[46:49]
	v_mfma_f32_16x16x32_bf16 v[42:45], v[226:229], v[174:177], v[42:45]
	v_mfma_f32_16x16x32_bf16 v[38:41], v[230:233], v[174:177], v[38:41]
	v_mfma_f32_16x16x32_bf16 v[34:37], v[234:237], v[174:177], v[34:37]
	s_waitcnt lgkmcnt(0)
	s_waitcnt vmcnt(0)
	s_add_u32 s16, s16, 0x80
	s_addc_u32 s17, s17, 0
	s_add_i32 s2, s2, 0x10000
	s_cmpk_eq_i32 s16, 0xf80
	s_waitcnt vmcnt(0)
	s_barrier
	s_cselect_b32 s100, 1, 0
	s_and_b32 s3, s2, 0x10000
	v_or_b32_e32 v150, s3, v149
	v_add_u32_e32 v169, v150, v148
	v_or_b32_e32 v150, s3, v146
	v_add_u32_e32 v178, v150, v147
	ds_read_b128 v[150:153], v169 offset:32768
	ds_read_b128 v[154:157], v169 offset:34816
	ds_read_b128 v[158:161], v169 offset:36864
	ds_read_b128 v[162:165], v169 offset:38912
	ds_read_b128 v[170:173], v178
	ds_read_b128 v[174:177], v178 offset:2048
	s_add_u32 s4, s4, 0x80
	s_addc_u32 s5, s5, 0
	s_add_u32 s6, s6, 0x80
	s_addc_u32 s7, s7, 0
	v_mfma_f32_16x16x32_bf16 v[30:33], v[222:225], v[192:195], v[30:33]
	v_mfma_f32_16x16x32_bf16 v[26:29], v[226:229], v[192:195], v[26:29]
	v_mfma_f32_16x16x32_bf16 v[22:25], v[230:233], v[192:195], v[22:25]
	v_mfma_f32_16x16x32_bf16 v[18:21], v[234:237], v[192:195], v[18:21]
	ds_read_b128 v[192:195], v178 offset:4096
	v_mfma_f32_16x16x32_bf16 v[14:17], v[222:225], v[198:201], v[14:17]
	v_mfma_f32_16x16x32_bf16 v[10:13], v[226:229], v[198:201], v[10:13]
	v_mfma_f32_16x16x32_bf16 v[6:9], v[230:233], v[198:201], v[6:9]
	v_mfma_f32_16x16x32_bf16 v[2:5], v[234:237], v[198:201], v[2:5]
	ds_read_b128 v[198:201], v178 offset:6144
	s_cmp_eq_u32 s100, 1
	s_cbranch_scc0 .Lkl_359_y
; template <int EPI>
; DEVI void gemm_tile(const u16* __restrict__ Ab, long lda, const u16* __restrict__ Bb, long ldb, int K, const EpiArgs& e,
;                     bool have0 = false, const u16* __restrict__ nA = nullptr, const u16* __restrict__ nB = nullptr) {
;     ...
;     if (t + 1 < nt) GLDS_STAGE(cur ^ 1, t + 1);
;     else if (nA) {
; #pragma unroll
;       for (int i = 0; i < GL; ++i) {
;         __builtin_amdgcn_global_load_lds((const unsigned*)(nA + (long)i * 64 * lda + toffA), (unsigned*)(g_shm + wid * 1024 + i * 8192), 16, 0, 0);
;         __builtin_amdgcn_global_load_lds((const unsigned*)(nB + (long)i * 64 * ldb + toffB), (unsigned*)(g_shm + TILE_B + wid * 1024 + i * 8192), 16, 0, 0);
;       }
;     }
.Lkl_359_x:
	s_setprio 0
	s_nop 3
	v_readlane_b32 s4, v240, 0
	v_readlane_b32 s5, v240, 1
	v_readlane_b32 s6, v240, 2
	v_readlane_b32 s7, v240, 3
	v_readlane_b32 s8, v240, 4
	v_readlane_b32 s9, v240, 5
	v_readlane_b32 s10, v240, 6
	s_waitcnt lgkmcnt(0)
	s_xor_b32 s3, s3, 0x10000
	v_or_b32_e32 v150, s3, v149
	v_add_u32_e32 v169, v150, v148
	v_or_b32_e32 v150, s3, v146
	v_add_u32_e32 v178, v150, v147
	s_cmp_eq_u32 s100, 1
	s_cmp_eq_u64 s[8:9], 0
	s_cbranch_scc1 .LBB0_362
	v_readfirstlane_b32 s2, v142
	v_lshl_add_u64 v[132:133], s[8:9], 0, v[130:131]
	s_mov_b32 m0, s2
	v_readfirstlane_b32 s2, v145
	v_lshl_add_u64 v[130:131], s[12:13], 0, v[130:131]
	global_load_lds_dwordx4 v[132:133], off
	s_mov_b32 m0, s2
	v_readfirstlane_b32 s2, v144
	global_load_lds_dwordx4 v[130:131], off
	v_lshl_add_u64 v[134:135], v[132:133], 0, s[96:97]
	s_mov_b32 m0, s2
	v_readfirstlane_b32 s2, v143
	global_load_lds_dwordx4 v[134:135], off
	v_lshl_add_u64 v[134:135], v[130:131], 0, s[96:97]
	s_mov_b32 m0, s2
	s_mov_b64 s[12:13], 0x80000
	v_readfirstlane_b32 s2, v141
	global_load_lds_dwordx4 v[134:135], off
	v_lshl_add_u64 v[134:135], v[132:133], 0, s[12:13]
	s_mov_b32 m0, s2
	v_readfirstlane_b32 s2, v140
	global_load_lds_dwordx4 v[134:135], off
	v_lshl_add_u64 v[134:135], v[130:131], 0, s[12:13]
	s_mov_b32 m0, s2
	s_mov_b64 s[12:13], 0xc0000
	v_readfirstlane_b32 s2, v139
	global_load_lds_dwordx4 v[134:135], off
	v_lshl_add_u64 v[132:133], v[132:133], 0, s[12:13]
	s_mov_b32 m0, s2
	v_readfirstlane_b32 s2, v138
	global_load_lds_dwordx4 v[132:133], off
	v_lshl_add_u64 v[130:131], v[130:131], 0, s[12:13]
	s_mov_b32 m0, s2
	s_nop 0
	global_load_lds_dwordx4 v[130:131], off

; #define WAIT_V0() asm volatile("s_waitcnt vmcnt(0)" ::: "memory")
; #define SBAR() __builtin_amdgcn_sched_barrier(0)
; template <int EPI>
; DEVI void gemm_tile(const u16* __restrict__ Ab, long lda, const u16* __restrict__ Bb, long ldb, int K, const EpiArgs& e,
;                     bool have0 = false, const u16* __restrict__ nA = nullptr, const u16* __restrict__ nB = nullptr) {
;     ...
;   f32x4 acc[8][4];
; #pragma unroll
;   for (int m = 0; m < 8; ++m)
; #pragma unroll
;     for (int n = 0; n < 4; ++n) acc[m][n] = f32x4{0.f, 0.f, 0.f, 0.f};
;   const int nt = K / BK;
;   if (!have0) GLDS_STAGE(0, 0);
;   WAIT_V0(); __syncthreads();
;   for (int t = 0; t < nt; ++t) {
;     const int cur = t & 1;
;     if (t + 1 < nt) GLDS_STAGE(cur ^ 1, t + 1);
;     else if (nA) {
; #pragma unroll
;       for (int i = 0; i < GL; ++i) {
;         __builtin_amdgcn_global_load_lds((const unsigned*)(nA + (long)i * 64 * lda + toffA), (unsigned*)(g_shm + wid * 1024 + i * 8192), 16, 0, 0);
;         __builtin_amdgcn_global_load_lds((const unsigned*)(nB + (long)i * 64 * ldb + toffB), (unsigned*)(g_shm + TILE_B + wid * 1024 + i * 8192), 16, 0, 0);
;       }
;     }
;     const char* sb = g_shm + cur * STAGE_B;
; #pragma unroll
;     for (int ks = 0; ks < 2; ++ks) {
;       bf16x8 Bf[4];
; #pragma unroll
;       for (int n = 0; n < 4; ++n) Bf[n] = *(const bf16x8*)(sb + b_base + n * 2048 + ks * 1024);
; #pragma unroll
;       for (int mh = 0; mh < 2; ++mh) {
;         bf16x8 At[4];
; #pragma unroll
;         for (int m = 0; m < 4; ++m) At[m] = *(const bf16x8*)(sb + a_base + (mh * 4 + m) * 2048 + ks * 1024);
;         __builtin_amdgcn_s_setprio(1);
; #pragma unroll
;         for (int m = 0; m < 4; ++m)
; #pragma unroll
;           for (int n = 0; n < 4; ++n) acc[mh * 4 + m][n] = __builtin_amdgcn_mfma_f32_16x16x32_bf16(Bf[n], At[m], acc[mh * 4 + m][n], 0, 0, 0);
;         __builtin_amdgcn_s_setprio(0);
;       }
;       SBAR();
;     }
;     if (t + 1 < nt) { WAIT_V0(); __syncthreads(); }
;   }
.Lkl_459:
	s_waitcnt lgkmcnt(3)
	v_mfma_f32_16x16x32_bf16 v[126:129], v[150:153], v[170:173], v[126:129]
	v_mfma_f32_16x16x32_bf16 v[122:125], v[154:157], v[170:173], v[122:125]
	v_mfma_f32_16x16x32_bf16 v[118:121], v[158:161], v[170:173], v[118:121]
	v_mfma_f32_16x16x32_bf16 v[114:117], v[162:165], v[170:173], v[114:117]
	ds_read_b128 v[170:173], v178 offset:8192
	ds_read_b128 v[222:225], v169 offset:33792
	s_add_u32 s8, s4, 0x17800
	s_addc_u32 s9, s5, 0x0
	global_load_lds_dwordx4 v238, s[8:9] offset:2048
	s_add_u32 s8, s4, 0x17440
	s_addc_u32 s9, s5, 0x0
	global_load_lds_dwordx4 v238, s[8:9] offset:3072

; #define WAIT_V0() asm volatile("s_waitcnt vmcnt(0)" ::: "memory")
; #define SBAR() __builtin_amdgcn_sched_barrier(0)
; template <int EPI>
; DEVI void gemm_tile(const u16* __restrict__ Ab, long lda, const u16* __restrict__ Bb, long ldb, int K, const EpiArgs& e,
;                     bool have0 = false, const u16* __restrict__ nA = nullptr, const u16* __restrict__ nB = nullptr) {
;     ...
;   f32x4 acc[8][4];
; #pragma unroll
;   for (int m = 0; m < 8; ++m)
; #pragma unroll
;     for (int n = 0; n < 4; ++n) acc[m][n] = f32x4{0.f, 0.f, 0.f, 0.f};
;   const int nt = K / BK;
;   if (!have0) GLDS_STAGE(0, 0);
;   WAIT_V0(); __syncthreads();
;   for (int t = 0; t < nt; ++t) {
;     const int cur = t & 1;
;     if (t + 1 < nt) GLDS_STAGE(cur ^ 1, t + 1);
;     else if (nA) {
; #pragma unroll
;       for (int i = 0; i < GL; ++i) {
;         __builtin_amdgcn_global_load_lds((const unsigned*)(nA + (long)i * 64 * lda + toffA), (unsigned*)(g_shm + wid * 1024 + i * 8192), 16, 0, 0);
;         __builtin_amdgcn_global_load_lds((const unsigned*)(nB + (long)i * 64 * ldb + toffB), (unsigned*)(g_shm + TILE_B + wid * 1024 + i * 8192), 16, 0, 0);
;       }
;     }
;     const char* sb = g_shm + cur * STAGE_B;
; #pragma unroll
;     for (int ks = 0; ks < 2; ++ks) {
;       bf16x8 Bf[4];
; #pragma unroll
;       for (int n = 0; n < 4; ++n) Bf[n] = *(const bf16x8*)(sb + b_base + n * 2048 + ks * 1024);
; #pragma unroll
;       for (int mh = 0; mh < 2; ++mh) {
;         bf16x8 At[4];
; #pragma unroll
;         for (int m = 0; m < 4; ++m) At[m] = *(const bf16x8*)(sb + a_base + (mh * 4 + m) * 2048 + ks * 1024);
;         __builtin_amdgcn_s_setprio(1);
; #pragma unroll
;         for (int m = 0; m < 4; ++m)
; #pragma unroll
;           for (int n = 0; n < 4; ++n) acc[mh * 4 + m][n] = __builtin_amdgcn_mfma_f32_16x16x32_bf16(Bf[n], At[m], acc[mh * 4 + m][n], 0, 0, 0);
;         __builtin_amdgcn_s_setprio(0);
;       }
;       SBAR();
;     }
;     if (t + 1 < nt) { WAIT_V0(); __syncthreads(); }
;   }
.Lkl_459_s5:
	s_waitcnt lgkmcnt(5)
	v_mfma_f32_16x16x32_bf16 v[94:97], v[150:153], v[192:195], v[94:97]
	v_mfma_f32_16x16x32_bf16 v[90:93], v[154:157], v[192:195], v[90:93]
	v_mfma_f32_16x16x32_bf16 v[86:89], v[158:161], v[192:195], v[86:89]
	v_mfma_f32_16x16x32_bf16 v[82:85], v[162:165], v[192:195], v[82:85]
	ds_read_b128 v[192:195], v178 offset:12288
	ds_read_b128 v[230:233], v169 offset:37888
	s_add_u32 s8, s6, 0x8800
	s_addc_u32 s9, s7, 0x0
	global_load_lds_dwordx4 v239, s[8:9] offset:-2048
	s_add_u32 s8, s6, 0x8440
	s_addc_u32 s9, s7, 0x0
	global_load_lds_dwordx4 v239, s[8:9] offset:-1024
.Lkl_459_s6:
	s_waitcnt lgkmcnt(6)
	v_mfma_f32_16x16x32_bf16 v[78:81], v[150:153], v[198:201], v[78:81]
	v_mfma_f32_16x16x32_bf16 v[74:77], v[154:157], v[198:201], v[74:77]
	v_mfma_f32_16x16x32_bf16 v[70:73], v[158:161], v[198:201], v[70:73]
	v_mfma_f32_16x16x32_bf16 v[66:69], v[162:165], v[198:201], v[66:69]
	ds_read_b128 v[198:201], v178 offset:14336
	ds_read_b128 v[234:237], v169 offset:39936
	s_add_u32 s8, s6, 0x10000
	s_addc_u32 s9, s7, 0x0
	global_load_lds_dwordx4 v239, s[8:9] offset:0
	s_add_u32 s8, s6, 0xfc40
	s_addc_u32 s9, s7, 0x0
	global_load_lds_dwordx4 v239, s[8:9] offset:1024
.Lkl_459_s7:
	s_waitcnt lgkmcnt(7)
	v_mfma_f32_16x16x32_bf16 v[62:65], v[150:153], v[170:173], v[62:65]
	v_mfma_f32_16x16x32_bf16 v[58:61], v[154:157], v[170:173], v[58:61]
	v_mfma_f32_16x16x32_bf16 v[54:57], v[158:161], v[170:173], v[54:57]
	v_mfma_f32_16x16x32_bf16 v[50:53], v[162:165], v[170:173], v[50:53]
	ds_read_b128 v[170:173], v178 offset:1024
	s_add_u32 s8, s6, 0x17800
	s_addc_u32 s9, s7, 0x0
	global_load_lds_dwordx4 v239, s[8:9] offset:2048
	s_add_u32 s8, s6, 0x17440
	s_addc_u32 s9, s7, 0x0
	global_load_lds_dwordx4 v239, s[8:9] offset:3072
; #define WAIT_V0() asm volatile("s_waitcnt vmcnt(0)" ::: "memory")
; #define SBAR() __builtin_amdgcn_sched_barrier(0)
; template <int EPI>
; DEVI void gemm_tile(const u16* __restrict__ Ab, long lda, const u16* __restrict__ Bb, long ldb, int K, const EpiArgs& e,
;                     bool have0 = false, const u16* __restrict__ nA = nullptr, const u16* __restrict__ nB = nullptr) {
;     ...
;   f32x4 acc[8][4];
; #pragma unroll
;   for (int m = 0; m < 8; ++m)
; #pragma unroll
;     for (int n = 0; n < 4; ++n) acc[m][n] = f32x4{0.f, 0.f, 0.f, 0.f};
;   const int nt = K / BK;
;   if (!have0) GLDS_STAGE(0, 0);
;   WAIT_V0(); __syncthreads();
;   for (int t = 0; t < nt; ++t) {
;     const int cur = t & 1;
;     if (t + 1 < nt) GLDS_STAGE(cur ^ 1, t + 1);
;     else if (nA) {
; #pragma unroll
;       for (int i = 0; i < GL; ++i) {
;         __builtin_amdgcn_global_load_lds((const unsigned*)(nA + (long)i * 64 * lda + toffA), (unsigned*)(g_shm + wid * 1024 + i * 8192), 16, 0, 0);
;         __builtin_amdgcn_global_load_lds((const unsigned*)(nB + (long)i * 64 * ldb + toffB), (unsigned*)(g_shm + TILE_B + wid * 1024 + i * 8192), 16, 0, 0);
;       }
;     }
;     const char* sb = g_shm + cur * STAGE_B;
; #pragma unroll
;     for (int ks = 0; ks < 2; ++ks) {
;       bf16x8 Bf[4];
; #pragma unroll
;       for (int n = 0; n < 4; ++n) Bf[n] = *(const bf16x8*)(sb + b_base + n * 2048 + ks * 1024);
; #pragma unroll
;       for (int mh = 0; mh < 2; ++mh) {
;         bf16x8 At[4];
; #pragma unroll
;         for (int m = 0; m < 4; ++m) At[m] = *(const bf16x8*)(sb + a_base + (mh * 4 + m) * 2048 + ks * 1024);
;         __builtin_amdgcn_s_setprio(1);
; #pragma unroll
;         for (int m = 0; m < 4; ++m)
; #pragma unroll
;           for (int n = 0; n < 4; ++n) acc[mh * 4 + m][n] = __builtin_amdgcn_mfma_f32_16x16x32_bf16(Bf[n], At[m], acc[mh * 4 + m][n], 0, 0, 0);
;         __builtin_amdgcn_s_setprio(0);
;       }
;       SBAR();
;     }
;     if (t + 1 < nt) { WAIT_V0(); __syncthreads(); }
;   }
.Lkl_459_s8:
	s_waitcnt lgkmcnt(6)
	v_mfma_f32_16x16x32_bf16 v[46:49], v[150:153], v[174:177], v[46:49]
	v_mfma_f32_16x16x32_bf16 v[42:45], v[154:157], v[174:177], v[42:45]
	v_mfma_f32_16x16x32_bf16 v[38:41], v[158:161], v[174:177], v[38:41]
	v_mfma_f32_16x16x32_bf16 v[34:37], v[162:165], v[174:177], v[34:37]
	ds_read_b128 v[174:177], v178 offset:3072
	s_waitcnt lgkmcnt(5)
	v_mfma_f32_16x16x32_bf16 v[30:33], v[150:153], v[192:195], v[30:33]
	v_mfma_f32_16x16x32_bf16 v[26:29], v[154:157], v[192:195], v[26:29]
	v_mfma_f32_16x16x32_bf16 v[22:25], v[158:161], v[192:195], v[22:25]
	v_mfma_f32_16x16x32_bf16 v[18:21], v[162:165], v[192:195], v[18:21]
	ds_read_b128 v[192:195], v178 offset:5120
	s_waitcnt lgkmcnt(4)
	v_mfma_f32_16x16x32_bf16 v[14:17], v[150:153], v[198:201], v[14:17]
	v_mfma_f32_16x16x32_bf16 v[10:13], v[154:157], v[198:201], v[10:13]
	v_mfma_f32_16x16x32_bf16 v[6:9], v[158:161], v[198:201], v[6:9]
	v_mfma_f32_16x16x32_bf16 v[2:5], v[162:165], v[198:201], v[2:5]
	ds_read_b128 v[198:201], v178 offset:7168
	s_waitcnt lgkmcnt(3)
	v_mfma_f32_16x16x32_bf16 v[126:129], v[222:225], v[170:173], v[126:129]
	v_mfma_f32_16x16x32_bf16 v[122:125], v[226:229], v[170:173], v[122:125]
	v_mfma_f32_16x16x32_bf16 v[118:121], v[230:233], v[170:173], v[118:121]
	v_mfma_f32_16x16x32_bf16 v[114:117], v[234:237], v[170:173], v[114:117]
	ds_read_b128 v[170:173], v178 offset:9216
	s_waitcnt lgkmcnt(3)
	v_mfma_f32_16x16x32_bf16 v[110:113], v[222:225], v[174:177], v[110:113]
	v_mfma_f32_16x16x32_bf16 v[106:109], v[226:229], v[174:177], v[106:109]
	v_mfma_f32_16x16x32_bf16 v[102:105], v[230:233], v[174:177], v[102:105]
	v_mfma_f32_16x16x32_bf16 v[98:101], v[234:237], v[174:177], v[98:101]
	ds_read_b128 v[174:177], v178 offset:11264
	s_waitcnt lgkmcnt(3)
	v_mfma_f32_16x16x32_bf16 v[94:97], v[222:225], v[192:195], v[94:97]
	v_mfma_f32_16x16x32_bf16 v[90:93], v[226:229], v[192:195], v[90:93]
	v_mfma_f32_16x16x32_bf16 v[86:89], v[230:233], v[192:195], v[86:89]
	v_mfma_f32_16x16x32_bf16 v[82:85], v[234:237], v[192:195], v[82:85]
	ds_read_b128 v[192:195], v178 offset:13312
	s_waitcnt lgkmcnt(3)
	v_mfma_f32_16x16x32_bf16 v[78:81], v[222:225], v[198:201], v[78:81]
	v_mfma_f32_16x16x32_bf16 v[74:77], v[226:229], v[198:201], v[74:77]
	v_mfma_f32_16x16x32_bf16 v[70:73], v[230:233], v[198:201], v[70:73]
	v_mfma_f32_16x16x32_bf16 v[66:69], v[234:237], v[198:201], v[66:69]
	ds_read_b128 v[198:201], v178 offset:15360
	s_waitcnt lgkmcnt(3)
	v_mfma_f32_16x16x32_bf16 v[62:65], v[222:225], v[170:173], v[62:65]
	v_mfma_f32_16x16x32_bf16 v[58:61], v[226:229], v[170:173], v[58:61]
	v_mfma_f32_16x16x32_bf16 v[54:57], v[230:233], v[170:173], v[54:57]
	v_mfma_f32_16x16x32_bf16 v[50:53], v[234:237], v[170:173], v[50:53]
	s_waitcnt lgkmcnt(2)
	v_mfma_f32_16x16x32_bf16 v[46:49], v[222:225], v[174:177], v[46:49]
	v_mfma_f32_16x16x32_bf16 v[42:45], v[226:229], v[174:177], v[42:45]
	v_mfma_f32_16x16x32_bf16 v[38:41], v[230:233], v[174:177], v[38:41]
	v_mfma_f32_16x16x32_bf16 v[34:37], v[234:237], v[174:177], v[34:37]
	s_waitcnt lgkmcnt(0)
	s_waitcnt vmcnt(0)
	s_add_u32 s14, s14, 0x80
	s_addc_u32 s15, s15, 0
	s_add_i32 s2, s2, 0x10000
	s_cmpk_eq_i32 s14, 0x780
	s_waitcnt vmcnt(0)
	s_barrier
	s_cselect_b32 s100, 1, 0
	s_and_b32 s3, s2, 0x10000
	v_or_b32_e32 v150, s3, v149
	v_add_u32_e32 v169, v150, v148
	v_or_b32_e32 v150, s3, v146
	v_add_u32_e32 v178, v150, v147
	ds_read_b128 v[150:153], v169 offset:32768
	ds_read_b128 v[154:157], v169 offset:34816
	ds_read_b128 v[158:161], v169 offset:36864
	ds_read_b128 v[162:165], v169 offset:38912
	ds_read_b128 v[170:173], v178
	ds_read_b128 v[174:177], v178 offset:2048
	s_add_u32 s4, s4, 0x80
	s_addc_u32 s5, s5, 0
	s_add_u32 s6, s6, 0x80
	s_addc_u32 s7, s7, 0
	s_cmp_eq_u32 s100, 1
	s_cbranch_scc1 .Lkl_459_s9
	v_readfirstlane_b32 s10, v142
	s_nop 3
	s_mul_i32 s8, s10, 8
	s_mul_i32 s9, s10, 0
	s_add_i32 s9, s9, 0x8000
	s_cmp_ge_u32 s10, 0x1000
	s_cselect_b32 s10, s9, s8
	s_xor_b32 s8, s3, 0x10000
	s_add_i32 s10, s10, s8
	s_add_i32 m0, s10, 0x1000
	s_add_u32 s8, s4, 0x1000
	s_addc_u32 s9, s5, 0x0
	global_load_lds_dwordx4 v238, s[8:9] offset:-4096
	s_add_u32 s8, s4, 0xc40
	s_addc_u32 s9, s5, 0x0
	global_load_lds_dwordx4 v238, s[8:9] offset:-3072
.Lkl_459_s9:
	v_mfma_f32_16x16x32_bf16 v[30:33], v[222:225], v[192:195], v[30:33]
	v_mfma_f32_16x16x32_bf16 v[26:29], v[226:229], v[192:195], v[26:29]
	v_mfma_f32_16x16x32_bf16 v[22:25], v[230:233], v[192:195], v[22:25]
	v_mfma_f32_16x16x32_bf16 v[18:21], v[234:237], v[192:195], v[18:21]
	ds_read_b128 v[192:195], v178 offset:4096
	s_cmp_eq_u32 s100, 1
	s_cbranch_scc1 .Lkl_459_s10
	s_add_u32 s8, s4, 0x8800
	s_addc_u32 s9, s5, 0x0
	global_load_lds_dwordx4 v238, s[8:9] offset:-2048
	s_add_u32 s8, s4, 0x8440
	s_addc_u32 s9, s5, 0x0
	global_load_lds_dwordx4 v238, s[8:9] offset:-1024
.Lkl_459_s10:
	v_mfma_f32_16x16x32_bf16 v[14:17], v[222:225], v[198:201], v[14:17]
	v_mfma_f32_16x16x32_bf16 v[10:13], v[226:229], v[198:201], v[10:13]
	v_mfma_f32_16x16x32_bf16 v[6:9], v[230:233], v[198:201], v[6:9]
	v_mfma_f32_16x16x32_bf16 v[2:5], v[234:237], v[198:201], v[2:5]
	ds_read_b128 v[198:201], v178 offset:6144
	s_cmp_eq_u32 s100, 1
	s_cbranch_scc1 .Lkl_459_s11
	s_add_u32 s8, s4, 0x10000
	s_addc_u32 s9, s5, 0x0
	global_load_lds_dwordx4 v238, s[8:9] offset:0
	s_add_u32 s8, s4, 0xfc40
	s_addc_u32 s9, s5, 0x0
	global_load_lds_dwordx4 v238, s[8:9] offset:1024

; #define WAIT_V0() asm volatile("s_waitcnt vmcnt(0)" ::: "memory")
; #define SBAR() __builtin_amdgcn_sched_barrier(0)
; template <int EPI>
; DEVI void gemm_tile(const u16* __restrict__ Ab, long lda, const u16* __restrict__ Bb, long ldb, int K, const EpiArgs& e,
;                     bool have0 = false, const u16* __restrict__ nA = nullptr, const u16* __restrict__ nB = nullptr) {
;     ...
;   for (int t = 0; t < nt; ++t) {
;     const int cur = t & 1;
;     if (t + 1 < nt) GLDS_STAGE(cur ^ 1, t + 1);
;     else if (nA) {
; #pragma unroll
;       for (int i = 0; i < GL; ++i) {
;         __builtin_amdgcn_global_load_lds((const unsigned*)(nA + (long)i * 64 * lda + toffA), (unsigned*)(g_shm + wid * 1024 + i * 8192), 16, 0, 0);
;         __builtin_amdgcn_global_load_lds((const unsigned*)(nB + (long)i * 64 * ldb + toffB), (unsigned*)(g_shm + TILE_B + wid * 1024 + i * 8192), 16, 0, 0);
;       }
;     }
;     const char* sb = g_shm + cur * STAGE_B;
; #pragma unroll
;     for (int ks = 0; ks < 2; ++ks) {
;       bf16x8 Bf[4];
; #pragma unroll
;       for (int n = 0; n < 4; ++n) Bf[n] = *(const bf16x8*)(sb + b_base + n * 2048 + ks * 1024);
; #pragma unroll
;       for (int mh = 0; mh < 2; ++mh) {
;         bf16x8 At[4];
; #pragma unroll
;         for (int m = 0; m < 4; ++m) At[m] = *(const bf16x8*)(sb + a_base + (mh * 4 + m) * 2048 + ks * 1024);
;         __builtin_amdgcn_s_setprio(1);
; #pragma unroll
;         for (int m = 0; m < 4; ++m)
; #pragma unroll
;           for (int n = 0; n < 4; ++n) acc[mh * 4 + m][n] = __builtin_amdgcn_mfma_f32_16x16x32_bf16(Bf[n], At[m], acc[mh * 4 + m][n], 0, 0, 0);
;         __builtin_amdgcn_s_setprio(0);
;       }
;       SBAR();
;     }
;     if (t + 1 < nt) { WAIT_V0(); __syncthreads(); }
;   }
.Lkl_459_y:
	s_waitcnt lgkmcnt(3)
	v_mfma_f32_16x16x32_bf16 v[126:129], v[150:153], v[170:173], v[126:129]
	v_mfma_f32_16x16x32_bf16 v[122:125], v[154:157], v[170:173], v[122:125]
	v_mfma_f32_16x16x32_bf16 v[118:121], v[158:161], v[170:173], v[118:121]
	v_mfma_f32_16x16x32_bf16 v[114:117], v[162:165], v[170:173], v[114:117]
	ds_read_b128 v[170:173], v178 offset:8192
	ds_read_b128 v[222:225], v169 offset:33792
	s_waitcnt lgkmcnt(4)
	v_mfma_f32_16x16x32_bf16 v[110:113], v[150:153], v[174:177], v[110:113]
	v_mfma_f32_16x16x32_bf16 v[106:109], v[154:157], v[174:177], v[106:109]
	v_mfma_f32_16x16x32_bf16 v[102:105], v[158:161], v[174:177], v[102:105]
	v_mfma_f32_16x16x32_bf16 v[98:101], v[162:165], v[174:177], v[98:101]
	ds_read_b128 v[174:177], v178 offset:10240
	ds_read_b128 v[226:229], v169 offset:35840
	s_waitcnt lgkmcnt(5)
	v_mfma_f32_16x16x32_bf16 v[94:97], v[150:153], v[192:195], v[94:97]
	v_mfma_f32_16x16x32_bf16 v[90:93], v[154:157], v[192:195], v[90:93]
	v_mfma_f32_16x16x32_bf16 v[86:89], v[158:161], v[192:195], v[86:89]
	v_mfma_f32_16x16x32_bf16 v[82:85], v[162:165], v[192:195], v[82:85]
	ds_read_b128 v[192:195], v178 offset:12288
	ds_read_b128 v[230:233], v169 offset:37888
	s_waitcnt lgkmcnt(6)
	v_mfma_f32_16x16x32_bf16 v[78:81], v[150:153], v[198:201], v[78:81]
	v_mfma_f32_16x16x32_bf16 v[74:77], v[154:157], v[198:201], v[74:77]
	v_mfma_f32_16x16x32_bf16 v[70:73], v[158:161], v[198:201], v[70:73]
	v_mfma_f32_16x16x32_bf16 v[66:69], v[162:165], v[198:201], v[66:69]
	ds_read_b128 v[198:201], v178 offset:14336
	ds_read_b128 v[234:237], v169 offset:39936
	s_waitcnt lgkmcnt(7)
	v_mfma_f32_16x16x32_bf16 v[62:65], v[150:153], v[170:173], v[62:65]
	v_mfma_f32_16x16x32_bf16 v[58:61], v[154:157], v[170:173], v[58:61]
	v_mfma_f32_16x16x32_bf16 v[54:57], v[158:161], v[170:173], v[54:57]
	v_mfma_f32_16x16x32_bf16 v[50:53], v[162:165], v[170:173], v[50:53]
	ds_read_b128 v[170:173], v178 offset:1024
	s_waitcnt lgkmcnt(6)
	v_mfma_f32_16x16x32_bf16 v[46:49], v[150:153], v[174:177], v[46:49]
	v_mfma_f32_16x16x32_bf16 v[42:45], v[154:157], v[174:177], v[42:45]
	v_mfma_f32_16x16x32_bf16 v[38:41], v[158:161], v[174:177], v[38:41]
	v_mfma_f32_16x16x32_bf16 v[34:37], v[162:165], v[174:177], v[34:37]
	ds_read_b128 v[174:177], v178 offset:3072
	s_waitcnt lgkmcnt(5)
	v_mfma_f32_16x16x32_bf16 v[30:33], v[150:153], v[192:195], v[30:33]
	v_mfma_f32_16x16x32_bf16 v[26:29], v[154:157], v[192:195], v[26:29]
	v_mfma_f32_16x16x32_bf16 v[22:25], v[158:161], v[192:195], v[22:25]
	v_mfma_f32_16x16x32_bf16 v[18:21], v[162:165], v[192:195], v[18:21]
	ds_read_b128 v[192:195], v178 offset:5120
	s_waitcnt lgkmcnt(4)
	v_mfma_f32_16x16x32_bf16 v[14:17], v[150:153], v[198:201], v[14:17]
	v_mfma_f32_16x16x32_bf16 v[10:13], v[154:157], v[198:201], v[10:13]
	v_mfma_f32_16x16x32_bf16 v[6:9], v[158:161], v[198:201], v[6:9]
	v_mfma_f32_16x16x32_bf16 v[2:5], v[162:165], v[198:201], v[2:5]
	ds_read_b128 v[198:201], v178 offset:7168
	s_waitcnt lgkmcnt(3)
	v_mfma_f32_16x16x32_bf16 v[126:129], v[222:225], v[170:173], v[126:129]
	v_mfma_f32_16x16x32_bf16 v[122:125], v[226:229], v[170:173], v[122:125]
	v_mfma_f32_16x16x32_bf16 v[118:121], v[230:233], v[170:173], v[118:121]
	v_mfma_f32_16x16x32_bf16 v[114:117], v[234:237], v[170:173], v[114:117]
	ds_read_b128 v[170:173], v178 offset:9216
	s_waitcnt lgkmcnt(3)
	v_mfma_f32_16x16x32_bf16 v[110:113], v[222:225], v[174:177], v[110:113]
	v_mfma_f32_16x16x32_bf16 v[106:109], v[226:229], v[174:177], v[106:109]
	v_mfma_f32_16x16x32_bf16 v[102:105], v[230:233], v[174:177], v[102:105]
	v_mfma_f32_16x16x32_bf16 v[98:101], v[234:237], v[174:177], v[98:101]
	ds_read_b128 v[174:177], v178 offset:11264
	s_waitcnt lgkmcnt(3)
	v_mfma_f32_16x16x32_bf16 v[94:97], v[222:225], v[192:195], v[94:97]
	v_mfma_f32_16x16x32_bf16 v[90:93], v[226:229], v[192:195], v[90:93]
	v_mfma_f32_16x16x32_bf16 v[86:89], v[230:233], v[192:195], v[86:89]
	v_mfma_f32_16x16x32_bf16 v[82:85], v[234:237], v[192:195], v[82:85]
	ds_read_b128 v[192:195], v178 offset:13312
	s_waitcnt lgkmcnt(3)
	v_mfma_f32_16x16x32_bf16 v[78:81], v[222:225], v[198:201], v[78:81]
	v_mfma_f32_16x16x32_bf16 v[74:77], v[226:229], v[198:201], v[74:77]
	v_mfma_f32_16x16x32_bf16 v[70:73], v[230:233], v[198:201], v[70:73]
	v_mfma_f32_16x16x32_bf16 v[66:69], v[234:237], v[198:201], v[66:69]
	ds_read_b128 v[198:201], v178 offset:15360
	s_waitcnt lgkmcnt(3)
	v_mfma_f32_16x16x32_bf16 v[62:65], v[222:225], v[170:173], v[62:65]
	v_mfma_f32_16x16x32_bf16 v[58:61], v[226:229], v[170:173], v[58:61]
	v_mfma_f32_16x16x32_bf16 v[54:57], v[230:233], v[170:173], v[54:57]
	v_mfma_f32_16x16x32_bf16 v[50:53], v[234:237], v[170:173], v[50:53]
	s_waitcnt lgkmcnt(2)
	v_mfma_f32_16x16x32_bf16 v[46:49], v[222:225], v[174:177], v[46:49]
	v_mfma_f32_16x16x32_bf16 v[42:45], v[226:229], v[174:177], v[42:45]
	v_mfma_f32_16x16x32_bf16 v[38:41], v[230:233], v[174:177], v[38:41]
	v_mfma_f32_16x16x32_bf16 v[34:37], v[234:237], v[174:177], v[34:37]
	s_waitcnt lgkmcnt(0)
	s_waitcnt vmcnt(0)
	s_add_u32 s14, s14, 0x80
	s_addc_u32 s15, s15, 0
	s_add_i32 s2, s2, 0x10000
	s_cmpk_eq_i32 s14, 0x780
	s_waitcnt vmcnt(0)
	s_barrier
	s_cselect_b32 s100, 1, 0
	s_and_b32 s3, s2, 0x10000
	v_or_b32_e32 v150, s3, v149
	v_add_u32_e32 v169, v150, v148
	v_or_b32_e32 v150, s3, v146
	v_add_u32_e32 v178, v150, v147
	ds_read_b128 v[150:153], v169 offset:32768
	ds_read_b128 v[154:157], v169 offset:34816
	ds_read_b128 v[158:161], v169 offset:36864
	ds_read_b128 v[162:165], v169 offset:38912
	ds_read_b128 v[170:173], v178
	ds_read_b128 v[174:177], v178 offset:2048
	s_add_u32 s4, s4, 0x80
	s_addc_u32 s5, s5, 0
	s_add_u32 s6, s6, 0x80
	s_addc_u32 s7, s7, 0
	v_mfma_f32_16x16x32_bf16 v[30:33], v[222:225], v[192:195], v[30:33]
	v_mfma_f32_16x16x32_bf16 v[26:29], v[226:229], v[192:195], v[26:29]
	v_mfma_f32_16x16x32_bf16 v[22:25], v[230:233], v[192:195], v[22:25]
	v_mfma_f32_16x16x32_bf16 v[18:21], v[234:237], v[192:195], v[18:21]
	ds_read_b128 v[192:195], v178 offset:4096
	v_mfma_f32_16x16x32_bf16 v[14:17], v[222:225], v[198:201], v[14:17]
	v_mfma_f32_16x16x32_bf16 v[10:13], v[226:229], v[198:201], v[10:13]
	v_mfma_f32_16x16x32_bf16 v[6:9], v[230:233], v[198:201], v[6:9]
	v_mfma_f32_16x16x32_bf16 v[2:5], v[234:237], v[198:201], v[2:5]
	ds_read_b128 v[198:201], v178 offset:6144
	s_cmp_eq_u32 s100, 1
	s_cbranch_scc0 .Lkl_459_y
; template <int EPI>
; DEVI void gemm_tile(const u16* __restrict__ Ab, long lda, const u16* __restrict__ Bb, long ldb, int K, const EpiArgs& e,
;                     bool have0 = false, const u16* __restrict__ nA = nullptr, const u16* __restrict__ nB = nullptr) {
;     ...
;     if (t + 1 < nt) GLDS_STAGE(cur ^ 1, t + 1);
;     else if (nA) {
; #pragma unroll
;       for (int i = 0; i < GL; ++i) {
;         __builtin_amdgcn_global_load_lds((const unsigned*)(nA + (long)i * 64 * lda + toffA), (unsigned*)(g_shm + wid * 1024 + i * 8192), 16, 0, 0);
;         __builtin_amdgcn_global_load_lds((const unsigned*)(nB + (long)i * 64 * ldb + toffB), (unsigned*)(g_shm + TILE_B + wid * 1024 + i * 8192), 16, 0, 0);
;       }
;     }
.Lkl_459_x:
	s_setprio 0
	s_nop 3
	v_readlane_b32 s4, v240, 0
	v_readlane_b32 s5, v240, 1
	v_readlane_b32 s6, v240, 2
	v_readlane_b32 s7, v240, 3
	v_readlane_b32 s8, v240, 4
	v_readlane_b32 s9, v240, 5
	v_readlane_b32 s10, v240, 6
	s_waitcnt lgkmcnt(0)
	s_xor_b32 s3, s3, 0x10000
	v_or_b32_e32 v150, s3, v149
	v_add_u32_e32 v169, v150, v148
	v_or_b32_e32 v150, s3, v146
	v_add_u32_e32 v178, v150, v147
	s_cmp_eq_u32 s100, 1
	s_cmp_eq_u64 s[8:9], 0
	s_cbranch_scc1 .LBB0_447
	v_readfirstlane_b32 s2, v142
	v_lshl_add_u64 v[132:133], s[8:9], 0, v[130:131]
	s_mov_b32 m0, s2
	v_readfirstlane_b32 s2, v145
	v_lshl_add_u64 v[130:131], s[12:13], 0, v[130:131]
	global_load_lds_dwordx4 v[132:133], off
	s_mov_b32 m0, s2
	s_mov_b64 s[12:13], 0x20000
	v_readfirstlane_b32 s2, v144
	global_load_lds_dwordx4 v[130:131], off
	v_lshl_add_u64 v[134:135], v[132:133], 0, s[12:13]
	s_mov_b32 m0, s2
	v_readfirstlane_b32 s2, v143
	global_load_lds_dwordx4 v[134:135], off
	v_lshl_add_u64 v[134:135], v[130:131], 0, s[12:13]
	s_mov_b32 m0, s2
	v_readfirstlane_b32 s2, v141
	global_load_lds_dwordx4 v[134:135], off
	v_lshl_add_u64 v[134:135], v[132:133], 0, s[96:97]
	s_mov_b32 m0, s2
	v_readfirstlane_b32 s2, v140
	global_load_lds_dwordx4 v[134:135], off
	v_lshl_add_u64 v[134:135], v[130:131], 0, s[96:97]
	s_mov_b32 m0, s2
	s_mov_b64 s[12:13], 0x60000
	v_readfirstlane_b32 s2, v139
	global_load_lds_dwordx4 v[134:135], off
	v_lshl_add_u64 v[132:133], v[132:133], 0, s[12:13]
	s_mov_b32 m0, s2
	v_readfirstlane_b32 s2, v138
	global_load_lds_dwordx4 v[132:133], off
	v_lshl_add_u64 v[130:131], v[130:131], 0, s[12:13]
	s_mov_b32 m0, s2
	s_nop 0
	global_load_lds_dwordx4 v[130:131], off
	s_branch .LBB0_447

; template <int EPI>
; DEVI void gemm_tile(const u16* __restrict__ Ab, long lda, const u16* __restrict__ Bb, long ldb, int K, const EpiArgs& e,
;                     bool have0 = false, const u16* __restrict__ nA = nullptr, const u16* __restrict__ nB = nullptr) {
;     ...
;     if (t + 1 < nt) GLDS_STAGE(cur ^ 1, t + 1);
;     else if (nA) {
; #pragma unroll
;       for (int i = 0; i < GL; ++i) {
;         __builtin_amdgcn_global_load_lds((const unsigned*)(nA + (long)i * 64 * lda + toffA), (unsigned*)(g_shm + wid * 1024 + i * 8192), 16, 0, 0);
;         __builtin_amdgcn_global_load_lds((const unsigned*)(nB + (long)i * 64 * ldb + toffB), (unsigned*)(g_shm + TILE_B + wid * 1024 + i * 8192), 16, 0, 0);
;       }
;     }
.Lkl_710_x:
	s_setprio 0
	s_nop 3
	v_readlane_b32 s4, v240, 0
	v_readlane_b32 s5, v240, 1
	v_readlane_b32 s6, v240, 2
	v_readlane_b32 s7, v240, 3
	v_readlane_b32 s8, v240, 4
	v_readlane_b32 s9, v240, 5
	v_readlane_b32 s10, v240, 6
	s_waitcnt lgkmcnt(0)
	s_xor_b32 s3, s3, 0x10000
	v_or_b32_e32 v150, s3, v149
	v_add_u32_e32 v169, v150, v148
	v_or_b32_e32 v150, s3, v146
	v_add_u32_e32 v178, v150, v147
	s_cmp_eq_u32 s100, 1
	s_cmp_eq_u64 s[8:9], 0
	s_cbranch_scc1 .LBB0_698
	v_readfirstlane_b32 s2, v142
	v_lshl_add_u64 v[132:133], s[8:9], 0, v[130:131]
	s_mov_b32 m0, s2
	v_readfirstlane_b32 s2, v145
	v_lshl_add_u64 v[130:131], s[10:11], 0, v[130:131]
	global_load_lds_dwordx4 v[132:133], off
	s_mov_b32 m0, s2
	s_mov_b64 s[10:11], 0x20000
	v_readfirstlane_b32 s2, v144
	global_load_lds_dwordx4 v[130:131], off
	v_lshl_add_u64 v[134:135], v[132:133], 0, s[10:11]
	s_mov_b32 m0, s2
	v_readfirstlane_b32 s2, v143
	global_load_lds_dwordx4 v[134:135], off
	v_lshl_add_u64 v[134:135], v[130:131], 0, s[10:11]
	s_mov_b32 m0, s2
	v_readfirstlane_b32 s2, v141
	global_load_lds_dwordx4 v[134:135], off
	v_lshl_add_u64 v[134:135], v[132:133], 0, s[96:97]
	s_mov_b32 m0, s2
	v_readfirstlane_b32 s2, v140
	global_load_lds_dwordx4 v[134:135], off
	v_lshl_add_u64 v[134:135], v[130:131], 0, s[96:97]
	s_mov_b32 m0, s2
	s_mov_b64 s[10:11], 0x60000
	v_readfirstlane_b32 s2, v139
	global_load_lds_dwordx4 v[134:135], off
	v_lshl_add_u64 v[132:133], v[132:133], 0, s[10:11]
	s_mov_b32 m0, s2
	v_readfirstlane_b32 s2, v138
	global_load_lds_dwordx4 v[132:133], off
	v_lshl_add_u64 v[130:131], v[130:131], 0, s[10:11]
	s_mov_b32 m0, s2
	s_nop 0
	global_load_lds_dwordx4 v[130:131], off
	s_branch .LBB0_698

; #define WAIT_V0() asm volatile("s_waitcnt vmcnt(0)" ::: "memory")
; #define SBAR() __builtin_amdgcn_sched_barrier(0)
; template <int EPI>
; DEVI void gemm_tile(const u16* __restrict__ Ab, long lda, const u16* __restrict__ Bb, long ldb, int K, const EpiArgs& e,
;                     bool have0 = false, const u16* __restrict__ nA = nullptr, const u16* __restrict__ nB = nullptr) {
;     ...
;   f32x4 acc[8][4];
; #pragma unroll
;   for (int m = 0; m < 8; ++m)
; #pragma unroll
;     for (int n = 0; n < 4; ++n) acc[m][n] = f32x4{0.f, 0.f, 0.f, 0.f};
;   const int nt = K / BK;
;   if (!have0) GLDS_STAGE(0, 0);
;   WAIT_V0(); __syncthreads();
;   for (int t = 0; t < nt; ++t) {
;     const int cur = t & 1;
;     if (t + 1 < nt) GLDS_STAGE(cur ^ 1, t + 1);
;     else if (nA) {
; #pragma unroll
;       for (int i = 0; i < GL; ++i) {
;         __builtin_amdgcn_global_load_lds((const unsigned*)(nA + (long)i * 64 * lda + toffA), (unsigned*)(g_shm + wid * 1024 + i * 8192), 16, 0, 0);
;         __builtin_amdgcn_global_load_lds((const unsigned*)(nB + (long)i * 64 * ldb + toffB), (unsigned*)(g_shm + TILE_B + wid * 1024 + i * 8192), 16, 0, 0);
;       }
;     }
;     const char* sb = g_shm + cur * STAGE_B;
; #pragma unroll
;     for (int ks = 0; ks < 2; ++ks) {
;       bf16x8 Bf[4];
; #pragma unroll
;       for (int n = 0; n < 4; ++n) Bf[n] = *(const bf16x8*)(sb + b_base + n * 2048 + ks * 1024);
; #pragma unroll
;       for (int mh = 0; mh < 2; ++mh) {
;         bf16x8 At[4];
; #pragma unroll
;         for (int m = 0; m < 4; ++m) At[m] = *(const bf16x8*)(sb + a_base + (mh * 4 + m) * 2048 + ks * 1024);
;         __builtin_amdgcn_s_setprio(1);
; #pragma unroll
;         for (int m = 0; m < 4; ++m)
; #pragma unroll
;           for (int n = 0; n < 4; ++n) acc[mh * 4 + m][n] = __builtin_amdgcn_mfma_f32_16x16x32_bf16(Bf[n], At[m], acc[mh * 4 + m][n], 0, 0, 0);
;         __builtin_amdgcn_s_setprio(0);
;       }
;       SBAR();
;     }
;     if (t + 1 < nt) { WAIT_V0(); __syncthreads(); }
;   }
.Lkl_1085_s8:
	s_waitcnt lgkmcnt(6)
	v_mfma_f32_16x16x32_bf16 v[46:49], v[150:153], v[174:177], v[46:49]
	v_mfma_f32_16x16x32_bf16 v[42:45], v[154:157], v[174:177], v[42:45]
	v_mfma_f32_16x16x32_bf16 v[38:41], v[158:161], v[174:177], v[38:41]
	v_mfma_f32_16x16x32_bf16 v[34:37], v[162:165], v[174:177], v[34:37]
	ds_read_b128 v[174:177], v178 offset:3072
	s_waitcnt lgkmcnt(5)
	v_mfma_f32_16x16x32_bf16 v[30:33], v[150:153], v[192:195], v[30:33]
	v_mfma_f32_16x16x32_bf16 v[26:29], v[154:157], v[192:195], v[26:29]
	v_mfma_f32_16x16x32_bf16 v[22:25], v[158:161], v[192:195], v[22:25]
	v_mfma_f32_16x16x32_bf16 v[18:21], v[162:165], v[192:195], v[18:21]
	ds_read_b128 v[192:195], v178 offset:5120
	s_waitcnt lgkmcnt(4)
	v_mfma_f32_16x16x32_bf16 v[14:17], v[150:153], v[198:201], v[14:17]
	v_mfma_f32_16x16x32_bf16 v[10:13], v[154:157], v[198:201], v[10:13]
	v_mfma_f32_16x16x32_bf16 v[6:9], v[158:161], v[198:201], v[6:9]
	v_mfma_f32_16x16x32_bf16 v[2:5], v[162:165], v[198:201], v[2:5]
	ds_read_b128 v[198:201], v178 offset:7168
	s_waitcnt lgkmcnt(3)
	v_mfma_f32_16x16x32_bf16 v[126:129], v[222:225], v[170:173], v[126:129]
	v_mfma_f32_16x16x32_bf16 v[122:125], v[226:229], v[170:173], v[122:125]
	v_mfma_f32_16x16x32_bf16 v[118:121], v[230:233], v[170:173], v[118:121]
	v_mfma_f32_16x16x32_bf16 v[114:117], v[234:237], v[170:173], v[114:117]
	ds_read_b128 v[170:173], v178 offset:9216
	s_waitcnt lgkmcnt(3)
	v_mfma_f32_16x16x32_bf16 v[110:113], v[222:225], v[174:177], v[110:113]
	v_mfma_f32_16x16x32_bf16 v[106:109], v[226:229], v[174:177], v[106:109]
	v_mfma_f32_16x16x32_bf16 v[102:105], v[230:233], v[174:177], v[102:105]
	v_mfma_f32_16x16x32_bf16 v[98:101], v[234:237], v[174:177], v[98:101]
	ds_read_b128 v[174:177], v178 offset:11264
	s_waitcnt lgkmcnt(3)
	v_mfma_f32_16x16x32_bf16 v[94:97], v[222:225], v[192:195], v[94:97]
	v_mfma_f32_16x16x32_bf16 v[90:93], v[226:229], v[192:195], v[90:93]
	v_mfma_f32_16x16x32_bf16 v[86:89], v[230:233], v[192:195], v[86:89]
	v_mfma_f32_16x16x32_bf16 v[82:85], v[234:237], v[192:195], v[82:85]
	ds_read_b128 v[192:195], v178 offset:13312
	s_waitcnt lgkmcnt(3)
	v_mfma_f32_16x16x32_bf16 v[78:81], v[222:225], v[198:201], v[78:81]
	v_mfma_f32_16x16x32_bf16 v[74:77], v[226:229], v[198:201], v[74:77]
	v_mfma_f32_16x16x32_bf16 v[70:73], v[230:233], v[198:201], v[70:73]
	v_mfma_f32_16x16x32_bf16 v[66:69], v[234:237], v[198:201], v[66:69]
	ds_read_b128 v[198:201], v178 offset:15360
	s_waitcnt lgkmcnt(3)
	v_mfma_f32_16x16x32_bf16 v[62:65], v[222:225], v[170:173], v[62:65]
	v_mfma_f32_16x16x32_bf16 v[58:61], v[226:229], v[170:173], v[58:61]
	v_mfma_f32_16x16x32_bf16 v[54:57], v[230:233], v[170:173], v[54:57]
	v_mfma_f32_16x16x32_bf16 v[50:53], v[234:237], v[170:173], v[50:53]
	s_waitcnt lgkmcnt(2)
	v_mfma_f32_16x16x32_bf16 v[46:49], v[222:225], v[174:177], v[46:49]
	v_mfma_f32_16x16x32_bf16 v[42:45], v[226:229], v[174:177], v[42:45]
	v_mfma_f32_16x16x32_bf16 v[38:41], v[230:233], v[174:177], v[38:41]
	v_mfma_f32_16x16x32_bf16 v[34:37], v[234:237], v[174:177], v[34:37]
	s_waitcnt lgkmcnt(0)
	s_waitcnt vmcnt(0)
	s_add_u32 s16, s16, 0x80
	s_addc_u32 s17, s17, 0
	s_add_i32 s2, s2, 0x10000
	s_cmpk_eq_i32 s16, 0x780
	s_waitcnt vmcnt(0)
	s_barrier
	s_cselect_b32 s100, 1, 0
	s_and_b32 s3, s2, 0x10000
	v_or_b32_e32 v150, s3, v149
	v_add_u32_e32 v169, v150, v148
	v_or_b32_e32 v150, s3, v146
	v_add_u32_e32 v178, v150, v147
	ds_read_b128 v[150:153], v169 offset:32768
	ds_read_b128 v[154:157], v169 offset:34816
	ds_read_b128 v[158:161], v169 offset:36864
	ds_read_b128 v[162:165], v169 offset:38912
	ds_read_b128 v[170:173], v178
	ds_read_b128 v[174:177], v178 offset:2048
	s_add_u32 s4, s4, 0x80
	s_addc_u32 s5, s5, 0
	s_add_u32 s6, s6, 0x80
	s_addc_u32 s7, s7, 0
	s_cmp_eq_u32 s100, 1
	s_cbranch_scc1 .Lkl_1085_s9
	v_readfirstlane_b32 s10, v142
	s_nop 3
	s_mul_i32 s8, s10, 8
	s_mul_i32 s9, s10, 0
	s_add_i32 s9, s9, 0x8000
	s_cmp_ge_u32 s10, 0x1000
	s_cselect_b32 s10, s9, s8
	s_xor_b32 s8, s3, 0x10000
	s_add_i32 s10, s10, s8
	s_add_i32 m0, s10, 0x1000
	s_add_u32 s8, s4, 0x1000
	s_addc_u32 s9, s5, 0x0
	global_load_lds_dwordx4 v238, s[8:9] offset:-4096
	s_add_u32 s8, s4, 0xc40
	s_addc_u32 s9, s5, 0x0
	global_load_lds_dwordx4 v238, s[8:9] offset:-3072

; #define WAIT_V0() asm volatile("s_waitcnt vmcnt(0)" ::: "memory")
; #define SBAR() __builtin_amdgcn_sched_barrier(0)
; template <int EPI>
; DEVI void gemm_tile(const u16* __restrict__ Ab, long lda, const u16* __restrict__ Bb, long ldb, int K, const EpiArgs& e,
;                     bool have0 = false, const u16* __restrict__ nA = nullptr, const u16* __restrict__ nB = nullptr) {
;     ...
;   for (int t = 0; t < nt; ++t) {
;     const int cur = t & 1;
;     if (t + 1 < nt) GLDS_STAGE(cur ^ 1, t + 1);
;     else if (nA) {
; #pragma unroll
;       for (int i = 0; i < GL; ++i) {
;         __builtin_amdgcn_global_load_lds((const unsigned*)(nA + (long)i * 64 * lda + toffA), (unsigned*)(g_shm + wid * 1024 + i * 8192), 16, 0, 0);
;         __builtin_amdgcn_global_load_lds((const unsigned*)(nB + (long)i * 64 * ldb + toffB), (unsigned*)(g_shm + TILE_B + wid * 1024 + i * 8192), 16, 0, 0);
;       }
;     }
;     const char* sb = g_shm + cur * STAGE_B;
; #pragma unroll
;     for (int ks = 0; ks < 2; ++ks) {
;       bf16x8 Bf[4];
; #pragma unroll
;       for (int n = 0; n < 4; ++n) Bf[n] = *(const bf16x8*)(sb + b_base + n * 2048 + ks * 1024);
; #pragma unroll
;       for (int mh = 0; mh < 2; ++mh) {
;         bf16x8 At[4];
; #pragma unroll
;         for (int m = 0; m < 4; ++m) At[m] = *(const bf16x8*)(sb + a_base + (mh * 4 + m) * 2048 + ks * 1024);
;         __builtin_amdgcn_s_setprio(1);
; #pragma unroll
;         for (int m = 0; m < 4; ++m)
; #pragma unroll
;           for (int n = 0; n < 4; ++n) acc[mh * 4 + m][n] = __builtin_amdgcn_mfma_f32_16x16x32_bf16(Bf[n], At[m], acc[mh * 4 + m][n], 0, 0, 0);
;         __builtin_amdgcn_s_setprio(0);
;       }
;       SBAR();
;     }
;     if (t + 1 < nt) { WAIT_V0(); __syncthreads(); }
;   }
.Lkl_1085_y:
	s_waitcnt lgkmcnt(3)
	v_mfma_f32_16x16x32_bf16 v[126:129], v[150:153], v[170:173], v[126:129]
	v_mfma_f32_16x16x32_bf16 v[122:125], v[154:157], v[170:173], v[122:125]
	v_mfma_f32_16x16x32_bf16 v[118:121], v[158:161], v[170:173], v[118:121]
	v_mfma_f32_16x16x32_bf16 v[114:117], v[162:165], v[170:173], v[114:117]
	ds_read_b128 v[170:173], v178 offset:8192
	ds_read_b128 v[222:225], v169 offset:33792
	s_waitcnt lgkmcnt(4)
	v_mfma_f32_16x16x32_bf16 v[110:113], v[150:153], v[174:177], v[110:113]
	v_mfma_f32_16x16x32_bf16 v[106:109], v[154:157], v[174:177], v[106:109]
	v_mfma_f32_16x16x32_bf16 v[102:105], v[158:161], v[174:177], v[102:105]
	v_mfma_f32_16x16x32_bf16 v[98:101], v[162:165], v[174:177], v[98:101]
	ds_read_b128 v[174:177], v178 offset:10240
	ds_read_b128 v[226:229], v169 offset:35840
	s_waitcnt lgkmcnt(5)
	v_mfma_f32_16x16x32_bf16 v[94:97], v[150:153], v[192:195], v[94:97]
	v_mfma_f32_16x16x32_bf16 v[90:93], v[154:157], v[192:195], v[90:93]
	v_mfma_f32_16x16x32_bf16 v[86:89], v[158:161], v[192:195], v[86:89]
	v_mfma_f32_16x16x32_bf16 v[82:85], v[162:165], v[192:195], v[82:85]
	ds_read_b128 v[192:195], v178 offset:12288
	ds_read_b128 v[230:233], v169 offset:37888
	s_waitcnt lgkmcnt(6)
	v_mfma_f32_16x16x32_bf16 v[78:81], v[150:153], v[198:201], v[78:81]
	v_mfma_f32_16x16x32_bf16 v[74:77], v[154:157], v[198:201], v[74:77]
	v_mfma_f32_16x16x32_bf16 v[70:73], v[158:161], v[198:201], v[70:73]
	v_mfma_f32_16x16x32_bf16 v[66:69], v[162:165], v[198:201], v[66:69]
	ds_read_b128 v[198:201], v178 offset:14336
	ds_read_b128 v[234:237], v169 offset:39936
	s_waitcnt lgkmcnt(7)
	v_mfma_f32_16x16x32_bf16 v[62:65], v[150:153], v[170:173], v[62:65]
	v_mfma_f32_16x16x32_bf16 v[58:61], v[154:157], v[170:173], v[58:61]
	v_mfma_f32_16x16x32_bf16 v[54:57], v[158:161], v[170:173], v[54:57]
	v_mfma_f32_16x16x32_bf16 v[50:53], v[162:165], v[170:173], v[50:53]
	ds_read_b128 v[170:173], v178 offset:1024
	s_waitcnt lgkmcnt(6)
	v_mfma_f32_16x16x32_bf16 v[46:49], v[150:153], v[174:177], v[46:49]
	v_mfma_f32_16x16x32_bf16 v[42:45], v[154:157], v[174:177], v[42:45]
	v_mfma_f32_16x16x32_bf16 v[38:41], v[158:161], v[174:177], v[38:41]
	v_mfma_f32_16x16x32_bf16 v[34:37], v[162:165], v[174:177], v[34:37]
	ds_read_b128 v[174:177], v178 offset:3072
	s_waitcnt lgkmcnt(5)
	v_mfma_f32_16x16x32_bf16 v[30:33], v[150:153], v[192:195], v[30:33]
	v_mfma_f32_16x16x32_bf16 v[26:29], v[154:157], v[192:195], v[26:29]
	v_mfma_f32_16x16x32_bf16 v[22:25], v[158:161], v[192:195], v[22:25]
	v_mfma_f32_16x16x32_bf16 v[18:21], v[162:165], v[192:195], v[18:21]
	ds_read_b128 v[192:195], v178 offset:5120
	s_waitcnt lgkmcnt(4)
	v_mfma_f32_16x16x32_bf16 v[14:17], v[150:153], v[198:201], v[14:17]
	v_mfma_f32_16x16x32_bf16 v[10:13], v[154:157], v[198:201], v[10:13]
	v_mfma_f32_16x16x32_bf16 v[6:9], v[158:161], v[198:201], v[6:9]
	v_mfma_f32_16x16x32_bf16 v[2:5], v[162:165], v[198:201], v[2:5]
	ds_read_b128 v[198:201], v178 offset:7168
	s_waitcnt lgkmcnt(3)
	v_mfma_f32_16x16x32_bf16 v[126:129], v[222:225], v[170:173], v[126:129]
	v_mfma_f32_16x16x32_bf16 v[122:125], v[226:229], v[170:173], v[122:125]
	v_mfma_f32_16x16x32_bf16 v[118:121], v[230:233], v[170:173], v[118:121]
	v_mfma_f32_16x16x32_bf16 v[114:117], v[234:237], v[170:173], v[114:117]
	ds_read_b128 v[170:173], v178 offset:9216
	s_waitcnt lgkmcnt(3)
	v_mfma_f32_16x16x32_bf16 v[110:113], v[222:225], v[174:177], v[110:113]
	v_mfma_f32_16x16x32_bf16 v[106:109], v[226:229], v[174:177], v[106:109]
	v_mfma_f32_16x16x32_bf16 v[102:105], v[230:233], v[174:177], v[102:105]
	v_mfma_f32_16x16x32_bf16 v[98:101], v[234:237], v[174:177], v[98:101]
	ds_read_b128 v[174:177], v178 offset:11264
	s_waitcnt lgkmcnt(3)
	v_mfma_f32_16x16x32_bf16 v[94:97], v[222:225], v[192:195], v[94:97]
	v_mfma_f32_16x16x32_bf16 v[90:93], v[226:229], v[192:195], v[90:93]
	v_mfma_f32_16x16x32_bf16 v[86:89], v[230:233], v[192:195], v[86:89]
	v_mfma_f32_16x16x32_bf16 v[82:85], v[234:237], v[192:195], v[82:85]
	ds_read_b128 v[192:195], v178 offset:13312
	s_waitcnt lgkmcnt(3)
	v_mfma_f32_16x16x32_bf16 v[78:81], v[222:225], v[198:201], v[78:81]
	v_mfma_f32_16x16x32_bf16 v[74:77], v[226:229], v[198:201], v[74:77]
	v_mfma_f32_16x16x32_bf16 v[70:73], v[230:233], v[198:201], v[70:73]
	v_mfma_f32_16x16x32_bf16 v[66:69], v[234:237], v[198:201], v[66:69]
	ds_read_b128 v[198:201], v178 offset:15360
	s_waitcnt lgkmcnt(3)
	v_mfma_f32_16x16x32_bf16 v[62:65], v[222:225], v[170:173], v[62:65]
	v_mfma_f32_16x16x32_bf16 v[58:61], v[226:229], v[170:173], v[58:61]
	v_mfma_f32_16x16x32_bf16 v[54:57], v[230:233], v[170:173], v[54:57]
	v_mfma_f32_16x16x32_bf16 v[50:53], v[234:237], v[170:173], v[50:53]
	s_waitcnt lgkmcnt(2)
	v_mfma_f32_16x16x32_bf16 v[46:49], v[222:225], v[174:177], v[46:49]
	v_mfma_f32_16x16x32_bf16 v[42:45], v[226:229], v[174:177], v[42:45]
	v_mfma_f32_16x16x32_bf16 v[38:41], v[230:233], v[174:177], v[38:41]
	v_mfma_f32_16x16x32_bf16 v[34:37], v[234:237], v[174:177], v[34:37]
	s_waitcnt lgkmcnt(0)
	s_waitcnt vmcnt(0)
	s_add_u32 s16, s16, 0x80
	s_addc_u32 s17, s17, 0
	s_add_i32 s2, s2, 0x10000
	s_cmpk_eq_i32 s16, 0x780
	s_waitcnt vmcnt(0)
	s_barrier
	s_cselect_b32 s100, 1, 0
	s_and_b32 s3, s2, 0x10000
	v_or_b32_e32 v150, s3, v149
	v_add_u32_e32 v169, v150, v148
	v_or_b32_e32 v150, s3, v146
	v_add_u32_e32 v178, v150, v147
	ds_read_b128 v[150:153], v169 offset:32768
	ds_read_b128 v[154:157], v169 offset:34816
	ds_read_b128 v[158:161], v169 offset:36864
	ds_read_b128 v[162:165], v169 offset:38912
	ds_read_b128 v[170:173], v178
	ds_read_b128 v[174:177], v178 offset:2048
	s_add_u32 s4, s4, 0x80
	s_addc_u32 s5, s5, 0
	s_add_u32 s6, s6, 0x80
	s_addc_u32 s7, s7, 0
	v_mfma_f32_16x16x32_bf16 v[30:33], v[222:225], v[192:195], v[30:33]
	v_mfma_f32_16x16x32_bf16 v[26:29], v[226:229], v[192:195], v[26:29]
	v_mfma_f32_16x16x32_bf16 v[22:25], v[230:233], v[192:195], v[22:25]
	v_mfma_f32_16x16x32_bf16 v[18:21], v[234:237], v[192:195], v[18:21]
	ds_read_b128 v[192:195], v178 offset:4096
	v_mfma_f32_16x16x32_bf16 v[14:17], v[222:225], v[198:201], v[14:17]
	v_mfma_f32_16x16x32_bf16 v[10:13], v[226:229], v[198:201], v[10:13]
	v_mfma_f32_16x16x32_bf16 v[6:9], v[230:233], v[198:201], v[6:9]
	v_mfma_f32_16x16x32_bf16 v[2:5], v[234:237], v[198:201], v[2:5]
	ds_read_b128 v[198:201], v178 offset:6144
	s_cmp_eq_u32 s100, 1
	s_cbranch_scc0 .Lkl_1085_y
; template <int EPI>
; DEVI void gemm_tile(const u16* __restrict__ Ab, long lda, const u16* __restrict__ Bb, long ldb, int K, const EpiArgs& e,
;                     bool have0 = false, const u16* __restrict__ nA = nullptr, const u16* __restrict__ nB = nullptr) {
;     ...
;     if (t + 1 < nt) GLDS_STAGE(cur ^ 1, t + 1);
;     else if (nA) {
; #pragma unroll
;       for (int i = 0; i < GL; ++i) {
;         __builtin_amdgcn_global_load_lds((const unsigned*)(nA + (long)i * 64 * lda + toffA), (unsigned*)(g_shm + wid * 1024 + i * 8192), 16, 0, 0);
;         __builtin_amdgcn_global_load_lds((const unsigned*)(nB + (long)i * 64 * ldb + toffB), (unsigned*)(g_shm + TILE_B + wid * 1024 + i * 8192), 16, 0, 0);
;       }
;     }
.Lkl_1085_x:
	s_setprio 0
	s_nop 3
	v_readlane_b32 s4, v240, 0
	v_readlane_b32 s5, v240, 1
	v_readlane_b32 s6, v240, 2
	v_readlane_b32 s7, v240, 3
	v_readlane_b32 s8, v240, 4
	v_readlane_b32 s9, v240, 5
	v_readlane_b32 s10, v240, 6
	s_waitcnt lgkmcnt(0)
	s_xor_b32 s3, s3, 0x10000
	v_or_b32_e32 v150, s3, v149
	v_add_u32_e32 v169, v150, v148
	v_or_b32_e32 v150, s3, v146
	v_add_u32_e32 v178, v150, v147
	s_cmp_eq_u32 s100, 1
	s_cmp_eq_u64 s[8:9], 0
	s_cbranch_scc1 .LBB0_1073
	v_readfirstlane_b32 s2, v142
	v_lshl_add_u64 v[134:135], s[8:9], 0, v[132:133]
	s_mov_b32 m0, s2
	v_readfirstlane_b32 s2, v145
	v_lshl_add_u64 v[132:133], s[12:13], 0, v[132:133]
	global_load_lds_dwordx4 v[134:135], off
	s_mov_b32 m0, s2
	s_mov_b64 s[12:13], 0x20000
	v_readfirstlane_b32 s2, v144
	global_load_lds_dwordx4 v[132:133], off
	v_lshl_add_u64 v[136:137], v[134:135], 0, s[12:13]
	s_mov_b32 m0, s2
	v_readfirstlane_b32 s2, v143
	global_load_lds_dwordx4 v[136:137], off
	v_lshl_add_u64 v[136:137], v[132:133], 0, s[12:13]
	s_mov_b32 m0, s2
	v_readfirstlane_b32 s2, v141
	global_load_lds_dwordx4 v[136:137], off
	v_lshl_add_u64 v[136:137], v[134:135], 0, s[96:97]
	s_mov_b32 m0, s2
	v_readfirstlane_b32 s2, v140
	global_load_lds_dwordx4 v[136:137], off
	v_lshl_add_u64 v[136:137], v[132:133], 0, s[96:97]
	s_mov_b32 m0, s2
	s_mov_b64 s[12:13], 0x60000
	v_readfirstlane_b32 s2, v139
	global_load_lds_dwordx4 v[136:137], off
	v_lshl_add_u64 v[134:135], v[134:135], 0, s[12:13]
	s_mov_b32 m0, s2
	v_readfirstlane_b32 s2, v138
	global_load_lds_dwordx4 v[134:135], off
	v_lshl_add_u64 v[132:133], v[132:133], 0, s[12:13]
	s_mov_b32 m0, s2
	s_nop 0
	global_load_lds_dwordx4 v[132:133], off
	s_branch .LBB0_1073

; #define WAIT_V0() asm volatile("s_waitcnt vmcnt(0)" ::: "memory")
; #define SBAR() __builtin_amdgcn_sched_barrier(0)
; template <int EPI>
; DEVI void gemm_tile(const u16* __restrict__ Ab, long lda, const u16* __restrict__ Bb, long ldb, int K, const EpiArgs& e,
;                     bool have0 = false, const u16* __restrict__ nA = nullptr, const u16* __restrict__ nB = nullptr) {
;     ...
;   f32x4 acc[8][4];
; #pragma unroll
;   for (int m = 0; m < 8; ++m)
; #pragma unroll
;     for (int n = 0; n < 4; ++n) acc[m][n] = f32x4{0.f, 0.f, 0.f, 0.f};
;   const int nt = K / BK;
;   if (!have0) GLDS_STAGE(0, 0);
;   WAIT_V0(); __syncthreads();
;   for (int t = 0; t < nt; ++t) {
;     const int cur = t & 1;
;     if (t + 1 < nt) GLDS_STAGE(cur ^ 1, t + 1);
;     else if (nA) {
; #pragma unroll
;       for (int i = 0; i < GL; ++i) {
;         __builtin_amdgcn_global_load_lds((const unsigned*)(nA + (long)i * 64 * lda + toffA), (unsigned*)(g_shm + wid * 1024 + i * 8192), 16, 0, 0);
;         __builtin_amdgcn_global_load_lds((const unsigned*)(nB + (long)i * 64 * ldb + toffB), (unsigned*)(g_shm + TILE_B + wid * 1024 + i * 8192), 16, 0, 0);
;       }
;     }
;     const char* sb = g_shm + cur * STAGE_B;
; #pragma unroll
;     for (int ks = 0; ks < 2; ++ks) {
;       bf16x8 Bf[4];
; #pragma unroll
;       for (int n = 0; n < 4; ++n) Bf[n] = *(const bf16x8*)(sb + b_base + n * 2048 + ks * 1024);
; #pragma unroll
;       for (int mh = 0; mh < 2; ++mh) {
;         bf16x8 At[4];
; #pragma unroll
;         for (int m = 0; m < 4; ++m) At[m] = *(const bf16x8*)(sb + a_base + (mh * 4 + m) * 2048 + ks * 1024);
;         __builtin_amdgcn_s_setprio(1);
; #pragma unroll
;         for (int m = 0; m < 4; ++m)
; #pragma unroll
;           for (int n = 0; n < 4; ++n) acc[mh * 4 + m][n] = __builtin_amdgcn_mfma_f32_16x16x32_bf16(Bf[n], At[m], acc[mh * 4 + m][n], 0, 0, 0);
;         __builtin_amdgcn_s_setprio(0);
;       }
;       SBAR();
;     }
;     if (t + 1 < nt) { WAIT_V0(); __syncthreads(); }
;   }
.Lkl_1121_s5:
	s_waitcnt lgkmcnt(5)
	v_mfma_f32_16x16x32_bf16 v[94:97], v[150:153], v[214:217], v[94:97]
	v_mfma_f32_16x16x32_bf16 v[90:93], v[154:157], v[214:217], v[90:93]
	v_mfma_f32_16x16x32_bf16 v[86:89], v[158:161], v[214:217], v[86:89]
	v_mfma_f32_16x16x32_bf16 v[82:85], v[162:165], v[214:217], v[82:85]
	ds_read_b128 v[214:217], v178 offset:12288
	ds_read_b128 v[230:233], v169 offset:37888
	s_add_u32 s8, s6, 0x8800
	s_addc_u32 s9, s7, 0x0
	global_load_lds_dwordx4 v239, s[8:9] offset:-2048
	s_add_u32 s8, s6, 0x8440
	s_addc_u32 s9, s7, 0x0
	global_load_lds_dwordx4 v239, s[8:9] offset:-1024
.Lkl_1121_s6:
	s_waitcnt lgkmcnt(6)
	v_mfma_f32_16x16x32_bf16 v[78:81], v[150:153], v[218:221], v[78:81]
	v_mfma_f32_16x16x32_bf16 v[74:77], v[154:157], v[218:221], v[74:77]
	v_mfma_f32_16x16x32_bf16 v[70:73], v[158:161], v[218:221], v[70:73]
	v_mfma_f32_16x16x32_bf16 v[66:69], v[162:165], v[218:221], v[66:69]
	ds_read_b128 v[218:221], v178 offset:14336
	ds_read_b128 v[234:237], v169 offset:39936
	s_add_u32 s8, s6, 0x10000
	s_addc_u32 s9, s7, 0x0
	global_load_lds_dwordx4 v239, s[8:9] offset:0
	s_add_u32 s8, s6, 0xfc40
	s_addc_u32 s9, s7, 0x0
	global_load_lds_dwordx4 v239, s[8:9] offset:1024

; #define WAIT_V0() asm volatile("s_waitcnt vmcnt(0)" ::: "memory")
; #define SBAR() __builtin_amdgcn_sched_barrier(0)
; template <int EPI>
; DEVI void gemm_tile(const u16* __restrict__ Ab, long lda, const u16* __restrict__ Bb, long ldb, int K, const EpiArgs& e,
;                     bool have0 = false, const u16* __restrict__ nA = nullptr, const u16* __restrict__ nB = nullptr) {
;     ...
;   f32x4 acc[8][4];
; #pragma unroll
;   for (int m = 0; m < 8; ++m)
; #pragma unroll
;     for (int n = 0; n < 4; ++n) acc[m][n] = f32x4{0.f, 0.f, 0.f, 0.f};
;   const int nt = K / BK;
;   if (!have0) GLDS_STAGE(0, 0);
;   WAIT_V0(); __syncthreads();
;   for (int t = 0; t < nt; ++t) {
;     const int cur = t & 1;
;     if (t + 1 < nt) GLDS_STAGE(cur ^ 1, t + 1);
;     else if (nA) {
; #pragma unroll
;       for (int i = 0; i < GL; ++i) {
;         __builtin_amdgcn_global_load_lds((const unsigned*)(nA + (long)i * 64 * lda + toffA), (unsigned*)(g_shm + wid * 1024 + i * 8192), 16, 0, 0);
;         __builtin_amdgcn_global_load_lds((const unsigned*)(nB + (long)i * 64 * ldb + toffB), (unsigned*)(g_shm + TILE_B + wid * 1024 + i * 8192), 16, 0, 0);
;       }
;     }
;     const char* sb = g_shm + cur * STAGE_B;
; #pragma unroll
;     for (int ks = 0; ks < 2; ++ks) {
;       bf16x8 Bf[4];
; #pragma unroll
;       for (int n = 0; n < 4; ++n) Bf[n] = *(const bf16x8*)(sb + b_base + n * 2048 + ks * 1024);
; #pragma unroll
;       for (int mh = 0; mh < 2; ++mh) {
;         bf16x8 At[4];
; #pragma unroll
;         for (int m = 0; m < 4; ++m) At[m] = *(const bf16x8*)(sb + a_base + (mh * 4 + m) * 2048 + ks * 1024);
;         __builtin_amdgcn_s_setprio(1);
; #pragma unroll
;         for (int m = 0; m < 4; ++m)
; #pragma unroll
;           for (int n = 0; n < 4; ++n) acc[mh * 4 + m][n] = __builtin_amdgcn_mfma_f32_16x16x32_bf16(Bf[n], At[m], acc[mh * 4 + m][n], 0, 0, 0);
;         __builtin_amdgcn_s_setprio(0);
;       }
;       SBAR();
;     }
;     if (t + 1 < nt) { WAIT_V0(); __syncthreads(); }
;   }
.Lkl_1121_s8:
	s_waitcnt lgkmcnt(6)
	v_mfma_f32_16x16x32_bf16 v[46:49], v[150:153], v[174:177], v[46:49]
	v_mfma_f32_16x16x32_bf16 v[42:45], v[154:157], v[174:177], v[42:45]
	v_mfma_f32_16x16x32_bf16 v[38:41], v[158:161], v[174:177], v[38:41]
	v_mfma_f32_16x16x32_bf16 v[34:37], v[162:165], v[174:177], v[34:37]
	ds_read_b128 v[174:177], v178 offset:3072
	s_waitcnt lgkmcnt(5)
	v_mfma_f32_16x16x32_bf16 v[30:33], v[150:153], v[214:217], v[30:33]
	v_mfma_f32_16x16x32_bf16 v[26:29], v[154:157], v[214:217], v[26:29]
	v_mfma_f32_16x16x32_bf16 v[22:25], v[158:161], v[214:217], v[22:25]
	v_mfma_f32_16x16x32_bf16 v[18:21], v[162:165], v[214:217], v[18:21]
	ds_read_b128 v[214:217], v178 offset:5120
	s_waitcnt lgkmcnt(4)
	v_mfma_f32_16x16x32_bf16 v[14:17], v[150:153], v[218:221], v[14:17]
	v_mfma_f32_16x16x32_bf16 v[10:13], v[154:157], v[218:221], v[10:13]
	v_mfma_f32_16x16x32_bf16 v[6:9], v[158:161], v[218:221], v[6:9]
	v_mfma_f32_16x16x32_bf16 v[2:5], v[162:165], v[218:221], v[2:5]
	ds_read_b128 v[218:221], v178 offset:7168
	s_waitcnt lgkmcnt(3)
	v_mfma_f32_16x16x32_bf16 v[126:129], v[222:225], v[170:173], v[126:129]
	v_mfma_f32_16x16x32_bf16 v[122:125], v[226:229], v[170:173], v[122:125]
	v_mfma_f32_16x16x32_bf16 v[118:121], v[230:233], v[170:173], v[118:121]
	v_mfma_f32_16x16x32_bf16 v[114:117], v[234:237], v[170:173], v[114:117]
	ds_read_b128 v[170:173], v178 offset:9216
	s_waitcnt lgkmcnt(3)
	v_mfma_f32_16x16x32_bf16 v[110:113], v[222:225], v[174:177], v[110:113]
	v_mfma_f32_16x16x32_bf16 v[106:109], v[226:229], v[174:177], v[106:109]
	v_mfma_f32_16x16x32_bf16 v[102:105], v[230:233], v[174:177], v[102:105]
	v_mfma_f32_16x16x32_bf16 v[98:101], v[234:237], v[174:177], v[98:101]
	ds_read_b128 v[174:177], v178 offset:11264
	s_waitcnt lgkmcnt(3)
	v_mfma_f32_16x16x32_bf16 v[94:97], v[222:225], v[214:217], v[94:97]
	v_mfma_f32_16x16x32_bf16 v[90:93], v[226:229], v[214:217], v[90:93]
	v_mfma_f32_16x16x32_bf16 v[86:89], v[230:233], v[214:217], v[86:89]
	v_mfma_f32_16x16x32_bf16 v[82:85], v[234:237], v[214:217], v[82:85]
	ds_read_b128 v[214:217], v178 offset:13312
	s_waitcnt lgkmcnt(3)
	v_mfma_f32_16x16x32_bf16 v[78:81], v[222:225], v[218:221], v[78:81]
	v_mfma_f32_16x16x32_bf16 v[74:77], v[226:229], v[218:221], v[74:77]
	v_mfma_f32_16x16x32_bf16 v[70:73], v[230:233], v[218:221], v[70:73]
	v_mfma_f32_16x16x32_bf16 v[66:69], v[234:237], v[218:221], v[66:69]
	ds_read_b128 v[218:221], v178 offset:15360
	s_waitcnt lgkmcnt(3)
	v_mfma_f32_16x16x32_bf16 v[62:65], v[222:225], v[170:173], v[62:65]
	v_mfma_f32_16x16x32_bf16 v[58:61], v[226:229], v[170:173], v[58:61]
	v_mfma_f32_16x16x32_bf16 v[54:57], v[230:233], v[170:173], v[54:57]
	v_mfma_f32_16x16x32_bf16 v[50:53], v[234:237], v[170:173], v[50:53]
	s_waitcnt lgkmcnt(2)
	v_mfma_f32_16x16x32_bf16 v[46:49], v[222:225], v[174:177], v[46:49]
	v_mfma_f32_16x16x32_bf16 v[42:45], v[226:229], v[174:177], v[42:45]
	v_mfma_f32_16x16x32_bf16 v[38:41], v[230:233], v[174:177], v[38:41]
	v_mfma_f32_16x16x32_bf16 v[34:37], v[234:237], v[174:177], v[34:37]
	s_waitcnt lgkmcnt(0)
	s_waitcnt vmcnt(0)
	s_add_u32 s16, s16, 0x80
	s_addc_u32 s17, s17, 0
	s_add_i32 s2, s2, 0x10000
	s_cmpk_eq_i32 s16, 0x780
	s_waitcnt vmcnt(0)
	s_barrier
	s_cselect_b32 s100, 1, 0
	s_and_b32 s3, s2, 0x10000
	v_or_b32_e32 v150, s3, v149
	v_add_u32_e32 v169, v150, v148
	v_or_b32_e32 v150, s3, v146
	v_add_u32_e32 v178, v150, v147
	ds_read_b128 v[150:153], v169 offset:32768
	ds_read_b128 v[154:157], v169 offset:34816
	ds_read_b128 v[158:161], v169 offset:36864
	ds_read_b128 v[162:165], v169 offset:38912
	ds_read_b128 v[170:173], v178
	ds_read_b128 v[174:177], v178 offset:2048
	s_add_u32 s4, s4, 0x80
	s_addc_u32 s5, s5, 0
	s_add_u32 s6, s6, 0x80
	s_addc_u32 s7, s7, 0
	s_cmp_eq_u32 s100, 1
	s_cbranch_scc1 .Lkl_1121_s9
	v_readfirstlane_b32 s10, v142
	s_nop 3
	s_mul_i32 s8, s10, 8
	s_mul_i32 s9, s10, 0
	s_add_i32 s9, s9, 0x8000
	s_cmp_ge_u32 s10, 0x1000
	s_cselect_b32 s10, s9, s8
	s_xor_b32 s8, s3, 0x10000
	s_add_i32 s10, s10, s8
	s_add_i32 m0, s10, 0x1000
	s_add_u32 s8, s4, 0x1000
	s_addc_u32 s9, s5, 0x0
	global_load_lds_dwordx4 v238, s[8:9] offset:-4096
	s_add_u32 s8, s4, 0xc40
	s_addc_u32 s9, s5, 0x0
	global_load_lds_dwordx4 v238, s[8:9] offset:-3072
.Lkl_1121_s9:
	v_mfma_f32_16x16x32_bf16 v[30:33], v[222:225], v[214:217], v[30:33]
	v_mfma_f32_16x16x32_bf16 v[26:29], v[226:229], v[214:217], v[26:29]
	v_mfma_f32_16x16x32_bf16 v[22:25], v[230:233], v[214:217], v[22:25]
	v_mfma_f32_16x16x32_bf16 v[18:21], v[234:237], v[214:217], v[18:21]
	ds_read_b128 v[214:217], v178 offset:4096
	s_cmp_eq_u32 s100, 1
	s_cbranch_scc1 .Lkl_1121_s10
	s_add_u32 s8, s4, 0x8800
	s_addc_u32 s9, s5, 0x0
	global_load_lds_dwordx4 v238, s[8:9] offset:-2048
	s_add_u32 s8, s4, 0x8440
	s_addc_u32 s9, s5, 0x0
	global_load_lds_dwordx4 v238, s[8:9] offset:-1024
.Lkl_1121_s10:
	v_mfma_f32_16x16x32_bf16 v[14:17], v[222:225], v[218:221], v[14:17]
	v_mfma_f32_16x16x32_bf16 v[10:13], v[226:229], v[218:221], v[10:13]
	v_mfma_f32_16x16x32_bf16 v[6:9], v[230:233], v[218:221], v[6:9]
	v_mfma_f32_16x16x32_bf16 v[2:5], v[234:237], v[218:221], v[2:5]
	ds_read_b128 v[218:221], v178 offset:6144
	s_cmp_eq_u32 s100, 1
	s_cbranch_scc1 .Lkl_1121_s11
	s_add_u32 s8, s4, 0x10000
	s_addc_u32 s9, s5, 0x0
	global_load_lds_dwordx4 v238, s[8:9] offset:0
	s_add_u32 s8, s4, 0xfc40
	s_addc_u32 s9, s5, 0x0
	global_load_lds_dwordx4 v238, s[8:9] offset:1024

; #define WAIT_V0() asm volatile("s_waitcnt vmcnt(0)" ::: "memory")
; #define SBAR() __builtin_amdgcn_sched_barrier(0)
; template <int EPI>
; DEVI void gemm_tile(const u16* __restrict__ Ab, long lda, const u16* __restrict__ Bb, long ldb, int K, const EpiArgs& e,
;                     bool have0 = false, const u16* __restrict__ nA = nullptr, const u16* __restrict__ nB = nullptr) {
;     ...
;   for (int t = 0; t < nt; ++t) {
;     const int cur = t & 1;
;     if (t + 1 < nt) GLDS_STAGE(cur ^ 1, t + 1);
;     else if (nA) {
; #pragma unroll
;       for (int i = 0; i < GL; ++i) {
;         __builtin_amdgcn_global_load_lds((const unsigned*)(nA + (long)i * 64 * lda + toffA), (unsigned*)(g_shm + wid * 1024 + i * 8192), 16, 0, 0);
;         __builtin_amdgcn_global_load_lds((const unsigned*)(nB + (long)i * 64 * ldb + toffB), (unsigned*)(g_shm + TILE_B + wid * 1024 + i * 8192), 16, 0, 0);
;       }
;     }
;     const char* sb = g_shm + cur * STAGE_B;
; #pragma unroll
;     for (int ks = 0; ks < 2; ++ks) {
;       bf16x8 Bf[4];
; #pragma unroll
;       for (int n = 0; n < 4; ++n) Bf[n] = *(const bf16x8*)(sb + b_base + n * 2048 + ks * 1024);
; #pragma unroll
;       for (int mh = 0; mh < 2; ++mh) {
;         bf16x8 At[4];
; #pragma unroll
;         for (int m = 0; m < 4; ++m) At[m] = *(const bf16x8*)(sb + a_base + (mh * 4 + m) * 2048 + ks * 1024);
;         __builtin_amdgcn_s_setprio(1);
; #pragma unroll
;         for (int m = 0; m < 4; ++m)
; #pragma unroll
;           for (int n = 0; n < 4; ++n) acc[mh * 4 + m][n] = __builtin_amdgcn_mfma_f32_16x16x32_bf16(Bf[n], At[m], acc[mh * 4 + m][n], 0, 0, 0);
;         __builtin_amdgcn_s_setprio(0);
;       }
;       SBAR();
;     }
;     if (t + 1 < nt) { WAIT_V0(); __syncthreads(); }
;   }
.Lkl_1121_y:
	s_waitcnt lgkmcnt(3)
	v_mfma_f32_16x16x32_bf16 v[126:129], v[150:153], v[170:173], v[126:129]
	v_mfma_f32_16x16x32_bf16 v[122:125], v[154:157], v[170:173], v[122:125]
	v_mfma_f32_16x16x32_bf16 v[118:121], v[158:161], v[170:173], v[118:121]
	v_mfma_f32_16x16x32_bf16 v[114:117], v[162:165], v[170:173], v[114:117]
	ds_read_b128 v[170:173], v178 offset:8192
	ds_read_b128 v[222:225], v169 offset:33792
	s_waitcnt lgkmcnt(4)
	v_mfma_f32_16x16x32_bf16 v[110:113], v[150:153], v[174:177], v[110:113]
	v_mfma_f32_16x16x32_bf16 v[106:109], v[154:157], v[174:177], v[106:109]
	v_mfma_f32_16x16x32_bf16 v[102:105], v[158:161], v[174:177], v[102:105]
	v_mfma_f32_16x16x32_bf16 v[98:101], v[162:165], v[174:177], v[98:101]
	ds_read_b128 v[174:177], v178 offset:10240
	ds_read_b128 v[226:229], v169 offset:35840
	s_waitcnt lgkmcnt(5)
	v_mfma_f32_16x16x32_bf16 v[94:97], v[150:153], v[214:217], v[94:97]
	v_mfma_f32_16x16x32_bf16 v[90:93], v[154:157], v[214:217], v[90:93]
	v_mfma_f32_16x16x32_bf16 v[86:89], v[158:161], v[214:217], v[86:89]
	v_mfma_f32_16x16x32_bf16 v[82:85], v[162:165], v[214:217], v[82:85]
	ds_read_b128 v[214:217], v178 offset:12288
	ds_read_b128 v[230:233], v169 offset:37888
	s_waitcnt lgkmcnt(6)
	v_mfma_f32_16x16x32_bf16 v[78:81], v[150:153], v[218:221], v[78:81]
	v_mfma_f32_16x16x32_bf16 v[74:77], v[154:157], v[218:221], v[74:77]
	v_mfma_f32_16x16x32_bf16 v[70:73], v[158:161], v[218:221], v[70:73]
	v_mfma_f32_16x16x32_bf16 v[66:69], v[162:165], v[218:221], v[66:69]
	ds_read_b128 v[218:221], v178 offset:14336
	ds_read_b128 v[234:237], v169 offset:39936
	s_waitcnt lgkmcnt(7)
	v_mfma_f32_16x16x32_bf16 v[62:65], v[150:153], v[170:173], v[62:65]
	v_mfma_f32_16x16x32_bf16 v[58:61], v[154:157], v[170:173], v[58:61]
	v_mfma_f32_16x16x32_bf16 v[54:57], v[158:161], v[170:173], v[54:57]
	v_mfma_f32_16x16x32_bf16 v[50:53], v[162:165], v[170:173], v[50:53]
	ds_read_b128 v[170:173], v178 offset:1024
	s_waitcnt lgkmcnt(6)
	v_mfma_f32_16x16x32_bf16 v[46:49], v[150:153], v[174:177], v[46:49]
	v_mfma_f32_16x16x32_bf16 v[42:45], v[154:157], v[174:177], v[42:45]
	v_mfma_f32_16x16x32_bf16 v[38:41], v[158:161], v[174:177], v[38:41]
	v_mfma_f32_16x16x32_bf16 v[34:37], v[162:165], v[174:177], v[34:37]
	ds_read_b128 v[174:177], v178 offset:3072
	s_waitcnt lgkmcnt(5)
	v_mfma_f32_16x16x32_bf16 v[30:33], v[150:153], v[214:217], v[30:33]
	v_mfma_f32_16x16x32_bf16 v[26:29], v[154:157], v[214:217], v[26:29]
	v_mfma_f32_16x16x32_bf16 v[22:25], v[158:161], v[214:217], v[22:25]
	v_mfma_f32_16x16x32_bf16 v[18:21], v[162:165], v[214:217], v[18:21]
	ds_read_b128 v[214:217], v178 offset:5120
	s_waitcnt lgkmcnt(4)
	v_mfma_f32_16x16x32_bf16 v[14:17], v[150:153], v[218:221], v[14:17]
	v_mfma_f32_16x16x32_bf16 v[10:13], v[154:157], v[218:221], v[10:13]
	v_mfma_f32_16x16x32_bf16 v[6:9], v[158:161], v[218:221], v[6:9]
	v_mfma_f32_16x16x32_bf16 v[2:5], v[162:165], v[218:221], v[2:5]
	ds_read_b128 v[218:221], v178 offset:7168
	s_waitcnt lgkmcnt(3)
	v_mfma_f32_16x16x32_bf16 v[126:129], v[222:225], v[170:173], v[126:129]
	v_mfma_f32_16x16x32_bf16 v[122:125], v[226:229], v[170:173], v[122:125]
	v_mfma_f32_16x16x32_bf16 v[118:121], v[230:233], v[170:173], v[118:121]
	v_mfma_f32_16x16x32_bf16 v[114:117], v[234:237], v[170:173], v[114:117]
	ds_read_b128 v[170:173], v178 offset:9216
	s_waitcnt lgkmcnt(3)
	v_mfma_f32_16x16x32_bf16 v[110:113], v[222:225], v[174:177], v[110:113]
	v_mfma_f32_16x16x32_bf16 v[106:109], v[226:229], v[174:177], v[106:109]
	v_mfma_f32_16x16x32_bf16 v[102:105], v[230:233], v[174:177], v[102:105]
	v_mfma_f32_16x16x32_bf16 v[98:101], v[234:237], v[174:177], v[98:101]
	ds_read_b128 v[174:177], v178 offset:11264
	s_waitcnt lgkmcnt(3)
	v_mfma_f32_16x16x32_bf16 v[94:97], v[222:225], v[214:217], v[94:97]
	v_mfma_f32_16x16x32_bf16 v[90:93], v[226:229], v[214:217], v[90:93]
	v_mfma_f32_16x16x32_bf16 v[86:89], v[230:233], v[214:217], v[86:89]
	v_mfma_f32_16x16x32_bf16 v[82:85], v[234:237], v[214:217], v[82:85]
	ds_read_b128 v[214:217], v178 offset:13312
	s_waitcnt lgkmcnt(3)
	v_mfma_f32_16x16x32_bf16 v[78:81], v[222:225], v[218:221], v[78:81]
	v_mfma_f32_16x16x32_bf16 v[74:77], v[226:229], v[218:221], v[74:77]
	v_mfma_f32_16x16x32_bf16 v[70:73], v[230:233], v[218:221], v[70:73]
	v_mfma_f32_16x16x32_bf16 v[66:69], v[234:237], v[218:221], v[66:69]
	ds_read_b128 v[218:221], v178 offset:15360
	s_waitcnt lgkmcnt(3)
	v_mfma_f32_16x16x32_bf16 v[62:65], v[222:225], v[170:173], v[62:65]
	v_mfma_f32_16x16x32_bf16 v[58:61], v[226:229], v[170:173], v[58:61]
	v_mfma_f32_16x16x32_bf16 v[54:57], v[230:233], v[170:173], v[54:57]
	v_mfma_f32_16x16x32_bf16 v[50:53], v[234:237], v[170:173], v[50:53]
	s_waitcnt lgkmcnt(2)
	v_mfma_f32_16x16x32_bf16 v[46:49], v[222:225], v[174:177], v[46:49]
	v_mfma_f32_16x16x32_bf16 v[42:45], v[226:229], v[174:177], v[42:45]
	v_mfma_f32_16x16x32_bf16 v[38:41], v[230:233], v[174:177], v[38:41]
	v_mfma_f32_16x16x32_bf16 v[34:37], v[234:237], v[174:177], v[34:37]
	s_waitcnt lgkmcnt(0)
	s_waitcnt vmcnt(0)
	s_add_u32 s16, s16, 0x80
	s_addc_u32 s17, s17, 0
	s_add_i32 s2, s2, 0x10000
	s_cmpk_eq_i32 s16, 0x780
	s_waitcnt vmcnt(0)
	s_barrier
	s_cselect_b32 s100, 1, 0
	s_and_b32 s3, s2, 0x10000
	v_or_b32_e32 v150, s3, v149
	v_add_u32_e32 v169, v150, v148
	v_or_b32_e32 v150, s3, v146
	v_add_u32_e32 v178, v150, v147
	ds_read_b128 v[150:153], v169 offset:32768
	ds_read_b128 v[154:157], v169 offset:34816
	ds_read_b128 v[158:161], v169 offset:36864
	ds_read_b128 v[162:165], v169 offset:38912
	ds_read_b128 v[170:173], v178
	ds_read_b128 v[174:177], v178 offset:2048
	s_add_u32 s4, s4, 0x80
	s_addc_u32 s5, s5, 0
	s_add_u32 s6, s6, 0x80
	s_addc_u32 s7, s7, 0
	v_mfma_f32_16x16x32_bf16 v[30:33], v[222:225], v[214:217], v[30:33]
	v_mfma_f32_16x16x32_bf16 v[26:29], v[226:229], v[214:217], v[26:29]
	v_mfma_f32_16x16x32_bf16 v[22:25], v[230:233], v[214:217], v[22:25]
	v_mfma_f32_16x16x32_bf16 v[18:21], v[234:237], v[214:217], v[18:21]
	ds_read_b128 v[214:217], v178 offset:4096
	v_mfma_f32_16x16x32_bf16 v[14:17], v[222:225], v[218:221], v[14:17]
	v_mfma_f32_16x16x32_bf16 v[10:13], v[226:229], v[218:221], v[10:13]
	v_mfma_f32_16x16x32_bf16 v[6:9], v[230:233], v[218:221], v[6:9]
	v_mfma_f32_16x16x32_bf16 v[2:5], v[234:237], v[218:221], v[2:5]
	ds_read_b128 v[218:221], v178 offset:6144
	s_cmp_eq_u32 s100, 1
	s_cbranch_scc0 .Lkl_1121_y

; #define WAIT_V0() asm volatile("s_waitcnt vmcnt(0)" ::: "memory")
; #define SBAR() __builtin_amdgcn_sched_barrier(0)
; template <int EPI>
; DEVI void gemm_tile(const u16* __restrict__ Ab, long lda, const u16* __restrict__ Bb, long ldb, int K, const EpiArgs& e,
;                     bool have0 = false, const u16* __restrict__ nA = nullptr, const u16* __restrict__ nB = nullptr) {
;     ...
;   f32x4 acc[8][4];
; #pragma unroll
;   for (int m = 0; m < 8; ++m)
; #pragma unroll
;     for (int n = 0; n < 4; ++n) acc[m][n] = f32x4{0.f, 0.f, 0.f, 0.f};
;   const int nt = K / BK;
;   if (!have0) GLDS_STAGE(0, 0);
;   WAIT_V0(); __syncthreads();
;   for (int t = 0; t < nt; ++t) {
;     const int cur = t & 1;
;     if (t + 1 < nt) GLDS_STAGE(cur ^ 1, t + 1);
;     else if (nA) {
; #pragma unroll
;       for (int i = 0; i < GL; ++i) {
;         __builtin_amdgcn_global_load_lds((const unsigned*)(nA + (long)i * 64 * lda + toffA), (unsigned*)(g_shm + wid * 1024 + i * 8192), 16, 0, 0);
;         __builtin_amdgcn_global_load_lds((const unsigned*)(nB + (long)i * 64 * ldb + toffB), (unsigned*)(g_shm + TILE_B + wid * 1024 + i * 8192), 16, 0, 0);
;       }
;     }
;     const char* sb = g_shm + cur * STAGE_B;
; #pragma unroll
;     for (int ks = 0; ks < 2; ++ks) {
;       bf16x8 Bf[4];
; #pragma unroll
;       for (int n = 0; n < 4; ++n) Bf[n] = *(const bf16x8*)(sb + b_base + n * 2048 + ks * 1024);
; #pragma unroll
;       for (int mh = 0; mh < 2; ++mh) {
;         bf16x8 At[4];
; #pragma unroll
;         for (int m = 0; m < 4; ++m) At[m] = *(const bf16x8*)(sb + a_base + (mh * 4 + m) * 2048 + ks * 1024);
;         __builtin_amdgcn_s_setprio(1);
; #pragma unroll
;         for (int m = 0; m < 4; ++m)
; #pragma unroll
;           for (int n = 0; n < 4; ++n) acc[mh * 4 + m][n] = __builtin_amdgcn_mfma_f32_16x16x32_bf16(Bf[n], At[m], acc[mh * 4 + m][n], 0, 0, 0);
;         __builtin_amdgcn_s_setprio(0);
;       }
;       SBAR();
;     }
;     if (t + 1 < nt) { WAIT_V0(); __syncthreads(); }
;   }
.Lkl_1370_s5:
	s_waitcnt lgkmcnt(5)
	v_mfma_f32_16x16x32_bf16 v[94:97], v[150:153], v[192:195], v[94:97]
	v_mfma_f32_16x16x32_bf16 v[90:93], v[154:157], v[192:195], v[90:93]
	v_mfma_f32_16x16x32_bf16 v[86:89], v[158:161], v[192:195], v[86:89]
	v_mfma_f32_16x16x32_bf16 v[82:85], v[162:165], v[192:195], v[82:85]
	ds_read_b128 v[192:195], v149 offset:12288
	ds_read_b128 v[230:233], v169 offset:37888
	s_add_u32 s8, s6, 0x8800
	s_addc_u32 s9, s7, 0x0
	global_load_lds_dwordx4 v239, s[8:9] offset:-2048
	s_add_u32 s8, s6, 0x8440
	s_addc_u32 s9, s7, 0x0
	global_load_lds_dwordx4 v239, s[8:9] offset:-1024
.Lkl_1370_s6:
	s_waitcnt lgkmcnt(6)
	v_mfma_f32_16x16x32_bf16 v[78:81], v[150:153], v[198:201], v[78:81]
	v_mfma_f32_16x16x32_bf16 v[74:77], v[154:157], v[198:201], v[74:77]
	v_mfma_f32_16x16x32_bf16 v[70:73], v[158:161], v[198:201], v[70:73]
	v_mfma_f32_16x16x32_bf16 v[66:69], v[162:165], v[198:201], v[66:69]
	ds_read_b128 v[198:201], v149 offset:14336
	ds_read_b128 v[234:237], v169 offset:39936
	s_add_u32 s8, s6, 0x10000
	s_addc_u32 s9, s7, 0x0
	global_load_lds_dwordx4 v239, s[8:9] offset:0
	s_add_u32 s8, s6, 0xfc40
	s_addc_u32 s9, s7, 0x0
	global_load_lds_dwordx4 v239, s[8:9] offset:1024

; #define WAIT_V0() asm volatile("s_waitcnt vmcnt(0)" ::: "memory")
; #define SBAR() __builtin_amdgcn_sched_barrier(0)
; template <int EPI>
; DEVI void gemm_tile(const u16* __restrict__ Ab, long lda, const u16* __restrict__ Bb, long ldb, int K, const EpiArgs& e,
;                     bool have0 = false, const u16* __restrict__ nA = nullptr, const u16* __restrict__ nB = nullptr) {
;     ...
;   f32x4 acc[8][4];
; #pragma unroll
;   for (int m = 0; m < 8; ++m)
; #pragma unroll
;     for (int n = 0; n < 4; ++n) acc[m][n] = f32x4{0.f, 0.f, 0.f, 0.f};
;   const int nt = K / BK;
;   if (!have0) GLDS_STAGE(0, 0);
;   WAIT_V0(); __syncthreads();
;   for (int t = 0; t < nt; ++t) {
;     const int cur = t & 1;
;     if (t + 1 < nt) GLDS_STAGE(cur ^ 1, t + 1);
;     else if (nA) {
; #pragma unroll
;       for (int i = 0; i < GL; ++i) {
;         __builtin_amdgcn_global_load_lds((const unsigned*)(nA + (long)i * 64 * lda + toffA), (unsigned*)(g_shm + wid * 1024 + i * 8192), 16, 0, 0);
;         __builtin_amdgcn_global_load_lds((const unsigned*)(nB + (long)i * 64 * ldb + toffB), (unsigned*)(g_shm + TILE_B + wid * 1024 + i * 8192), 16, 0, 0);
;       }
;     }
;     const char* sb = g_shm + cur * STAGE_B;
; #pragma unroll
;     for (int ks = 0; ks < 2; ++ks) {
;       bf16x8 Bf[4];
; #pragma unroll
;       for (int n = 0; n < 4; ++n) Bf[n] = *(const bf16x8*)(sb + b_base + n * 2048 + ks * 1024);
; #pragma unroll
;       for (int mh = 0; mh < 2; ++mh) {
;         bf16x8 At[4];
; #pragma unroll
;         for (int m = 0; m < 4; ++m) At[m] = *(const bf16x8*)(sb + a_base + (mh * 4 + m) * 2048 + ks * 1024);
;         __builtin_amdgcn_s_setprio(1);
; #pragma unroll
;         for (int m = 0; m < 4; ++m)
; #pragma unroll
;           for (int n = 0; n < 4; ++n) acc[mh * 4 + m][n] = __builtin_amdgcn_mfma_f32_16x16x32_bf16(Bf[n], At[m], acc[mh * 4 + m][n], 0, 0, 0);
;         __builtin_amdgcn_s_setprio(0);
;       }
;       SBAR();
;     }
;     if (t + 1 < nt) { WAIT_V0(); __syncthreads(); }
;   }
.Lkl_1370_s8:
	s_waitcnt lgkmcnt(6)
	v_mfma_f32_16x16x32_bf16 v[46:49], v[150:153], v[174:177], v[46:49]
	v_mfma_f32_16x16x32_bf16 v[42:45], v[154:157], v[174:177], v[42:45]
	v_mfma_f32_16x16x32_bf16 v[38:41], v[158:161], v[174:177], v[38:41]
	v_mfma_f32_16x16x32_bf16 v[34:37], v[162:165], v[174:177], v[34:37]
	ds_read_b128 v[174:177], v149 offset:3072
	s_waitcnt lgkmcnt(5)
	v_mfma_f32_16x16x32_bf16 v[30:33], v[150:153], v[192:195], v[30:33]
	v_mfma_f32_16x16x32_bf16 v[26:29], v[154:157], v[192:195], v[26:29]
	v_mfma_f32_16x16x32_bf16 v[22:25], v[158:161], v[192:195], v[22:25]
	v_mfma_f32_16x16x32_bf16 v[18:21], v[162:165], v[192:195], v[18:21]
	ds_read_b128 v[192:195], v149 offset:5120
	s_waitcnt lgkmcnt(4)
	v_mfma_f32_16x16x32_bf16 v[14:17], v[150:153], v[198:201], v[14:17]
	v_mfma_f32_16x16x32_bf16 v[10:13], v[154:157], v[198:201], v[10:13]
	v_mfma_f32_16x16x32_bf16 v[6:9], v[158:161], v[198:201], v[6:9]
	v_mfma_f32_16x16x32_bf16 v[2:5], v[162:165], v[198:201], v[2:5]
	ds_read_b128 v[198:201], v149 offset:7168
	s_waitcnt lgkmcnt(3)
	v_mfma_f32_16x16x32_bf16 v[126:129], v[222:225], v[170:173], v[126:129]
	v_mfma_f32_16x16x32_bf16 v[122:125], v[226:229], v[170:173], v[122:125]
	v_mfma_f32_16x16x32_bf16 v[118:121], v[230:233], v[170:173], v[118:121]
	v_mfma_f32_16x16x32_bf16 v[114:117], v[234:237], v[170:173], v[114:117]
	ds_read_b128 v[170:173], v149 offset:9216
	s_waitcnt lgkmcnt(3)
	v_mfma_f32_16x16x32_bf16 v[110:113], v[222:225], v[174:177], v[110:113]
	v_mfma_f32_16x16x32_bf16 v[106:109], v[226:229], v[174:177], v[106:109]
	v_mfma_f32_16x16x32_bf16 v[102:105], v[230:233], v[174:177], v[102:105]
	v_mfma_f32_16x16x32_bf16 v[98:101], v[234:237], v[174:177], v[98:101]
	ds_read_b128 v[174:177], v149 offset:11264
	s_waitcnt lgkmcnt(3)
	v_mfma_f32_16x16x32_bf16 v[94:97], v[222:225], v[192:195], v[94:97]
	v_mfma_f32_16x16x32_bf16 v[90:93], v[226:229], v[192:195], v[90:93]
	v_mfma_f32_16x16x32_bf16 v[86:89], v[230:233], v[192:195], v[86:89]
	v_mfma_f32_16x16x32_bf16 v[82:85], v[234:237], v[192:195], v[82:85]
	ds_read_b128 v[192:195], v149 offset:13312
	s_waitcnt lgkmcnt(3)
	v_mfma_f32_16x16x32_bf16 v[78:81], v[222:225], v[198:201], v[78:81]
	v_mfma_f32_16x16x32_bf16 v[74:77], v[226:229], v[198:201], v[74:77]
	v_mfma_f32_16x16x32_bf16 v[70:73], v[230:233], v[198:201], v[70:73]
	v_mfma_f32_16x16x32_bf16 v[66:69], v[234:237], v[198:201], v[66:69]
	ds_read_b128 v[198:201], v149 offset:15360
	s_waitcnt lgkmcnt(3)
	v_mfma_f32_16x16x32_bf16 v[62:65], v[222:225], v[170:173], v[62:65]
	v_mfma_f32_16x16x32_bf16 v[58:61], v[226:229], v[170:173], v[58:61]
	v_mfma_f32_16x16x32_bf16 v[54:57], v[230:233], v[170:173], v[54:57]
	v_mfma_f32_16x16x32_bf16 v[50:53], v[234:237], v[170:173], v[50:53]
	s_waitcnt lgkmcnt(2)
	v_mfma_f32_16x16x32_bf16 v[46:49], v[222:225], v[174:177], v[46:49]
	v_mfma_f32_16x16x32_bf16 v[42:45], v[226:229], v[174:177], v[42:45]
	v_mfma_f32_16x16x32_bf16 v[38:41], v[230:233], v[174:177], v[38:41]
	v_mfma_f32_16x16x32_bf16 v[34:37], v[234:237], v[174:177], v[34:37]
	s_waitcnt lgkmcnt(0)
	s_add_i32 s2, s2, 0x10000
	s_waitcnt vmcnt(0)
	s_add_u32 s18, s18, 0x80
	s_addc_u32 s19, s19, 0
	s_cmpk_eq_i32 s18, 0x780
	s_waitcnt vmcnt(0)
	s_barrier
	s_cselect_b32 s100, 1, 0
	s_and_b32 s3, s2, 0x10000
	v_or_b32_e32 v149, s3, v147
	v_add_u32_e32 v169, v149, v148
	v_add_u32_e32 v149, v149, v146
	ds_read_b128 v[150:153], v169 offset:32768
	ds_read_b128 v[154:157], v169 offset:34816
	ds_read_b128 v[158:161], v169 offset:36864
	ds_read_b128 v[162:165], v169 offset:38912
	ds_read_b128 v[170:173], v149
	ds_read_b128 v[174:177], v149 offset:2048
	s_add_u32 s4, s4, 0x80
	s_addc_u32 s5, s5, 0
	s_add_u32 s6, s6, 0x80
	s_addc_u32 s7, s7, 0
	s_cmp_eq_u32 s100, 1
	s_cbranch_scc1 .Lkl_1370_s9
	v_readfirstlane_b32 s10, v140
	s_nop 3
	s_mul_i32 s8, s10, 8
	s_mul_i32 s9, s10, 0
	s_add_i32 s9, s9, 0x8000
	s_cmp_ge_u32 s10, 0x1000
	s_cselect_b32 s10, s9, s8
	s_xor_b32 s8, s3, 0x10000
	s_add_i32 s10, s10, s8
	s_add_i32 m0, s10, 0x1000
	s_add_u32 s8, s4, 0x1000
	s_addc_u32 s9, s5, 0x0
	global_load_lds_dwordx4 v238, s[8:9] offset:-4096
	s_add_u32 s8, s4, 0xc40
	s_addc_u32 s9, s5, 0x0
	global_load_lds_dwordx4 v238, s[8:9] offset:-3072
.Lkl_1370_s9:
	v_mfma_f32_16x16x32_bf16 v[30:33], v[222:225], v[192:195], v[30:33]
	v_mfma_f32_16x16x32_bf16 v[26:29], v[226:229], v[192:195], v[26:29]
	v_mfma_f32_16x16x32_bf16 v[22:25], v[230:233], v[192:195], v[22:25]
	v_mfma_f32_16x16x32_bf16 v[18:21], v[234:237], v[192:195], v[18:21]
	ds_read_b128 v[192:195], v149 offset:4096
	s_cmp_eq_u32 s100, 1
	s_cbranch_scc1 .Lkl_1370_s10
	s_add_u32 s8, s4, 0x8800
	s_addc_u32 s9, s5, 0x0
	global_load_lds_dwordx4 v238, s[8:9] offset:-2048
	s_add_u32 s8, s4, 0x8440
	s_addc_u32 s9, s5, 0x0
	global_load_lds_dwordx4 v238, s[8:9] offset:-1024
.Lkl_1370_s10:
	v_mfma_f32_16x16x32_bf16 v[14:17], v[222:225], v[198:201], v[14:17]
	v_mfma_f32_16x16x32_bf16 v[10:13], v[226:229], v[198:201], v[10:13]
	v_mfma_f32_16x16x32_bf16 v[6:9], v[230:233], v[198:201], v[6:9]
	v_mfma_f32_16x16x32_bf16 v[2:5], v[234:237], v[198:201], v[2:5]
	ds_read_b128 v[198:201], v149 offset:6144
	s_cmp_eq_u32 s100, 1
	s_cbranch_scc1 .Lkl_1370_s11
	s_add_u32 s8, s4, 0x10000
	s_addc_u32 s9, s5, 0x0
	global_load_lds_dwordx4 v238, s[8:9] offset:0
	s_add_u32 s8, s4, 0xfc40
	s_addc_u32 s9, s5, 0x0
	global_load_lds_dwordx4 v238, s[8:9] offset:1024

; #define WAIT_V0() asm volatile("s_waitcnt vmcnt(0)" ::: "memory")
; #define SBAR() __builtin_amdgcn_sched_barrier(0)
; template <int EPI>
; DEVI void gemm_tile(const u16* __restrict__ Ab, long lda, const u16* __restrict__ Bb, long ldb, int K, const EpiArgs& e,
;                     bool have0 = false, const u16* __restrict__ nA = nullptr, const u16* __restrict__ nB = nullptr) {
;     ...
;   for (int t = 0; t < nt; ++t) {
;     const int cur = t & 1;
;     if (t + 1 < nt) GLDS_STAGE(cur ^ 1, t + 1);
;     else if (nA) {
; #pragma unroll
;       for (int i = 0; i < GL; ++i) {
;         __builtin_amdgcn_global_load_lds((const unsigned*)(nA + (long)i * 64 * lda + toffA), (unsigned*)(g_shm + wid * 1024 + i * 8192), 16, 0, 0);
;         __builtin_amdgcn_global_load_lds((const unsigned*)(nB + (long)i * 64 * ldb + toffB), (unsigned*)(g_shm + TILE_B + wid * 1024 + i * 8192), 16, 0, 0);
;       }
;     }
;     const char* sb = g_shm + cur * STAGE_B;
; #pragma unroll
;     for (int ks = 0; ks < 2; ++ks) {
;       bf16x8 Bf[4];
; #pragma unroll
;       for (int n = 0; n < 4; ++n) Bf[n] = *(const bf16x8*)(sb + b_base + n * 2048 + ks * 1024);
; #pragma unroll
;       for (int mh = 0; mh < 2; ++mh) {
;         bf16x8 At[4];
; #pragma unroll
;         for (int m = 0; m < 4; ++m) At[m] = *(const bf16x8*)(sb + a_base + (mh * 4 + m) * 2048 + ks * 1024);
;         __builtin_amdgcn_s_setprio(1);
; #pragma unroll
;         for (int m = 0; m < 4; ++m)
; #pragma unroll
;           for (int n = 0; n < 4; ++n) acc[mh * 4 + m][n] = __builtin_amdgcn_mfma_f32_16x16x32_bf16(Bf[n], At[m], acc[mh * 4 + m][n], 0, 0, 0);
;         __builtin_amdgcn_s_setprio(0);
;       }
;       SBAR();
;     }
;     if (t + 1 < nt) { WAIT_V0(); __syncthreads(); }
;   }
.Lkl_1370_y:
	s_waitcnt lgkmcnt(3)
	v_mfma_f32_16x16x32_bf16 v[126:129], v[150:153], v[170:173], v[126:129]
	v_mfma_f32_16x16x32_bf16 v[122:125], v[154:157], v[170:173], v[122:125]
	v_mfma_f32_16x16x32_bf16 v[118:121], v[158:161], v[170:173], v[118:121]
	v_mfma_f32_16x16x32_bf16 v[114:117], v[162:165], v[170:173], v[114:117]
	ds_read_b128 v[170:173], v149 offset:8192
	ds_read_b128 v[222:225], v169 offset:33792
	s_waitcnt lgkmcnt(4)
	v_mfma_f32_16x16x32_bf16 v[110:113], v[150:153], v[174:177], v[110:113]
	v_mfma_f32_16x16x32_bf16 v[106:109], v[154:157], v[174:177], v[106:109]
	v_mfma_f32_16x16x32_bf16 v[102:105], v[158:161], v[174:177], v[102:105]
	v_mfma_f32_16x16x32_bf16 v[98:101], v[162:165], v[174:177], v[98:101]
	ds_read_b128 v[174:177], v149 offset:10240
	ds_read_b128 v[226:229], v169 offset:35840
	s_waitcnt lgkmcnt(5)
	v_mfma_f32_16x16x32_bf16 v[94:97], v[150:153], v[192:195], v[94:97]
	v_mfma_f32_16x16x32_bf16 v[90:93], v[154:157], v[192:195], v[90:93]
	v_mfma_f32_16x16x32_bf16 v[86:89], v[158:161], v[192:195], v[86:89]
	v_mfma_f32_16x16x32_bf16 v[82:85], v[162:165], v[192:195], v[82:85]
	ds_read_b128 v[192:195], v149 offset:12288
	ds_read_b128 v[230:233], v169 offset:37888
	s_waitcnt lgkmcnt(6)
	v_mfma_f32_16x16x32_bf16 v[78:81], v[150:153], v[198:201], v[78:81]
	v_mfma_f32_16x16x32_bf16 v[74:77], v[154:157], v[198:201], v[74:77]
	v_mfma_f32_16x16x32_bf16 v[70:73], v[158:161], v[198:201], v[70:73]
	v_mfma_f32_16x16x32_bf16 v[66:69], v[162:165], v[198:201], v[66:69]
	ds_read_b128 v[198:201], v149 offset:14336
	ds_read_b128 v[234:237], v169 offset:39936
	s_waitcnt lgkmcnt(7)
	v_mfma_f32_16x16x32_bf16 v[62:65], v[150:153], v[170:173], v[62:65]
	v_mfma_f32_16x16x32_bf16 v[58:61], v[154:157], v[170:173], v[58:61]
	v_mfma_f32_16x16x32_bf16 v[54:57], v[158:161], v[170:173], v[54:57]
	v_mfma_f32_16x16x32_bf16 v[50:53], v[162:165], v[170:173], v[50:53]
	ds_read_b128 v[170:173], v149 offset:1024
	s_waitcnt lgkmcnt(6)
	v_mfma_f32_16x16x32_bf16 v[46:49], v[150:153], v[174:177], v[46:49]
	v_mfma_f32_16x16x32_bf16 v[42:45], v[154:157], v[174:177], v[42:45]
	v_mfma_f32_16x16x32_bf16 v[38:41], v[158:161], v[174:177], v[38:41]
	v_mfma_f32_16x16x32_bf16 v[34:37], v[162:165], v[174:177], v[34:37]
	ds_read_b128 v[174:177], v149 offset:3072
	s_waitcnt lgkmcnt(5)
	v_mfma_f32_16x16x32_bf16 v[30:33], v[150:153], v[192:195], v[30:33]
	v_mfma_f32_16x16x32_bf16 v[26:29], v[154:157], v[192:195], v[26:29]
	v_mfma_f32_16x16x32_bf16 v[22:25], v[158:161], v[192:195], v[22:25]
	v_mfma_f32_16x16x32_bf16 v[18:21], v[162:165], v[192:195], v[18:21]
	ds_read_b128 v[192:195], v149 offset:5120
	s_waitcnt lgkmcnt(4)
	v_mfma_f32_16x16x32_bf16 v[14:17], v[150:153], v[198:201], v[14:17]
	v_mfma_f32_16x16x32_bf16 v[10:13], v[154:157], v[198:201], v[10:13]
	v_mfma_f32_16x16x32_bf16 v[6:9], v[158:161], v[198:201], v[6:9]
	v_mfma_f32_16x16x32_bf16 v[2:5], v[162:165], v[198:201], v[2:5]
	ds_read_b128 v[198:201], v149 offset:7168
	s_waitcnt lgkmcnt(3)
	v_mfma_f32_16x16x32_bf16 v[126:129], v[222:225], v[170:173], v[126:129]
	v_mfma_f32_16x16x32_bf16 v[122:125], v[226:229], v[170:173], v[122:125]
	v_mfma_f32_16x16x32_bf16 v[118:121], v[230:233], v[170:173], v[118:121]
	v_mfma_f32_16x16x32_bf16 v[114:117], v[234:237], v[170:173], v[114:117]
	ds_read_b128 v[170:173], v149 offset:9216
	s_waitcnt lgkmcnt(3)
	v_mfma_f32_16x16x32_bf16 v[110:113], v[222:225], v[174:177], v[110:113]
	v_mfma_f32_16x16x32_bf16 v[106:109], v[226:229], v[174:177], v[106:109]
	v_mfma_f32_16x16x32_bf16 v[102:105], v[230:233], v[174:177], v[102:105]
	v_mfma_f32_16x16x32_bf16 v[98:101], v[234:237], v[174:177], v[98:101]
	ds_read_b128 v[174:177], v149 offset:11264
	s_waitcnt lgkmcnt(3)
	v_mfma_f32_16x16x32_bf16 v[94:97], v[222:225], v[192:195], v[94:97]
	v_mfma_f32_16x16x32_bf16 v[90:93], v[226:229], v[192:195], v[90:93]
	v_mfma_f32_16x16x32_bf16 v[86:89], v[230:233], v[192:195], v[86:89]
	v_mfma_f32_16x16x32_bf16 v[82:85], v[234:237], v[192:195], v[82:85]
	ds_read_b128 v[192:195], v149 offset:13312
	s_waitcnt lgkmcnt(3)
	v_mfma_f32_16x16x32_bf16 v[78:81], v[222:225], v[198:201], v[78:81]
	v_mfma_f32_16x16x32_bf16 v[74:77], v[226:229], v[198:201], v[74:77]
	v_mfma_f32_16x16x32_bf16 v[70:73], v[230:233], v[198:201], v[70:73]
	v_mfma_f32_16x16x32_bf16 v[66:69], v[234:237], v[198:201], v[66:69]
	ds_read_b128 v[198:201], v149 offset:15360
	s_waitcnt lgkmcnt(3)
	v_mfma_f32_16x16x32_bf16 v[62:65], v[222:225], v[170:173], v[62:65]
	v_mfma_f32_16x16x32_bf16 v[58:61], v[226:229], v[170:173], v[58:61]
	v_mfma_f32_16x16x32_bf16 v[54:57], v[230:233], v[170:173], v[54:57]
	v_mfma_f32_16x16x32_bf16 v[50:53], v[234:237], v[170:173], v[50:53]
	s_waitcnt lgkmcnt(2)
	v_mfma_f32_16x16x32_bf16 v[46:49], v[222:225], v[174:177], v[46:49]
	v_mfma_f32_16x16x32_bf16 v[42:45], v[226:229], v[174:177], v[42:45]
	v_mfma_f32_16x16x32_bf16 v[38:41], v[230:233], v[174:177], v[38:41]
	v_mfma_f32_16x16x32_bf16 v[34:37], v[234:237], v[174:177], v[34:37]
	s_waitcnt lgkmcnt(0)
	s_add_i32 s2, s2, 0x10000
	s_waitcnt vmcnt(0)
	s_add_u32 s18, s18, 0x80
	s_addc_u32 s19, s19, 0
	s_cmpk_eq_i32 s18, 0x780
	s_waitcnt vmcnt(0)
	s_barrier
	s_cselect_b32 s100, 1, 0
	s_and_b32 s3, s2, 0x10000
	v_or_b32_e32 v149, s3, v147
	v_add_u32_e32 v169, v149, v148
	v_add_u32_e32 v149, v149, v146
	ds_read_b128 v[150:153], v169 offset:32768
	ds_read_b128 v[154:157], v169 offset:34816
	ds_read_b128 v[158:161], v169 offset:36864
	ds_read_b128 v[162:165], v169 offset:38912
	ds_read_b128 v[170:173], v149
	ds_read_b128 v[174:177], v149 offset:2048
	s_add_u32 s4, s4, 0x80
	s_addc_u32 s5, s5, 0
	s_add_u32 s6, s6, 0x80
	s_addc_u32 s7, s7, 0
	v_mfma_f32_16x16x32_bf16 v[30:33], v[222:225], v[192:195], v[30:33]
	v_mfma_f32_16x16x32_bf16 v[26:29], v[226:229], v[192:195], v[26:29]
	v_mfma_f32_16x16x32_bf16 v[22:25], v[230:233], v[192:195], v[22:25]
	v_mfma_f32_16x16x32_bf16 v[18:21], v[234:237], v[192:195], v[18:21]
	ds_read_b128 v[192:195], v149 offset:4096
	v_mfma_f32_16x16x32_bf16 v[14:17], v[222:225], v[198:201], v[14:17]
	v_mfma_f32_16x16x32_bf16 v[10:13], v[226:229], v[198:201], v[10:13]
	v_mfma_f32_16x16x32_bf16 v[6:9], v[230:233], v[198:201], v[6:9]
	v_mfma_f32_16x16x32_bf16 v[2:5], v[234:237], v[198:201], v[2:5]
	ds_read_b128 v[198:201], v149 offset:6144
	s_cmp_eq_u32 s100, 1
	s_cbranch_scc0 .Lkl_1370_y
; template <int EPI>
; DEVI void gemm_tile(const u16* __restrict__ Ab, long lda, const u16* __restrict__ Bb, long ldb, int K, const EpiArgs& e,
;                     bool have0 = false, const u16* __restrict__ nA = nullptr, const u16* __restrict__ nB = nullptr) {
;     ...
;     if (t + 1 < nt) GLDS_STAGE(cur ^ 1, t + 1);
;     else if (nA) {
; #pragma unroll
;       for (int i = 0; i < GL; ++i) {
;         __builtin_amdgcn_global_load_lds((const unsigned*)(nA + (long)i * 64 * lda + toffA), (unsigned*)(g_shm + wid * 1024 + i * 8192), 16, 0, 0);
;         __builtin_amdgcn_global_load_lds((const unsigned*)(nB + (long)i * 64 * ldb + toffB), (unsigned*)(g_shm + TILE_B + wid * 1024 + i * 8192), 16, 0, 0);
;       }
;     }
.Lkl_1370_x:
	s_setprio 0
	s_nop 3
	v_readlane_b32 s4, v240, 0
	v_readlane_b32 s5, v240, 1
	v_readlane_b32 s6, v240, 2
	v_readlane_b32 s7, v240, 3
	v_readlane_b32 s8, v240, 4
	v_readlane_b32 s9, v240, 5
	v_readlane_b32 s10, v240, 6
	s_waitcnt lgkmcnt(0)
	s_xor_b32 s3, s3, 0x10000
	v_or_b32_e32 v149, s3, v147
	v_add_u32_e32 v169, v149, v148
	v_add_u32_e32 v149, v149, v146
	s_cmp_eq_u32 s100, 1
	s_cmp_eq_u64 s[10:11], 0
	s_cbranch_scc1 .LBB0_1358
	v_readfirstlane_b32 s2, v140
	v_lshl_add_u64 v[132:133], s[10:11], 0, v[130:131]
	s_mov_b32 m0, s2
	v_readfirstlane_b32 s2, v145
	v_lshl_add_u64 v[130:131], s[16:17], 0, v[130:131]
	global_load_lds_dwordx4 v[132:133], off
	s_mov_b32 m0, s2
	s_mov_b64 s[16:17], 0x20000
	v_readfirstlane_b32 s2, v144
	global_load_lds_dwordx4 v[130:131], off
	v_lshl_add_u64 v[134:135], v[132:133], 0, s[16:17]
	s_mov_b32 m0, s2
	v_readfirstlane_b32 s2, v143
	global_load_lds_dwordx4 v[134:135], off
	v_lshl_add_u64 v[134:135], v[130:131], 0, s[16:17]
	s_mov_b32 m0, s2
	v_readfirstlane_b32 s2, v142
	global_load_lds_dwordx4 v[134:135], off
	v_lshl_add_u64 v[134:135], v[132:133], 0, s[96:97]
	s_mov_b32 m0, s2
	v_readfirstlane_b32 s2, v141
	global_load_lds_dwordx4 v[134:135], off
	v_lshl_add_u64 v[134:135], v[130:131], 0, s[96:97]
	s_mov_b32 m0, s2
	s_mov_b64 s[16:17], 0x60000
	v_readfirstlane_b32 s2, v139
	global_load_lds_dwordx4 v[134:135], off
	v_lshl_add_u64 v[132:133], v[132:133], 0, s[16:17]
	s_mov_b32 m0, s2
	v_readfirstlane_b32 s2, v138
	global_load_lds_dwordx4 v[132:133], off
	v_lshl_add_u64 v[130:131], v[130:131], 0, s[16:17]
	s_mov_b32 m0, s2
	s_nop 0
	global_load_lds_dwordx4 v[130:131], off
	s_branch .LBB0_1358

; #define WAIT_V0() asm volatile("s_waitcnt vmcnt(0)" ::: "memory")
; #define SBAR() __builtin_amdgcn_sched_barrier(0)
; template <int EPI>
; DEVI void gemm_tile(const u16* __restrict__ Ab, long lda, const u16* __restrict__ Bb, long ldb, int K, const EpiArgs& e,
;                     bool have0 = false, const u16* __restrict__ nA = nullptr, const u16* __restrict__ nB = nullptr) {
;     ...
;   f32x4 acc[8][4];
; #pragma unroll
;   for (int m = 0; m < 8; ++m)
; #pragma unroll
;     for (int n = 0; n < 4; ++n) acc[m][n] = f32x4{0.f, 0.f, 0.f, 0.f};
;   const int nt = K / BK;
;   if (!have0) GLDS_STAGE(0, 0);
;   WAIT_V0(); __syncthreads();
;   for (int t = 0; t < nt; ++t) {
;     const int cur = t & 1;
;     if (t + 1 < nt) GLDS_STAGE(cur ^ 1, t + 1);
;     else if (nA) {
; #pragma unroll
;       for (int i = 0; i < GL; ++i) {
;         __builtin_amdgcn_global_load_lds((const unsigned*)(nA + (long)i * 64 * lda + toffA), (unsigned*)(g_shm + wid * 1024 + i * 8192), 16, 0, 0);
;         __builtin_amdgcn_global_load_lds((const unsigned*)(nB + (long)i * 64 * ldb + toffB), (unsigned*)(g_shm + TILE_B + wid * 1024 + i * 8192), 16, 0, 0);
;       }
;     }
;     const char* sb = g_shm + cur * STAGE_B;
; #pragma unroll
;     for (int ks = 0; ks < 2; ++ks) {
;       bf16x8 Bf[4];
; #pragma unroll
;       for (int n = 0; n < 4; ++n) Bf[n] = *(const bf16x8*)(sb + b_base + n * 2048 + ks * 1024);
; #pragma unroll
;       for (int mh = 0; mh < 2; ++mh) {
;         bf16x8 At[4];
; #pragma unroll
;         for (int m = 0; m < 4; ++m) At[m] = *(const bf16x8*)(sb + a_base + (mh * 4 + m) * 2048 + ks * 1024);
;         __builtin_amdgcn_s_setprio(1);
; #pragma unroll
;         for (int m = 0; m < 4; ++m)
; #pragma unroll
;           for (int n = 0; n < 4; ++n) acc[mh * 4 + m][n] = __builtin_amdgcn_mfma_f32_16x16x32_bf16(Bf[n], At[m], acc[mh * 4 + m][n], 0, 0, 0);
;         __builtin_amdgcn_s_setprio(0);
;       }
;       SBAR();
;     }
;     if (t + 1 < nt) { WAIT_V0(); __syncthreads(); }
;   }
.Lkl_1404_s5:
	s_waitcnt lgkmcnt(5)
	v_mfma_f32_16x16x32_bf16 v[94:97], v[150:153], v[192:195], v[94:97]
	v_mfma_f32_16x16x32_bf16 v[90:93], v[154:157], v[192:195], v[90:93]
	v_mfma_f32_16x16x32_bf16 v[86:89], v[158:161], v[192:195], v[86:89]
	v_mfma_f32_16x16x32_bf16 v[82:85], v[162:165], v[192:195], v[82:85]
	ds_read_b128 v[192:195], v178 offset:12288
	ds_read_b128 v[230:233], v169 offset:37888
	s_add_u32 s8, s6, 0x16800
	s_addc_u32 s9, s7, 0x0
	global_load_lds_dwordx4 v239, s[8:9] offset:-2048
	s_add_u32 s8, s6, 0x16440
	s_addc_u32 s9, s7, 0x0
	global_load_lds_dwordx4 v239, s[8:9] offset:-1024
.Lkl_1404_s6:
	s_waitcnt lgkmcnt(6)
	v_mfma_f32_16x16x32_bf16 v[78:81], v[150:153], v[198:201], v[78:81]
	v_mfma_f32_16x16x32_bf16 v[74:77], v[154:157], v[198:201], v[74:77]
	v_mfma_f32_16x16x32_bf16 v[70:73], v[158:161], v[198:201], v[70:73]
	v_mfma_f32_16x16x32_bf16 v[66:69], v[162:165], v[198:201], v[66:69]
	ds_read_b128 v[198:201], v178 offset:14336
	ds_read_b128 v[234:237], v169 offset:39936
	s_add_u32 s8, s6, 0x2c000
	s_addc_u32 s9, s7, 0x0
	global_load_lds_dwordx4 v239, s[8:9] offset:0
	s_add_u32 s8, s6, 0x2bc40
	s_addc_u32 s9, s7, 0x0
	global_load_lds_dwordx4 v239, s[8:9] offset:1024

; #define WAIT_V0() asm volatile("s_waitcnt vmcnt(0)" ::: "memory")
; #define SBAR() __builtin_amdgcn_sched_barrier(0)
; template <int EPI>
; DEVI void gemm_tile(const u16* __restrict__ Ab, long lda, const u16* __restrict__ Bb, long ldb, int K, const EpiArgs& e,
;                     bool have0 = false, const u16* __restrict__ nA = nullptr, const u16* __restrict__ nB = nullptr) {
;     ...
;   f32x4 acc[8][4];
; #pragma unroll
;   for (int m = 0; m < 8; ++m)
; #pragma unroll
;     for (int n = 0; n < 4; ++n) acc[m][n] = f32x4{0.f, 0.f, 0.f, 0.f};
;   const int nt = K / BK;
;   if (!have0) GLDS_STAGE(0, 0);
;   WAIT_V0(); __syncthreads();
;   for (int t = 0; t < nt; ++t) {
;     const int cur = t & 1;
;     if (t + 1 < nt) GLDS_STAGE(cur ^ 1, t + 1);
;     else if (nA) {
; #pragma unroll
;       for (int i = 0; i < GL; ++i) {
;         __builtin_amdgcn_global_load_lds((const unsigned*)(nA + (long)i * 64 * lda + toffA), (unsigned*)(g_shm + wid * 1024 + i * 8192), 16, 0, 0);
;         __builtin_amdgcn_global_load_lds((const unsigned*)(nB + (long)i * 64 * ldb + toffB), (unsigned*)(g_shm + TILE_B + wid * 1024 + i * 8192), 16, 0, 0);
;       }
;     }
;     const char* sb = g_shm + cur * STAGE_B;
; #pragma unroll
;     for (int ks = 0; ks < 2; ++ks) {
;       bf16x8 Bf[4];
; #pragma unroll
;       for (int n = 0; n < 4; ++n) Bf[n] = *(const bf16x8*)(sb + b_base + n * 2048 + ks * 1024);
; #pragma unroll
;       for (int mh = 0; mh < 2; ++mh) {
;         bf16x8 At[4];
; #pragma unroll
;         for (int m = 0; m < 4; ++m) At[m] = *(const bf16x8*)(sb + a_base + (mh * 4 + m) * 2048 + ks * 1024);
;         __builtin_amdgcn_s_setprio(1);
; #pragma unroll
;         for (int m = 0; m < 4; ++m)
; #pragma unroll
;           for (int n = 0; n < 4; ++n) acc[mh * 4 + m][n] = __builtin_amdgcn_mfma_f32_16x16x32_bf16(Bf[n], At[m], acc[mh * 4 + m][n], 0, 0, 0);
;         __builtin_amdgcn_s_setprio(0);
;       }
;       SBAR();
;     }
;     if (t + 1 < nt) { WAIT_V0(); __syncthreads(); }
;   }
.Lkl_1404_s8:
	s_waitcnt lgkmcnt(6)
	v_mfma_f32_16x16x32_bf16 v[46:49], v[150:153], v[174:177], v[46:49]
	v_mfma_f32_16x16x32_bf16 v[42:45], v[154:157], v[174:177], v[42:45]
	v_mfma_f32_16x16x32_bf16 v[38:41], v[158:161], v[174:177], v[38:41]
	v_mfma_f32_16x16x32_bf16 v[34:37], v[162:165], v[174:177], v[34:37]
	ds_read_b128 v[174:177], v178 offset:3072
	s_waitcnt lgkmcnt(5)
	v_mfma_f32_16x16x32_bf16 v[30:33], v[150:153], v[192:195], v[30:33]
	v_mfma_f32_16x16x32_bf16 v[26:29], v[154:157], v[192:195], v[26:29]
	v_mfma_f32_16x16x32_bf16 v[22:25], v[158:161], v[192:195], v[22:25]
	v_mfma_f32_16x16x32_bf16 v[18:21], v[162:165], v[192:195], v[18:21]
	ds_read_b128 v[192:195], v178 offset:5120
	s_waitcnt lgkmcnt(4)
	v_mfma_f32_16x16x32_bf16 v[14:17], v[150:153], v[198:201], v[14:17]
	v_mfma_f32_16x16x32_bf16 v[10:13], v[154:157], v[198:201], v[10:13]
	v_mfma_f32_16x16x32_bf16 v[6:9], v[158:161], v[198:201], v[6:9]
	v_mfma_f32_16x16x32_bf16 v[2:5], v[162:165], v[198:201], v[2:5]
	ds_read_b128 v[198:201], v178 offset:7168
	s_waitcnt lgkmcnt(3)
	v_mfma_f32_16x16x32_bf16 v[126:129], v[222:225], v[170:173], v[126:129]
	v_mfma_f32_16x16x32_bf16 v[122:125], v[226:229], v[170:173], v[122:125]
	v_mfma_f32_16x16x32_bf16 v[118:121], v[230:233], v[170:173], v[118:121]
	v_mfma_f32_16x16x32_bf16 v[114:117], v[234:237], v[170:173], v[114:117]
	ds_read_b128 v[170:173], v178 offset:9216
	s_waitcnt lgkmcnt(3)
	v_mfma_f32_16x16x32_bf16 v[110:113], v[222:225], v[174:177], v[110:113]
	v_mfma_f32_16x16x32_bf16 v[106:109], v[226:229], v[174:177], v[106:109]
	v_mfma_f32_16x16x32_bf16 v[102:105], v[230:233], v[174:177], v[102:105]
	v_mfma_f32_16x16x32_bf16 v[98:101], v[234:237], v[174:177], v[98:101]
	ds_read_b128 v[174:177], v178 offset:11264
	s_waitcnt lgkmcnt(3)
	v_mfma_f32_16x16x32_bf16 v[94:97], v[222:225], v[192:195], v[94:97]
	v_mfma_f32_16x16x32_bf16 v[90:93], v[226:229], v[192:195], v[90:93]
	v_mfma_f32_16x16x32_bf16 v[86:89], v[230:233], v[192:195], v[86:89]
	v_mfma_f32_16x16x32_bf16 v[82:85], v[234:237], v[192:195], v[82:85]
	ds_read_b128 v[192:195], v178 offset:13312
	s_waitcnt lgkmcnt(3)
	v_mfma_f32_16x16x32_bf16 v[78:81], v[222:225], v[198:201], v[78:81]
	v_mfma_f32_16x16x32_bf16 v[74:77], v[226:229], v[198:201], v[74:77]
	v_mfma_f32_16x16x32_bf16 v[70:73], v[230:233], v[198:201], v[70:73]
	v_mfma_f32_16x16x32_bf16 v[66:69], v[234:237], v[198:201], v[66:69]
	ds_read_b128 v[198:201], v178 offset:15360
	s_waitcnt lgkmcnt(3)
	v_mfma_f32_16x16x32_bf16 v[62:65], v[222:225], v[170:173], v[62:65]
	v_mfma_f32_16x16x32_bf16 v[58:61], v[226:229], v[170:173], v[58:61]
	v_mfma_f32_16x16x32_bf16 v[54:57], v[230:233], v[170:173], v[54:57]
	v_mfma_f32_16x16x32_bf16 v[50:53], v[234:237], v[170:173], v[50:53]
	s_waitcnt lgkmcnt(2)
	v_mfma_f32_16x16x32_bf16 v[46:49], v[222:225], v[174:177], v[46:49]
	v_mfma_f32_16x16x32_bf16 v[42:45], v[226:229], v[174:177], v[42:45]
	v_mfma_f32_16x16x32_bf16 v[38:41], v[230:233], v[174:177], v[38:41]
	v_mfma_f32_16x16x32_bf16 v[34:37], v[234:237], v[174:177], v[34:37]
	s_waitcnt lgkmcnt(0)
	s_waitcnt vmcnt(0)
	s_add_u32 s18, s18, 0x80
	s_addc_u32 s19, s19, 0
	s_add_i32 s3, s3, 0x10000
	s_cmpk_eq_i32 s18, 0x1580
	s_waitcnt vmcnt(0)
	s_barrier
	s_cselect_b32 s100, 1, 0
	s_and_b32 s26, s3, 0x10000
	v_or_b32_e32 v150, s26, v149
	v_add_u32_e32 v169, v150, v148
	v_or_b32_e32 v150, s26, v146
	v_add_u32_e32 v178, v150, v147
	ds_read_b128 v[150:153], v169 offset:32768
	ds_read_b128 v[154:157], v169 offset:34816
	ds_read_b128 v[158:161], v169 offset:36864
	ds_read_b128 v[162:165], v169 offset:38912
	ds_read_b128 v[170:173], v178
	ds_read_b128 v[174:177], v178 offset:2048
	s_add_u32 s4, s4, 0x80
	s_addc_u32 s5, s5, 0
	s_add_u32 s6, s6, 0x80
	s_addc_u32 s7, s7, 0
	s_cmp_eq_u32 s100, 1
	s_cbranch_scc1 .Lkl_1404_s9
	v_readfirstlane_b32 s10, v143
	s_nop 3
	s_mul_i32 s8, s10, 8
	s_mul_i32 s9, s10, 0
	s_add_i32 s9, s9, 0x8000
	s_cmp_ge_u32 s10, 0x1000
	s_cselect_b32 s10, s9, s8
	s_xor_b32 s8, s26, 0x10000
	s_add_i32 s10, s10, s8
	s_add_i32 m0, s10, 0x1000
	s_add_u32 s8, s4, 0x1000
	s_addc_u32 s9, s5, 0x0
	global_load_lds_dwordx4 v238, s[8:9] offset:-4096
	s_add_u32 s8, s4, 0xc40
	s_addc_u32 s9, s5, 0x0
	global_load_lds_dwordx4 v238, s[8:9] offset:-3072
.Lkl_1404_s9:
	v_mfma_f32_16x16x32_bf16 v[30:33], v[222:225], v[192:195], v[30:33]
	v_mfma_f32_16x16x32_bf16 v[26:29], v[226:229], v[192:195], v[26:29]
	v_mfma_f32_16x16x32_bf16 v[22:25], v[230:233], v[192:195], v[22:25]
	v_mfma_f32_16x16x32_bf16 v[18:21], v[234:237], v[192:195], v[18:21]
	ds_read_b128 v[192:195], v178 offset:4096
	s_cmp_eq_u32 s100, 1
	s_cbranch_scc1 .Lkl_1404_s10
	s_add_u32 s8, s4, 0x16800
	s_addc_u32 s9, s5, 0x0
	global_load_lds_dwordx4 v238, s[8:9] offset:-2048
	s_add_u32 s8, s4, 0x16440
	s_addc_u32 s9, s5, 0x0
	global_load_lds_dwordx4 v238, s[8:9] offset:-1024
.Lkl_1404_s10:
	v_mfma_f32_16x16x32_bf16 v[14:17], v[222:225], v[198:201], v[14:17]
	v_mfma_f32_16x16x32_bf16 v[10:13], v[226:229], v[198:201], v[10:13]
	v_mfma_f32_16x16x32_bf16 v[6:9], v[230:233], v[198:201], v[6:9]
	v_mfma_f32_16x16x32_bf16 v[2:5], v[234:237], v[198:201], v[2:5]
	ds_read_b128 v[198:201], v178 offset:6144
	s_cmp_eq_u32 s100, 1
	s_cbranch_scc1 .Lkl_1404_s11
	s_add_u32 s8, s4, 0x2c000
	s_addc_u32 s9, s5, 0x0
	global_load_lds_dwordx4 v238, s[8:9] offset:0
	s_add_u32 s8, s4, 0x2bc40
	s_addc_u32 s9, s5, 0x0
	global_load_lds_dwordx4 v238, s[8:9] offset:1024

; #define WAIT_V0() asm volatile("s_waitcnt vmcnt(0)" ::: "memory")
; #define SBAR() __builtin_amdgcn_sched_barrier(0)
; template <int EPI>
; DEVI void gemm_tile(const u16* __restrict__ Ab, long lda, const u16* __restrict__ Bb, long ldb, int K, const EpiArgs& e,
;                     bool have0 = false, const u16* __restrict__ nA = nullptr, const u16* __restrict__ nB = nullptr) {
;     ...
;   for (int t = 0; t < nt; ++t) {
;     const int cur = t & 1;
;     if (t + 1 < nt) GLDS_STAGE(cur ^ 1, t + 1);
;     else if (nA) {
; #pragma unroll
;       for (int i = 0; i < GL; ++i) {
;         __builtin_amdgcn_global_load_lds((const unsigned*)(nA + (long)i * 64 * lda + toffA), (unsigned*)(g_shm + wid * 1024 + i * 8192), 16, 0, 0);
;         __builtin_amdgcn_global_load_lds((const unsigned*)(nB + (long)i * 64 * ldb + toffB), (unsigned*)(g_shm + TILE_B + wid * 1024 + i * 8192), 16, 0, 0);
;       }
;     }
;     const char* sb = g_shm + cur * STAGE_B;
; #pragma unroll
;     for (int ks = 0; ks < 2; ++ks) {
;       bf16x8 Bf[4];
; #pragma unroll
;       for (int n = 0; n < 4; ++n) Bf[n] = *(const bf16x8*)(sb + b_base + n * 2048 + ks * 1024);
; #pragma unroll
;       for (int mh = 0; mh < 2; ++mh) {
;         bf16x8 At[4];
; #pragma unroll
;         for (int m = 0; m < 4; ++m) At[m] = *(const bf16x8*)(sb + a_base + (mh * 4 + m) * 2048 + ks * 1024);
;         __builtin_amdgcn_s_setprio(1);
; #pragma unroll
;         for (int m = 0; m < 4; ++m)
; #pragma unroll
;           for (int n = 0; n < 4; ++n) acc[mh * 4 + m][n] = __builtin_amdgcn_mfma_f32_16x16x32_bf16(Bf[n], At[m], acc[mh * 4 + m][n], 0, 0, 0);
;         __builtin_amdgcn_s_setprio(0);
;       }
;       SBAR();
;     }
;     if (t + 1 < nt) { WAIT_V0(); __syncthreads(); }
;   }
.Lkl_1404_y:
	s_waitcnt lgkmcnt(3)
	v_mfma_f32_16x16x32_bf16 v[126:129], v[150:153], v[170:173], v[126:129]
	v_mfma_f32_16x16x32_bf16 v[122:125], v[154:157], v[170:173], v[122:125]
	v_mfma_f32_16x16x32_bf16 v[118:121], v[158:161], v[170:173], v[118:121]
	v_mfma_f32_16x16x32_bf16 v[114:117], v[162:165], v[170:173], v[114:117]
	ds_read_b128 v[170:173], v178 offset:8192
	ds_read_b128 v[222:225], v169 offset:33792
	s_waitcnt lgkmcnt(4)
	v_mfma_f32_16x16x32_bf16 v[110:113], v[150:153], v[174:177], v[110:113]
	v_mfma_f32_16x16x32_bf16 v[106:109], v[154:157], v[174:177], v[106:109]
	v_mfma_f32_16x16x32_bf16 v[102:105], v[158:161], v[174:177], v[102:105]
	v_mfma_f32_16x16x32_bf16 v[98:101], v[162:165], v[174:177], v[98:101]
	ds_read_b128 v[174:177], v178 offset:10240
	ds_read_b128 v[226:229], v169 offset:35840
	s_waitcnt lgkmcnt(5)
	v_mfma_f32_16x16x32_bf16 v[94:97], v[150:153], v[192:195], v[94:97]
	v_mfma_f32_16x16x32_bf16 v[90:93], v[154:157], v[192:195], v[90:93]
	v_mfma_f32_16x16x32_bf16 v[86:89], v[158:161], v[192:195], v[86:89]
	v_mfma_f32_16x16x32_bf16 v[82:85], v[162:165], v[192:195], v[82:85]
	ds_read_b128 v[192:195], v178 offset:12288
	ds_read_b128 v[230:233], v169 offset:37888
	s_waitcnt lgkmcnt(6)
	v_mfma_f32_16x16x32_bf16 v[78:81], v[150:153], v[198:201], v[78:81]
	v_mfma_f32_16x16x32_bf16 v[74:77], v[154:157], v[198:201], v[74:77]
	v_mfma_f32_16x16x32_bf16 v[70:73], v[158:161], v[198:201], v[70:73]
	v_mfma_f32_16x16x32_bf16 v[66:69], v[162:165], v[198:201], v[66:69]
	ds_read_b128 v[198:201], v178 offset:14336
	ds_read_b128 v[234:237], v169 offset:39936
	s_waitcnt lgkmcnt(7)
	v_mfma_f32_16x16x32_bf16 v[62:65], v[150:153], v[170:173], v[62:65]
	v_mfma_f32_16x16x32_bf16 v[58:61], v[154:157], v[170:173], v[58:61]
	v_mfma_f32_16x16x32_bf16 v[54:57], v[158:161], v[170:173], v[54:57]
	v_mfma_f32_16x16x32_bf16 v[50:53], v[162:165], v[170:173], v[50:53]
	ds_read_b128 v[170:173], v178 offset:1024
	s_waitcnt lgkmcnt(6)
	v_mfma_f32_16x16x32_bf16 v[46:49], v[150:153], v[174:177], v[46:49]
	v_mfma_f32_16x16x32_bf16 v[42:45], v[154:157], v[174:177], v[42:45]
	v_mfma_f32_16x16x32_bf16 v[38:41], v[158:161], v[174:177], v[38:41]
	v_mfma_f32_16x16x32_bf16 v[34:37], v[162:165], v[174:177], v[34:37]
	ds_read_b128 v[174:177], v178 offset:3072
	s_waitcnt lgkmcnt(5)
	v_mfma_f32_16x16x32_bf16 v[30:33], v[150:153], v[192:195], v[30:33]
	v_mfma_f32_16x16x32_bf16 v[26:29], v[154:157], v[192:195], v[26:29]
	v_mfma_f32_16x16x32_bf16 v[22:25], v[158:161], v[192:195], v[22:25]
	v_mfma_f32_16x16x32_bf16 v[18:21], v[162:165], v[192:195], v[18:21]
	ds_read_b128 v[192:195], v178 offset:5120
	s_waitcnt lgkmcnt(4)
	v_mfma_f32_16x16x32_bf16 v[14:17], v[150:153], v[198:201], v[14:17]
	v_mfma_f32_16x16x32_bf16 v[10:13], v[154:157], v[198:201], v[10:13]
	v_mfma_f32_16x16x32_bf16 v[6:9], v[158:161], v[198:201], v[6:9]
	v_mfma_f32_16x16x32_bf16 v[2:5], v[162:165], v[198:201], v[2:5]
	ds_read_b128 v[198:201], v178 offset:7168
	s_waitcnt lgkmcnt(3)
	v_mfma_f32_16x16x32_bf16 v[126:129], v[222:225], v[170:173], v[126:129]
	v_mfma_f32_16x16x32_bf16 v[122:125], v[226:229], v[170:173], v[122:125]
	v_mfma_f32_16x16x32_bf16 v[118:121], v[230:233], v[170:173], v[118:121]
	v_mfma_f32_16x16x32_bf16 v[114:117], v[234:237], v[170:173], v[114:117]
	ds_read_b128 v[170:173], v178 offset:9216
	s_waitcnt lgkmcnt(3)
	v_mfma_f32_16x16x32_bf16 v[110:113], v[222:225], v[174:177], v[110:113]
	v_mfma_f32_16x16x32_bf16 v[106:109], v[226:229], v[174:177], v[106:109]
	v_mfma_f32_16x16x32_bf16 v[102:105], v[230:233], v[174:177], v[102:105]
	v_mfma_f32_16x16x32_bf16 v[98:101], v[234:237], v[174:177], v[98:101]
	ds_read_b128 v[174:177], v178 offset:11264
	s_waitcnt lgkmcnt(3)
	v_mfma_f32_16x16x32_bf16 v[94:97], v[222:225], v[192:195], v[94:97]
	v_mfma_f32_16x16x32_bf16 v[90:93], v[226:229], v[192:195], v[90:93]
	v_mfma_f32_16x16x32_bf16 v[86:89], v[230:233], v[192:195], v[86:89]
	v_mfma_f32_16x16x32_bf16 v[82:85], v[234:237], v[192:195], v[82:85]
	ds_read_b128 v[192:195], v178 offset:13312
	s_waitcnt lgkmcnt(3)
	v_mfma_f32_16x16x32_bf16 v[78:81], v[222:225], v[198:201], v[78:81]
	v_mfma_f32_16x16x32_bf16 v[74:77], v[226:229], v[198:201], v[74:77]
	v_mfma_f32_16x16x32_bf16 v[70:73], v[230:233], v[198:201], v[70:73]
	v_mfma_f32_16x16x32_bf16 v[66:69], v[234:237], v[198:201], v[66:69]
	ds_read_b128 v[198:201], v178 offset:15360
	s_waitcnt lgkmcnt(3)
	v_mfma_f32_16x16x32_bf16 v[62:65], v[222:225], v[170:173], v[62:65]
	v_mfma_f32_16x16x32_bf16 v[58:61], v[226:229], v[170:173], v[58:61]
	v_mfma_f32_16x16x32_bf16 v[54:57], v[230:233], v[170:173], v[54:57]
	v_mfma_f32_16x16x32_bf16 v[50:53], v[234:237], v[170:173], v[50:53]
	s_waitcnt lgkmcnt(2)
	v_mfma_f32_16x16x32_bf16 v[46:49], v[222:225], v[174:177], v[46:49]
	v_mfma_f32_16x16x32_bf16 v[42:45], v[226:229], v[174:177], v[42:45]
	v_mfma_f32_16x16x32_bf16 v[38:41], v[230:233], v[174:177], v[38:41]
	v_mfma_f32_16x16x32_bf16 v[34:37], v[234:237], v[174:177], v[34:37]
	s_waitcnt lgkmcnt(0)
	s_waitcnt vmcnt(0)
	s_add_u32 s18, s18, 0x80
	s_addc_u32 s19, s19, 0
	s_add_i32 s3, s3, 0x10000
	s_cmpk_eq_i32 s18, 0x1580
	s_waitcnt vmcnt(0)
	s_barrier
	s_cselect_b32 s100, 1, 0
	s_and_b32 s26, s3, 0x10000
	v_or_b32_e32 v150, s26, v149
	v_add_u32_e32 v169, v150, v148
	v_or_b32_e32 v150, s26, v146
	v_add_u32_e32 v178, v150, v147
	ds_read_b128 v[150:153], v169 offset:32768
	ds_read_b128 v[154:157], v169 offset:34816
	ds_read_b128 v[158:161], v169 offset:36864
	ds_read_b128 v[162:165], v169 offset:38912
	ds_read_b128 v[170:173], v178
	ds_read_b128 v[174:177], v178 offset:2048
	s_add_u32 s4, s4, 0x80
	s_addc_u32 s5, s5, 0
	s_add_u32 s6, s6, 0x80
	s_addc_u32 s7, s7, 0
	v_mfma_f32_16x16x32_bf16 v[30:33], v[222:225], v[192:195], v[30:33]
	v_mfma_f32_16x16x32_bf16 v[26:29], v[226:229], v[192:195], v[26:29]
	v_mfma_f32_16x16x32_bf16 v[22:25], v[230:233], v[192:195], v[22:25]
	v_mfma_f32_16x16x32_bf16 v[18:21], v[234:237], v[192:195], v[18:21]
	ds_read_b128 v[192:195], v178 offset:4096
	v_mfma_f32_16x16x32_bf16 v[14:17], v[222:225], v[198:201], v[14:17]
	v_mfma_f32_16x16x32_bf16 v[10:13], v[226:229], v[198:201], v[10:13]
	v_mfma_f32_16x16x32_bf16 v[6:9], v[230:233], v[198:201], v[6:9]
	v_mfma_f32_16x16x32_bf16 v[2:5], v[234:237], v[198:201], v[2:5]
	ds_read_b128 v[198:201], v178 offset:6144
	s_cmp_eq_u32 s100, 1
	s_cbranch_scc0 .Lkl_1404_y
; template <int EPI>
; DEVI void gemm_tile(const u16* __restrict__ Ab, long lda, const u16* __restrict__ Bb, long ldb, int K, const EpiArgs& e,
;                     bool have0 = false, const u16* __restrict__ nA = nullptr, const u16* __restrict__ nB = nullptr) {
;     ...
;     if (t + 1 < nt) GLDS_STAGE(cur ^ 1, t + 1);
;     else if (nA) {
; #pragma unroll
;       for (int i = 0; i < GL; ++i) {
;         __builtin_amdgcn_global_load_lds((const unsigned*)(nA + (long)i * 64 * lda + toffA), (unsigned*)(g_shm + wid * 1024 + i * 8192), 16, 0, 0);
;         __builtin_amdgcn_global_load_lds((const unsigned*)(nB + (long)i * 64 * ldb + toffB), (unsigned*)(g_shm + TILE_B + wid * 1024 + i * 8192), 16, 0, 0);
;       }
;     }
.Lkl_1404_x:
	s_setprio 0
	s_nop 3
	v_readlane_b32 s4, v240, 0
	v_readlane_b32 s5, v240, 1
	v_readlane_b32 s6, v240, 2
	v_readlane_b32 s7, v240, 3
	v_readlane_b32 s8, v240, 4
	v_readlane_b32 s9, v240, 5
	v_readlane_b32 s10, v240, 6
	s_waitcnt lgkmcnt(0)
	s_xor_b32 s26, s26, 0x10000
	v_or_b32_e32 v150, s26, v149
	v_add_u32_e32 v169, v150, v148
	v_or_b32_e32 v150, s26, v146
	v_add_u32_e32 v178, v150, v147
	s_cmp_eq_u32 s100, 1
	s_cmp_eq_u64 s[10:11], 0
	s_cbranch_scc1 .LBB0_1392
	v_readfirstlane_b32 s3, v143
	v_lshl_add_u64 v[134:135], s[10:11], 0, v[132:133]
	s_mov_b32 m0, s3
	v_readfirstlane_b32 s3, v145
	v_lshl_add_u64 v[132:133], s[16:17], 0, v[132:133]
	global_load_lds_dwordx4 v[134:135], off
	s_mov_b32 m0, s3
	s_mov_b64 s[16:17], 0x58000
	v_readfirstlane_b32 s3, v144
	global_load_lds_dwordx4 v[132:133], off
	v_lshl_add_u64 v[136:137], v[134:135], 0, s[16:17]
	s_mov_b32 m0, s3
	v_readfirstlane_b32 s3, v142
	global_load_lds_dwordx4 v[136:137], off
	v_lshl_add_u64 v[136:137], v[132:133], 0, s[16:17]
	s_mov_b32 m0, s3
	s_mov_b64 s[16:17], 0xb0000
	v_readfirstlane_b32 s3, v141
	global_load_lds_dwordx4 v[136:137], off
	v_lshl_add_u64 v[136:137], v[134:135], 0, s[16:17]
	s_mov_b32 m0, s3
	v_readfirstlane_b32 s3, v140
	global_load_lds_dwordx4 v[136:137], off
	v_lshl_add_u64 v[136:137], v[132:133], 0, s[16:17]
	s_mov_b32 m0, s3
	s_mov_b64 s[16:17], 0x108000
	v_readfirstlane_b32 s3, v139
	global_load_lds_dwordx4 v[136:137], off
	v_lshl_add_u64 v[134:135], v[134:135], 0, s[16:17]
	s_mov_b32 m0, s3
	v_readfirstlane_b32 s3, v138
	global_load_lds_dwordx4 v[134:135], off
	v_lshl_add_u64 v[132:133], v[132:133], 0, s[16:17]
	s_mov_b32 m0, s3
	s_nop 0
	global_load_lds_dwordx4 v[132:133], off
	s_branch .LBB0_1392
